# ssd3 intra-chunk decay/mask passes rewritten branch-free with wide LDS reads (16 divergent blocks per pass removed); GEMM DMA split 4+4 over two segments
# speedup vs baseline: 1.1286x; 1.0333x over previous
.LBB0_22:
	s_add_i32 s2, s7, s8
	s_cmpk_gt_i32 s2, 0x1ff
	s_mov_b64 s[0:1], -1
	s_cbranch_scc1 .LBB0_21
	s_ashr_i32 s0, s2, 31
	s_lshr_b32 s0, s0, 27
	s_add_i32 s0, s2, s0
	s_and_b32 s1, s0, 0xffffffe0
	s_sub_i32 s1, s2, s1
	s_ashr_i32 s2, s1, 31
	s_lshr_b32 s2, s2, 29
	s_add_i32 s2, s1, s2
	s_and_b32 s3, s2, 0xfffff8
	s_sub_i32 s1, s1, s3
	s_lshl_b32 s0, s0, 6
	s_and_b32 s0, s0, 0xfffff800
	s_lshl_b32 s1, s1, 8
	s_add_i32 s0, s1, s0
	s_ashr_i32 s1, s0, 31
	s_lshl_b64 s[4:5], s[0:1], 12
	s_lshl_b32 s1, s2, 5
	s_and_b32 s2, s1, 0xffffff00
	s_ashr_i32 s3, s2, 31
	s_lshl_b64 s[10:11], s[2:3], 12
	s_add_u32 s12, s64, s4
	v_mov_b32_e32 v0, v138
	s_addc_u32 s13, s65, s5
	s_barrier
	v_readlane_b32 s14, v251, 22
	v_lshl_add_u64 v[2:3], v[0:1], 1, s[12:13]
	v_add_u32_e32 v0, 32, v139
	v_readlane_b32 s15, v251, 23
	v_readfirstlane_b32 s1, v0
	s_mov_b32 m0, s1
	v_mov_b32_e32 v0, v140
	global_load_lds_dwordx4 v[2:3], off
	s_add_u32 s14, s14, s10
	v_lshl_add_u64 v[2:3], v[0:1], 1, s[12:13]
	v_add_u32_e32 v0, 32, v141
	s_addc_u32 s15, s15, s11
	v_readfirstlane_b32 s1, v0
	s_mov_b32 m0, s1
	v_mov_b32_e32 v0, v142
	global_load_lds_dwordx4 v[2:3], off
	v_readlane_b32 s3, v254, 3
	v_lshl_add_u64 v[2:3], v[0:1], 1, s[12:13]
	v_add_u32_e32 v0, 32, v143
	s_mov_b32 s27, s51
	v_readfirstlane_b32 s1, v0
	s_mov_b32 m0, s1
	v_mov_b32_e32 v0, v144
	global_load_lds_dwordx4 v[2:3], off
	s_nop 0
	v_lshl_add_u64 v[2:3], v[0:1], 1, s[12:13]
	v_add_u32_e32 v0, 32, v145
	s_nop 0
	v_readfirstlane_b32 s1, v0
	s_mov_b32 m0, s1
	v_mov_b32_e32 v0, v138
	global_load_lds_dwordx4 v[2:3], off
	s_nop 0
	v_lshl_add_u64 v[2:3], v[0:1], 1, s[14:15]
	v_add_u32_e32 v0, s3, v139
	s_nop 0
	v_readfirstlane_b32 s1, v0
	s_mov_b32 m0, s1
	v_mov_b32_e32 v0, v140
	global_load_lds_dwordx4 v[2:3], off
	s_nop 0
	v_lshl_add_u64 v[2:3], v[0:1], 1, s[14:15]
	v_add_u32_e32 v0, s3, v141
	s_nop 0
	v_readfirstlane_b32 s1, v0
	s_mov_b32 m0, s1
	v_mov_b32_e32 v0, v142
	global_load_lds_dwordx4 v[2:3], off
	s_nop 0
	v_lshl_add_u64 v[2:3], v[0:1], 1, s[14:15]
	v_add_u32_e32 v0, s3, v143
	s_nop 0
	v_readfirstlane_b32 s1, v0
	s_mov_b32 m0, s1
	v_mov_b32_e32 v0, v144
	global_load_lds_dwordx4 v[2:3], off
	s_nop 0
	v_lshl_add_u64 v[2:3], v[0:1], 1, s[14:15]
	v_add_u32_e32 v0, s3, v145
	v_readlane_b32 s3, v253, 26
	v_readfirstlane_b32 s1, v0
	s_mov_b32 m0, s1
	v_readlane_b32 s1, v253, 25
	global_load_lds_dwordx4 v[2:3], off
	s_add_u32 s1, s1, s4
	s_waitcnt vmcnt(0)
	s_addc_u32 s3, s3, s5
	v_readlane_b32 s4, v253, 27
	s_add_u32 s9, s4, s10
	v_readlane_b32 s4, v253, 28
	v_mov_b32_e32 v2, 0
	s_addc_u32 s10, s4, s11
	s_mov_b64 s[4:5], 0
	s_mov_b32 s11, 0
	v_mov_b32_e32 v3, v2
	v_mov_b32_e32 v4, v2
	v_mov_b32_e32 v5, v2
	v_mov_b32_e32 v6, v2
	v_mov_b32_e32 v7, v2
	v_mov_b32_e32 v8, v2
	v_mov_b32_e32 v9, v2
	v_mov_b32_e32 v10, v2
	v_mov_b32_e32 v11, v2
	v_mov_b32_e32 v12, v2
	v_mov_b32_e32 v13, v2
	s_waitcnt vmcnt(0)
	v_mov_b32_e32 v14, v2
	v_mov_b32_e32 v15, v2
	v_mov_b32_e32 v16, v2
	v_mov_b32_e32 v17, v2
	v_mov_b32_e32 v18, v2
	v_mov_b32_e32 v19, v2
	v_mov_b32_e32 v20, v2
	v_mov_b32_e32 v21, v2
	v_mov_b32_e32 v22, v2
	v_mov_b32_e32 v23, v2
	v_mov_b32_e32 v24, v2
	v_mov_b32_e32 v25, v2
	v_mov_b32_e32 v26, v2
	v_mov_b32_e32 v27, v2
	v_mov_b32_e32 v28, v2
	v_mov_b32_e32 v29, v2
	v_mov_b32_e32 v30, v2
	v_mov_b32_e32 v31, v2
	v_mov_b32_e32 v32, v2
	v_mov_b32_e32 v33, v2
	v_mov_b32_e32 v34, v2
	v_mov_b32_e32 v35, v2
	v_mov_b32_e32 v36, v2
	v_mov_b32_e32 v37, v2
	v_mov_b32_e32 v38, v2
	v_mov_b32_e32 v39, v2
	v_mov_b32_e32 v40, v2
	v_mov_b32_e32 v41, v2
	v_mov_b32_e32 v42, v2
	v_mov_b32_e32 v43, v2
	v_mov_b32_e32 v44, v2
	v_mov_b32_e32 v45, v2
	v_mov_b32_e32 v46, v2
	v_mov_b32_e32 v47, v2
	v_mov_b32_e32 v48, v2
	v_mov_b32_e32 v49, v2
	v_mov_b32_e32 v50, v2
	v_mov_b32_e32 v51, v2
	v_mov_b32_e32 v52, v2
	v_mov_b32_e32 v53, v2
	v_mov_b32_e32 v54, v2
	v_mov_b32_e32 v55, v2
	v_mov_b32_e32 v56, v2
	v_mov_b32_e32 v57, v2
	v_mov_b32_e32 v58, v2
	v_mov_b32_e32 v59, v2
	v_mov_b32_e32 v60, v2
	v_mov_b32_e32 v61, v2
	v_mov_b32_e32 v62, v2
	v_mov_b32_e32 v63, v2
	v_mov_b32_e32 v64, v2
	v_mov_b32_e32 v65, v2
	v_mov_b32_e32 v66, v2
	v_mov_b32_e32 v67, v2
	v_mov_b32_e32 v68, v2
	v_mov_b32_e32 v69, v2
	v_mov_b32_e32 v70, v2
	v_mov_b32_e32 v71, v2
	v_mov_b32_e32 v72, v2
	v_mov_b32_e32 v73, v2
	v_mov_b32_e32 v74, v2
	v_mov_b32_e32 v75, v2
	v_mov_b32_e32 v76, v2
	v_mov_b32_e32 v77, v2
	v_mov_b32_e32 v78, v2
	v_mov_b32_e32 v79, v2
	v_mov_b32_e32 v80, v2
	v_mov_b32_e32 v81, v2
	v_mov_b32_e32 v82, v2
	v_mov_b32_e32 v83, v2
	v_mov_b32_e32 v84, v2
	v_mov_b32_e32 v85, v2
	v_mov_b32_e32 v86, v2
	v_mov_b32_e32 v87, v2
	v_mov_b32_e32 v88, v2
	v_mov_b32_e32 v89, v2
	v_mov_b32_e32 v90, v2
	v_mov_b32_e32 v91, v2
	v_mov_b32_e32 v92, v2
	v_mov_b32_e32 v93, v2
	v_mov_b32_e32 v94, v2
	v_mov_b32_e32 v95, v2
	v_mov_b32_e32 v96, v2
	v_mov_b32_e32 v97, v2
	v_mov_b32_e32 v98, v2
	v_mov_b32_e32 v99, v2
	v_mov_b32_e32 v100, v2
	v_mov_b32_e32 v101, v2
	v_mov_b32_e32 v102, v2
	v_mov_b32_e32 v103, v2
	v_mov_b32_e32 v104, v2
	v_mov_b32_e32 v105, v2
	v_mov_b32_e32 v106, v2
	v_mov_b32_e32 v107, v2
	v_mov_b32_e32 v108, v2
	v_mov_b32_e32 v109, v2
	v_mov_b32_e32 v110, v2
	v_mov_b32_e32 v111, v2
	v_mov_b32_e32 v112, v2
	v_mov_b32_e32 v113, v2
	v_mov_b32_e32 v114, v2
	v_mov_b32_e32 v115, v2
	v_mov_b32_e32 v116, v2
	v_mov_b32_e32 v117, v2
	v_mov_b32_e32 v118, v2
	v_mov_b32_e32 v119, v2
	v_mov_b32_e32 v120, v2
	v_mov_b32_e32 v121, v2
	v_mov_b32_e32 v122, v2
	v_mov_b32_e32 v123, v2
	v_mov_b32_e32 v124, v2
	v_mov_b32_e32 v125, v2
	v_mov_b32_e32 v126, v2
	v_mov_b32_e32 v127, v2
	v_mov_b32_e32 v128, v2
	v_mov_b32_e32 v129, v2
	s_waitcnt vmcnt(0) lgkmcnt(0)
	s_barrier
	v_lshlrev_b32_e32 v155, 1, v138
	v_readfirstlane_b32 s14, v139
	v_add_u32_e32 v177, v146, v148
	v_add_u32_e32 v207, v147, v148
	v_add_u32_e32 v204, v146, v152
	v_add_u32_e32 v208, v147, v152
	v_add_u32_e32 v205, v146, v153
	v_add_u32_e32 v209, v147, v153
	v_add_u32_e32 v206, v146, v154
	v_add_u32_e32 v210, v147, v154
	s_mov_b32 s11, 15
	s_add_u32 m0, s14, 0x8020
	s_add_u32 s12, s1, s4
	s_addc_u32 s13, s3, s5
	global_load_lds_dwordx4 v155, s[12:13]
	s_add_u32 m0, s14, 0xa020
	s_add_u32 s12, s12, 0x40000
	s_addc_u32 s13, s13, 0
	global_load_lds_dwordx4 v155, s[12:13]
	s_add_u32 m0, s14, 0xc020
	s_add_u32 s12, s12, 0x40000
	s_addc_u32 s13, s13, 0
	global_load_lds_dwordx4 v155, s[12:13]
	s_add_u32 m0, s14, 0xe020
	s_add_u32 s12, s12, 0x40000
	s_addc_u32 s13, s13, 0
	global_load_lds_dwordx4 v155, s[12:13]
	ds_read_b128 v[130:133], v177 offset:0
	ds_read_b128 v[164:167], v207 offset:0
	ds_read_b128 v[168:171], v207 offset:4096
	ds_read_b128 v[134:137], v177 offset:4096
	ds_read_b128 v[156:159], v177 offset:8192
	ds_read_b128 v[160:163], v177 offset:12288
.Lg24_loop:
	s_waitcnt lgkmcnt(4)
	v_mfma_f32_32x32x16_bf16 v[114:129], v[130:133], v[164:167], v[114:129]
	ds_read_b128 v[172:175], v204 offset:0
	s_waitcnt lgkmcnt(4)
	v_mfma_f32_32x32x16_bf16 v[98:113], v[130:133], v[168:171], v[98:113]
	ds_read_b128 v[192:195], v208 offset:0
	s_add_u32 m0, s14, 0x18020
	s_add_u32 s12, s9, s4
	s_addc_u32 s13, s10, s5
	global_load_lds_dwordx4 v155, s[12:13]
	s_waitcnt lgkmcnt(4)
	v_mfma_f32_32x32x16_bf16 v[82:97], v[134:137], v[164:167], v[82:97]
	ds_read_b128 v[200:203], v208 offset:4096
	v_mfma_f32_32x32x16_bf16 v[66:81], v[134:137], v[168:171], v[66:81]
	ds_read_b128 v[180:183], v204 offset:4096
	s_add_u32 m0, s14, 0x1a020
	s_add_u32 s12, s12, 0x40000
	s_addc_u32 s13, s13, 0
	global_load_lds_dwordx4 v155, s[12:13]
	s_waitcnt lgkmcnt(5)
	v_mfma_f32_32x32x16_bf16 v[50:65], v[156:159], v[164:167], v[50:65]
	ds_read_b128 v[184:187], v204 offset:8192
	v_mfma_f32_32x32x16_bf16 v[34:49], v[156:159], v[168:171], v[34:49]
	ds_read_b128 v[188:191], v204 offset:12288
	s_add_u32 m0, s14, 0x1c020
	s_add_u32 s12, s12, 0x40000
	s_addc_u32 s13, s13, 0
	global_load_lds_dwordx4 v155, s[12:13]
	s_waitcnt lgkmcnt(6)
	v_mfma_f32_32x32x16_bf16 v[18:33], v[160:163], v[164:167], v[18:33]
	v_mfma_f32_32x32x16_bf16 v[2:17], v[160:163], v[168:171], v[2:17]
	s_add_u32 m0, s14, 0x1e020
	s_add_u32 s12, s12, 0x40000
	s_addc_u32 s13, s13, 0
	global_load_lds_dwordx4 v155, s[12:13]
	s_add_u32 s4, s4, 0x80
	s_addc_u32 s5, s5, 0
	s_waitcnt lgkmcnt(4)
	v_mfma_f32_32x32x16_bf16 v[114:129], v[172:175], v[192:195], v[114:129]
	ds_read_b128 v[130:133], v205 offset:0
	s_waitcnt lgkmcnt(4)
	v_mfma_f32_32x32x16_bf16 v[98:113], v[172:175], v[200:203], v[98:113]
	ds_read_b128 v[164:167], v209 offset:0
	s_waitcnt lgkmcnt(4)
	v_mfma_f32_32x32x16_bf16 v[82:97], v[180:183], v[192:195], v[82:97]
	ds_read_b128 v[168:171], v209 offset:4096
	v_mfma_f32_32x32x16_bf16 v[66:81], v[180:183], v[200:203], v[66:81]
	ds_read_b128 v[134:137], v205 offset:4096
	s_waitcnt lgkmcnt(5)
	v_mfma_f32_32x32x16_bf16 v[50:65], v[184:187], v[192:195], v[50:65]
	ds_read_b128 v[156:159], v205 offset:8192
	v_mfma_f32_32x32x16_bf16 v[34:49], v[184:187], v[200:203], v[34:49]
	ds_read_b128 v[160:163], v205 offset:12288
	s_waitcnt lgkmcnt(6)
	v_mfma_f32_32x32x16_bf16 v[18:33], v[188:191], v[192:195], v[18:33]
	v_mfma_f32_32x32x16_bf16 v[2:17], v[188:191], v[200:203], v[2:17]
	s_waitcnt lgkmcnt(4)
	v_mfma_f32_32x32x16_bf16 v[114:129], v[130:133], v[164:167], v[114:129]
	ds_read_b128 v[172:175], v206 offset:0
	ds_read_b128 v[192:195], v210 offset:0
	s_waitcnt lgkmcnt(5)
	v_mfma_f32_32x32x16_bf16 v[98:113], v[130:133], v[168:171], v[98:113]
	ds_read_b128 v[200:203], v210 offset:4096
	ds_read_b128 v[180:183], v206 offset:4096
	s_waitcnt lgkmcnt(6)
	v_mfma_f32_32x32x16_bf16 v[82:97], v[134:137], v[164:167], v[82:97]
	ds_read_b128 v[184:187], v206 offset:8192
	ds_read_b128 v[188:191], v206 offset:12288
	v_mfma_f32_32x32x16_bf16 v[66:81], v[134:137], v[168:171], v[66:81]
	s_waitcnt lgkmcnt(7)
	v_mfma_f32_32x32x16_bf16 v[50:65], v[156:159], v[164:167], v[50:65]
	v_mfma_f32_32x32x16_bf16 v[34:49], v[156:159], v[168:171], v[34:49]
	s_waitcnt lgkmcnt(6)
	v_mfma_f32_32x32x16_bf16 v[18:33], v[160:163], v[164:167], v[18:33]
	v_mfma_f32_32x32x16_bf16 v[2:17], v[160:163], v[168:171], v[2:17]
	s_waitcnt vmcnt(0) lgkmcnt(0)
	s_barrier
	v_mfma_f32_32x32x16_bf16 v[114:129], v[172:175], v[192:195], v[114:129]
	ds_read_b128 v[130:133], v177 offset:32768
	v_mfma_f32_32x32x16_bf16 v[98:113], v[172:175], v[200:203], v[98:113]
	ds_read_b128 v[164:167], v207 offset:32768
	s_add_u32 m0, s14, 0x20
	s_add_u32 s12, s1, s4
	s_addc_u32 s13, s3, s5
	global_load_lds_dwordx4 v155, s[12:13]
	v_mfma_f32_32x32x16_bf16 v[82:97], v[180:183], v[192:195], v[82:97]
	ds_read_b128 v[168:171], v207 offset:36864
	v_mfma_f32_32x32x16_bf16 v[66:81], v[180:183], v[200:203], v[66:81]
	ds_read_b128 v[134:137], v177 offset:36864
	s_add_u32 m0, s14, 0x2020
	s_add_u32 s12, s12, 0x40000
	s_addc_u32 s13, s13, 0
	global_load_lds_dwordx4 v155, s[12:13]
	v_mfma_f32_32x32x16_bf16 v[50:65], v[184:187], v[192:195], v[50:65]
	ds_read_b128 v[156:159], v177 offset:40960
	v_mfma_f32_32x32x16_bf16 v[34:49], v[184:187], v[200:203], v[34:49]
	ds_read_b128 v[160:163], v177 offset:45056
	s_add_u32 m0, s14, 0x4020
	s_add_u32 s12, s12, 0x40000
	s_addc_u32 s13, s13, 0
	global_load_lds_dwordx4 v155, s[12:13]
	v_mfma_f32_32x32x16_bf16 v[18:33], v[188:191], v[192:195], v[18:33]
	v_mfma_f32_32x32x16_bf16 v[2:17], v[188:191], v[200:203], v[2:17]
	s_add_u32 m0, s14, 0x6020
	s_add_u32 s12, s12, 0x40000
	s_addc_u32 s13, s13, 0
	global_load_lds_dwordx4 v155, s[12:13]
	s_waitcnt lgkmcnt(4)
	v_mfma_f32_32x32x16_bf16 v[114:129], v[130:133], v[164:167], v[114:129]
	ds_read_b128 v[172:175], v204 offset:32768
	s_waitcnt lgkmcnt(4)
	v_mfma_f32_32x32x16_bf16 v[98:113], v[130:133], v[168:171], v[98:113]
	ds_read_b128 v[192:195], v208 offset:32768
	s_add_u32 m0, s14, 0x10020
	s_add_u32 s12, s9, s4
	s_addc_u32 s13, s10, s5
	global_load_lds_dwordx4 v155, s[12:13]
	s_waitcnt lgkmcnt(4)
	v_mfma_f32_32x32x16_bf16 v[82:97], v[134:137], v[164:167], v[82:97]
	ds_read_b128 v[200:203], v208 offset:36864
	v_mfma_f32_32x32x16_bf16 v[66:81], v[134:137], v[168:171], v[66:81]
	ds_read_b128 v[180:183], v204 offset:36864
	s_add_u32 m0, s14, 0x12020
	s_add_u32 s12, s12, 0x40000
	s_addc_u32 s13, s13, 0
	global_load_lds_dwordx4 v155, s[12:13]
	s_waitcnt lgkmcnt(5)
	v_mfma_f32_32x32x16_bf16 v[50:65], v[156:159], v[164:167], v[50:65]
	ds_read_b128 v[184:187], v204 offset:40960
	v_mfma_f32_32x32x16_bf16 v[34:49], v[156:159], v[168:171], v[34:49]
	ds_read_b128 v[188:191], v204 offset:45056
	s_add_u32 m0, s14, 0x14020
	s_add_u32 s12, s12, 0x40000
	s_addc_u32 s13, s13, 0
	global_load_lds_dwordx4 v155, s[12:13]
	s_waitcnt lgkmcnt(6)
	v_mfma_f32_32x32x16_bf16 v[18:33], v[160:163], v[164:167], v[18:33]
	v_mfma_f32_32x32x16_bf16 v[2:17], v[160:163], v[168:171], v[2:17]
	s_add_u32 m0, s14, 0x16020
	s_add_u32 s12, s12, 0x40000
	s_addc_u32 s13, s13, 0
	global_load_lds_dwordx4 v155, s[12:13]
	s_add_u32 s4, s4, 0x80
	s_addc_u32 s5, s5, 0
	s_waitcnt lgkmcnt(4)
	v_mfma_f32_32x32x16_bf16 v[114:129], v[172:175], v[192:195], v[114:129]
	ds_read_b128 v[130:133], v205 offset:32768
	s_waitcnt lgkmcnt(4)
	v_mfma_f32_32x32x16_bf16 v[98:113], v[172:175], v[200:203], v[98:113]
	ds_read_b128 v[164:167], v209 offset:32768
	s_waitcnt lgkmcnt(4)
	v_mfma_f32_32x32x16_bf16 v[82:97], v[180:183], v[192:195], v[82:97]
	ds_read_b128 v[168:171], v209 offset:36864
	v_mfma_f32_32x32x16_bf16 v[66:81], v[180:183], v[200:203], v[66:81]
	ds_read_b128 v[134:137], v205 offset:36864
	s_waitcnt lgkmcnt(5)
	v_mfma_f32_32x32x16_bf16 v[50:65], v[184:187], v[192:195], v[50:65]
	ds_read_b128 v[156:159], v205 offset:40960
	v_mfma_f32_32x32x16_bf16 v[34:49], v[184:187], v[200:203], v[34:49]
	ds_read_b128 v[160:163], v205 offset:45056
	s_waitcnt lgkmcnt(6)
	v_mfma_f32_32x32x16_bf16 v[18:33], v[188:191], v[192:195], v[18:33]
	v_mfma_f32_32x32x16_bf16 v[2:17], v[188:191], v[200:203], v[2:17]
	s_waitcnt lgkmcnt(4)
	v_mfma_f32_32x32x16_bf16 v[114:129], v[130:133], v[164:167], v[114:129]
	ds_read_b128 v[172:175], v206 offset:32768
	ds_read_b128 v[192:195], v210 offset:32768
	s_waitcnt lgkmcnt(5)
	v_mfma_f32_32x32x16_bf16 v[98:113], v[130:133], v[168:171], v[98:113]
	ds_read_b128 v[200:203], v210 offset:36864
	ds_read_b128 v[180:183], v206 offset:36864
	s_waitcnt lgkmcnt(6)
	v_mfma_f32_32x32x16_bf16 v[82:97], v[134:137], v[164:167], v[82:97]
	ds_read_b128 v[184:187], v206 offset:40960
	ds_read_b128 v[188:191], v206 offset:45056
	v_mfma_f32_32x32x16_bf16 v[66:81], v[134:137], v[168:171], v[66:81]
	s_waitcnt lgkmcnt(7)
	v_mfma_f32_32x32x16_bf16 v[50:65], v[156:159], v[164:167], v[50:65]
	v_mfma_f32_32x32x16_bf16 v[34:49], v[156:159], v[168:171], v[34:49]
	s_waitcnt lgkmcnt(6)
	v_mfma_f32_32x32x16_bf16 v[18:33], v[160:163], v[164:167], v[18:33]
	v_mfma_f32_32x32x16_bf16 v[2:17], v[160:163], v[168:171], v[2:17]
	s_waitcnt vmcnt(0) lgkmcnt(0)
	s_barrier
	v_mfma_f32_32x32x16_bf16 v[114:129], v[172:175], v[192:195], v[114:129]
	ds_read_b128 v[130:133], v177 offset:0
	v_mfma_f32_32x32x16_bf16 v[98:113], v[172:175], v[200:203], v[98:113]
	ds_read_b128 v[164:167], v207 offset:0
	s_add_u32 m0, s14, 0x8020
	s_add_u32 s12, s1, s4
	s_addc_u32 s13, s3, s5
	global_load_lds_dwordx4 v155, s[12:13]
	v_mfma_f32_32x32x16_bf16 v[82:97], v[180:183], v[192:195], v[82:97]
	ds_read_b128 v[168:171], v207 offset:4096
	v_mfma_f32_32x32x16_bf16 v[66:81], v[180:183], v[200:203], v[66:81]
	ds_read_b128 v[134:137], v177 offset:4096
	s_add_u32 m0, s14, 0xa020
	s_add_u32 s12, s12, 0x40000
	s_addc_u32 s13, s13, 0
	global_load_lds_dwordx4 v155, s[12:13]
	v_mfma_f32_32x32x16_bf16 v[50:65], v[184:187], v[192:195], v[50:65]
	ds_read_b128 v[156:159], v177 offset:8192
	v_mfma_f32_32x32x16_bf16 v[34:49], v[184:187], v[200:203], v[34:49]
	ds_read_b128 v[160:163], v177 offset:12288
	s_add_u32 m0, s14, 0xc020
	s_add_u32 s12, s12, 0x40000
	s_addc_u32 s13, s13, 0
	global_load_lds_dwordx4 v155, s[12:13]
	v_mfma_f32_32x32x16_bf16 v[18:33], v[188:191], v[192:195], v[18:33]
	v_mfma_f32_32x32x16_bf16 v[2:17], v[188:191], v[200:203], v[2:17]
	s_add_u32 m0, s14, 0xe020
	s_add_u32 s12, s12, 0x40000
	s_addc_u32 s13, s13, 0
	global_load_lds_dwordx4 v155, s[12:13]
	s_sub_u32 s11, s11, 1
	s_cmp_lg_u32 s11, 0
	s_cbranch_scc1 .Lg24_loop
	s_waitcnt lgkmcnt(4)
	v_mfma_f32_32x32x16_bf16 v[114:129], v[130:133], v[164:167], v[114:129]
	ds_read_b128 v[172:175], v204 offset:0
	s_waitcnt lgkmcnt(4)
	v_mfma_f32_32x32x16_bf16 v[98:113], v[130:133], v[168:171], v[98:113]
	ds_read_b128 v[192:195], v208 offset:0
	s_add_u32 m0, s14, 0x18020
	s_add_u32 s12, s9, s4
	s_addc_u32 s13, s10, s5
	global_load_lds_dwordx4 v155, s[12:13]
	s_waitcnt lgkmcnt(4)
	v_mfma_f32_32x32x16_bf16 v[82:97], v[134:137], v[164:167], v[82:97]
	ds_read_b128 v[200:203], v208 offset:4096
	v_mfma_f32_32x32x16_bf16 v[66:81], v[134:137], v[168:171], v[66:81]
	ds_read_b128 v[180:183], v204 offset:4096
	s_add_u32 m0, s14, 0x1a020
	s_add_u32 s12, s12, 0x40000
	s_addc_u32 s13, s13, 0
	global_load_lds_dwordx4 v155, s[12:13]
	s_waitcnt lgkmcnt(5)
	v_mfma_f32_32x32x16_bf16 v[50:65], v[156:159], v[164:167], v[50:65]
	ds_read_b128 v[184:187], v204 offset:8192
	v_mfma_f32_32x32x16_bf16 v[34:49], v[156:159], v[168:171], v[34:49]
	ds_read_b128 v[188:191], v204 offset:12288
	s_add_u32 m0, s14, 0x1c020
	s_add_u32 s12, s12, 0x40000
	s_addc_u32 s13, s13, 0
	global_load_lds_dwordx4 v155, s[12:13]
	s_waitcnt lgkmcnt(6)
	v_mfma_f32_32x32x16_bf16 v[18:33], v[160:163], v[164:167], v[18:33]
	v_mfma_f32_32x32x16_bf16 v[2:17], v[160:163], v[168:171], v[2:17]
	s_add_u32 m0, s14, 0x1e020
	s_add_u32 s12, s12, 0x40000
	s_addc_u32 s13, s13, 0
	global_load_lds_dwordx4 v155, s[12:13]
	s_add_u32 s4, s4, 0x80
	s_addc_u32 s5, s5, 0
	s_waitcnt lgkmcnt(4)
	v_mfma_f32_32x32x16_bf16 v[114:129], v[172:175], v[192:195], v[114:129]
	ds_read_b128 v[130:133], v205 offset:0
	s_waitcnt lgkmcnt(4)
	v_mfma_f32_32x32x16_bf16 v[98:113], v[172:175], v[200:203], v[98:113]
	ds_read_b128 v[164:167], v209 offset:0
	s_waitcnt lgkmcnt(4)
	v_mfma_f32_32x32x16_bf16 v[82:97], v[180:183], v[192:195], v[82:97]
	ds_read_b128 v[168:171], v209 offset:4096
	v_mfma_f32_32x32x16_bf16 v[66:81], v[180:183], v[200:203], v[66:81]
	ds_read_b128 v[134:137], v205 offset:4096
	s_waitcnt lgkmcnt(5)
	v_mfma_f32_32x32x16_bf16 v[50:65], v[184:187], v[192:195], v[50:65]
	ds_read_b128 v[156:159], v205 offset:8192
	v_mfma_f32_32x32x16_bf16 v[34:49], v[184:187], v[200:203], v[34:49]
	ds_read_b128 v[160:163], v205 offset:12288
	s_waitcnt lgkmcnt(6)
	v_mfma_f32_32x32x16_bf16 v[18:33], v[188:191], v[192:195], v[18:33]
	v_mfma_f32_32x32x16_bf16 v[2:17], v[188:191], v[200:203], v[2:17]
	s_waitcnt lgkmcnt(4)
	v_mfma_f32_32x32x16_bf16 v[114:129], v[130:133], v[164:167], v[114:129]
	ds_read_b128 v[172:175], v206 offset:0
	ds_read_b128 v[192:195], v210 offset:0
	s_waitcnt lgkmcnt(5)
	v_mfma_f32_32x32x16_bf16 v[98:113], v[130:133], v[168:171], v[98:113]
	ds_read_b128 v[200:203], v210 offset:4096
	ds_read_b128 v[180:183], v206 offset:4096
	s_waitcnt lgkmcnt(6)
	v_mfma_f32_32x32x16_bf16 v[82:97], v[134:137], v[164:167], v[82:97]
	ds_read_b128 v[184:187], v206 offset:8192
	ds_read_b128 v[188:191], v206 offset:12288
	v_mfma_f32_32x32x16_bf16 v[66:81], v[134:137], v[168:171], v[66:81]
	s_waitcnt lgkmcnt(7)
	v_mfma_f32_32x32x16_bf16 v[50:65], v[156:159], v[164:167], v[50:65]
	v_mfma_f32_32x32x16_bf16 v[34:49], v[156:159], v[168:171], v[34:49]
	s_waitcnt lgkmcnt(6)
	v_mfma_f32_32x32x16_bf16 v[18:33], v[160:163], v[164:167], v[18:33]
	v_mfma_f32_32x32x16_bf16 v[2:17], v[160:163], v[168:171], v[2:17]
	s_waitcnt vmcnt(0) lgkmcnt(0)
	s_barrier
	v_mfma_f32_32x32x16_bf16 v[114:129], v[172:175], v[192:195], v[114:129]
	ds_read_b128 v[130:133], v177 offset:32768
	v_mfma_f32_32x32x16_bf16 v[98:113], v[172:175], v[200:203], v[98:113]
	ds_read_b128 v[164:167], v207 offset:32768
	v_mfma_f32_32x32x16_bf16 v[82:97], v[180:183], v[192:195], v[82:97]
	ds_read_b128 v[168:171], v207 offset:36864
	v_mfma_f32_32x32x16_bf16 v[66:81], v[180:183], v[200:203], v[66:81]
	ds_read_b128 v[134:137], v177 offset:36864
	v_mfma_f32_32x32x16_bf16 v[50:65], v[184:187], v[192:195], v[50:65]
	ds_read_b128 v[156:159], v177 offset:40960
	v_mfma_f32_32x32x16_bf16 v[34:49], v[184:187], v[200:203], v[34:49]
	ds_read_b128 v[160:163], v177 offset:45056
	v_mfma_f32_32x32x16_bf16 v[18:33], v[188:191], v[192:195], v[18:33]
	v_mfma_f32_32x32x16_bf16 v[2:17], v[188:191], v[200:203], v[2:17]
	s_waitcnt lgkmcnt(4)
	v_mfma_f32_32x32x16_bf16 v[114:129], v[130:133], v[164:167], v[114:129]
	ds_read_b128 v[172:175], v204 offset:32768
	s_waitcnt lgkmcnt(4)
	v_mfma_f32_32x32x16_bf16 v[98:113], v[130:133], v[168:171], v[98:113]
	ds_read_b128 v[192:195], v208 offset:32768
	s_waitcnt lgkmcnt(4)
	v_mfma_f32_32x32x16_bf16 v[82:97], v[134:137], v[164:167], v[82:97]
	ds_read_b128 v[200:203], v208 offset:36864
	v_mfma_f32_32x32x16_bf16 v[66:81], v[134:137], v[168:171], v[66:81]
	ds_read_b128 v[180:183], v204 offset:36864
	s_waitcnt lgkmcnt(5)
	v_mfma_f32_32x32x16_bf16 v[50:65], v[156:159], v[164:167], v[50:65]
	ds_read_b128 v[184:187], v204 offset:40960
	v_mfma_f32_32x32x16_bf16 v[34:49], v[156:159], v[168:171], v[34:49]
	ds_read_b128 v[188:191], v204 offset:45056
	s_waitcnt lgkmcnt(6)
	v_mfma_f32_32x32x16_bf16 v[18:33], v[160:163], v[164:167], v[18:33]
	v_mfma_f32_32x32x16_bf16 v[2:17], v[160:163], v[168:171], v[2:17]
	s_waitcnt lgkmcnt(4)
	v_mfma_f32_32x32x16_bf16 v[114:129], v[172:175], v[192:195], v[114:129]
	ds_read_b128 v[130:133], v205 offset:32768
	s_waitcnt lgkmcnt(4)
	v_mfma_f32_32x32x16_bf16 v[98:113], v[172:175], v[200:203], v[98:113]
	ds_read_b128 v[164:167], v209 offset:32768
	s_waitcnt lgkmcnt(4)
	v_mfma_f32_32x32x16_bf16 v[82:97], v[180:183], v[192:195], v[82:97]
	ds_read_b128 v[168:171], v209 offset:36864
	v_mfma_f32_32x32x16_bf16 v[66:81], v[180:183], v[200:203], v[66:81]
	ds_read_b128 v[134:137], v205 offset:36864
	s_waitcnt lgkmcnt(5)
	v_mfma_f32_32x32x16_bf16 v[50:65], v[184:187], v[192:195], v[50:65]
	ds_read_b128 v[156:159], v205 offset:40960
	v_mfma_f32_32x32x16_bf16 v[34:49], v[184:187], v[200:203], v[34:49]
	ds_read_b128 v[160:163], v205 offset:45056
	s_waitcnt lgkmcnt(6)
	v_mfma_f32_32x32x16_bf16 v[18:33], v[188:191], v[192:195], v[18:33]
	v_mfma_f32_32x32x16_bf16 v[2:17], v[188:191], v[200:203], v[2:17]
	s_waitcnt lgkmcnt(4)
	v_mfma_f32_32x32x16_bf16 v[114:129], v[130:133], v[164:167], v[114:129]
	ds_read_b128 v[172:175], v206 offset:32768
	ds_read_b128 v[192:195], v210 offset:32768
	s_waitcnt lgkmcnt(5)
	v_mfma_f32_32x32x16_bf16 v[98:113], v[130:133], v[168:171], v[98:113]
	ds_read_b128 v[200:203], v210 offset:36864
	ds_read_b128 v[180:183], v206 offset:36864
	s_waitcnt lgkmcnt(6)
	v_mfma_f32_32x32x16_bf16 v[82:97], v[134:137], v[164:167], v[82:97]
	ds_read_b128 v[184:187], v206 offset:40960
	ds_read_b128 v[188:191], v206 offset:45056
	v_mfma_f32_32x32x16_bf16 v[66:81], v[134:137], v[168:171], v[66:81]
	s_waitcnt lgkmcnt(7)
	v_mfma_f32_32x32x16_bf16 v[50:65], v[156:159], v[164:167], v[50:65]
	v_mfma_f32_32x32x16_bf16 v[34:49], v[156:159], v[168:171], v[34:49]
	s_waitcnt lgkmcnt(6)
	v_mfma_f32_32x32x16_bf16 v[18:33], v[160:163], v[164:167], v[18:33]
	v_mfma_f32_32x32x16_bf16 v[2:17], v[160:163], v[168:171], v[2:17]
	s_waitcnt vmcnt(0) lgkmcnt(0)
	s_barrier
	v_mfma_f32_32x32x16_bf16 v[114:129], v[172:175], v[192:195], v[114:129]
	v_mfma_f32_32x32x16_bf16 v[98:113], v[172:175], v[200:203], v[98:113]
	v_mfma_f32_32x32x16_bf16 v[82:97], v[180:183], v[192:195], v[82:97]
	v_mfma_f32_32x32x16_bf16 v[66:81], v[180:183], v[200:203], v[66:81]
	v_mfma_f32_32x32x16_bf16 v[50:65], v[184:187], v[192:195], v[50:65]
	v_mfma_f32_32x32x16_bf16 v[34:49], v[184:187], v[200:203], v[34:49]
	v_mfma_f32_32x32x16_bf16 v[18:33], v[188:191], v[192:195], v[18:33]
	v_mfma_f32_32x32x16_bf16 v[2:17], v[188:191], v[200:203], v[2:17]
	v_add_u32_e32 v130, s0, v149
	v_ashrrev_i32_e32 v131, 31, v130
	v_lshrrev_b32_e32 v155, 18, v131
	v_add_u32_e32 v0, v130, v155
	v_ashrrev_i32_e32 v0, 14, v0
	v_mul_i32_i24_e32 v133, 0x4000, v0
	v_sub_u32_e32 v133, v130, v133
	v_add_u32_e32 v156, 0x100, v133
	v_mul_hi_i32_i24_e32 v137, 0x4100, v0
	v_mul_i32_i24_e32 v136, 0x4100, v0
	v_ashrrev_i32_e32 v157, 31, v156
	v_lshl_add_u64 v[136:137], v[136:137], 0, v[156:157]
	v_mov_b32_e32 v156, v179
	s_waitcnt vmcnt(0)
	s_barrier
	v_mul_i32_i24_e32 v134, 0xc00, v0
	v_readlane_b32 s40, v251, 2
	v_and_b32_e32 v0, 31, v156
	v_bfe_u32 v133, v156, 5, 1
	v_mul_u32_u24_e32 v133, 0x240, v133
	v_lshlrev_b32_e32 v0, 2, v0
	v_add3_u32 v0, v151, v133, v0
	ds_write2_b32 v0, v114, v115 offset1:36
	ds_write2_b32 v0, v116, v117 offset0:72 offset1:108
	v_add_u32_e32 v114, 0x400, v0
	v_or_b32_e32 v132, s2, v150
	ds_write2_b32 v114, v118, v119 offset0:32 offset1:68
	ds_write2_b32 v114, v120, v121 offset0:104 offset1:140
	v_add_u32_e32 v114, 0x800, v0
	v_add_u32_e32 v0, 0xc00, v0
	v_readlane_b32 s41, v251, 3
	v_readlane_b32 s42, v251, 4
	v_readlane_b32 s43, v251, 5
	v_readlane_b32 s44, v251, 6
	v_readlane_b32 s45, v251, 7
	v_readlane_b32 s46, v251, 8
	v_readlane_b32 s47, v251, 9
	v_readlane_b32 s48, v251, 10
	v_readlane_b32 s49, v251, 11
	v_readlane_b32 s50, v251, 12
	v_readlane_b32 s51, v251, 13
	v_readlane_b32 s0, v251, 26
	v_ashrrev_i32_e32 v135, 31, v134
	v_lshlrev_b64 v[136:137], 11, v[136:137]
	ds_write2_b32 v114, v122, v123 offset0:64 offset1:100
	ds_write2_b32 v114, v124, v125 offset0:136 offset1:172
	ds_write2_b32 v0, v126, v127 offset0:96 offset1:132
	ds_write2_b32 v0, v128, v129 offset0:168 offset1:204
	v_readlane_b32 s54, v251, 16
	v_readlane_b32 s55, v251, 17
	v_ashrrev_i32_e32 v133, 31, v132
	v_readlane_b32 s1, v251, 27
	v_readlane_b32 s36, v253, 47
	v_lshlrev_b32_e32 v0, 2, v156
	v_readlane_b32 s52, v251, 14
	v_readlane_b32 s53, v251, 15
	v_lshl_add_u64 v[114:115], v[134:135], 2, s[54:55]
	s_mov_b64 s[2:3], 0x1b0b000
	v_lshl_add_u64 v[118:119], s[0:1], 0, v[136:137]
	v_lshlrev_b64 v[116:117], 1, v[132:133]
	v_lshlrev_b64 v[122:123], 12, v[130:131]
	v_readlane_b32 s37, v253, 48
	v_and_b32_e32 v128, 28, v0
	v_lshl_add_u64 v[120:121], v[114:115], 0, s[2:3]
	v_lshlrev_b64 v[114:115], 2, v[132:133]
	v_lshl_add_u64 v[118:119], v[118:119], 0, v[116:117]
	v_lshl_add_u64 v[124:125], s[36:37], 0, v[122:123]
	v_lshl_add_u64 v[122:123], s[52:53], 0, v[122:123]
	v_lshlrev_b32_e32 v0, 2, v128
	v_lshlrev_b32_e32 v128, 1, v128
	v_mov_b32_e32 v129, v1
	v_bfe_u32 v133, v156, 3, 3
	v_lshl_add_u64 v[126:127], v[120:121], 0, v[114:115]
	v_lshl_add_u64 v[124:125], v[124:125], 0, v[114:115]
	v_lshl_add_u64 v[122:123], v[122:123], 0, v[114:115]
	v_lshl_add_u64 v[134:135], v[118:119], 0, v[128:129]
	v_mul_u32_u24_e32 v131, 0x90, v133
	v_lshlrev_b32_e32 v156, 11, v133
	v_mov_b32_e32 v157, v1
	s_waitcnt lgkmcnt(0)
	v_lshl_add_u64 v[126:127], v[126:127], 0, v[0:1]
	v_lshl_add_u64 v[136:137], v[124:125], 0, v[0:1]
	v_lshl_add_u64 v[128:129], v[122:123], 0, v[0:1]
	v_add3_u32 v131, v151, v0, v131
	v_lshlrev_b32_e32 v0, 12, v133
	v_lshl_add_u64 v[156:157], v[134:135], 0, v[156:157]
	v_lshl_add_u64 v[164:165], v[136:137], 0, v[0:1]
	global_load_dwordx2 v[168:169], v[156:157], off
	ds_read_b128 v[156:159], v131
	global_load_dwordx4 v[160:163], v[126:127], off
	s_nop 0
	global_load_dwordx4 v[164:167], v[164:165], off
	v_lshl_add_u64 v[170:171], v[128:129], 0, v[0:1]
	v_readlane_b32 s38, v253, 49
	v_readlane_b32 s39, v253, 50
	v_readlane_b32 s42, v253, 53
	v_readlane_b32 s43, v253, 54
	v_readlane_b32 s44, v253, 55
	v_readlane_b32 s45, v253, 56
	v_readlane_b32 s46, v253, 57
	v_readlane_b32 s47, v253, 58
	v_readlane_b32 s48, v253, 59
	v_readlane_b32 s49, v253, 60
	v_readlane_b32 s51, v253, 62
	v_readlane_b32 s40, v253, 51
	v_readlane_b32 s41, v253, 52
	v_readlane_b32 s50, v253, 61
	s_waitcnt vmcnt(2)
	v_and_b32_e32 v173, 0xffff0000, v168
	v_lshlrev_b32_e32 v172, 16, v168
	s_waitcnt vmcnt(0)
	v_pk_add_f32 v[164:165], v[164:165], v[172:173]
	s_waitcnt lgkmcnt(0)
	v_pk_fma_f32 v[156:157], v[156:157], v[160:161], v[164:165]
	v_and_b32_e32 v161, 0xffff0000, v169
	v_lshlrev_b32_e32 v160, 16, v169
	v_pk_add_f32 v[160:161], v[166:167], v[160:161]
	s_nop 0
	v_pk_fma_f32 v[158:159], v[158:159], v[162:163], v[160:161]
	global_store_dwordx4 v[170:171], v[156:159], off
	s_nop 1
	v_or_b32_e32 v156, 8, v133
	v_lshlrev_b32_e32 v0, 12, v156
	v_lshlrev_b32_e32 v156, 11, v156
	v_mov_b32_e32 v157, v1
	v_lshl_add_u64 v[156:157], v[134:135], 0, v[156:157]
	v_lshl_add_u64 v[164:165], v[136:137], 0, v[0:1]
	global_load_dwordx2 v[168:169], v[156:157], off
	ds_read_b128 v[156:159], v131 offset:1152
	global_load_dwordx4 v[160:163], v[126:127], off
	s_nop 0
	global_load_dwordx4 v[164:167], v[164:165], off
	v_lshl_add_u64 v[170:171], v[128:129], 0, v[0:1]
	v_or_b32_e32 v0, 16, v133
	s_waitcnt vmcnt(2)
	v_and_b32_e32 v173, 0xffff0000, v168
	v_lshlrev_b32_e32 v172, 16, v168
	s_waitcnt vmcnt(0)
	v_pk_add_f32 v[164:165], v[164:165], v[172:173]
	s_waitcnt lgkmcnt(0)
	v_pk_fma_f32 v[156:157], v[156:157], v[160:161], v[164:165]
	v_and_b32_e32 v161, 0xffff0000, v169
	v_lshlrev_b32_e32 v160, 16, v169
	v_pk_add_f32 v[160:161], v[166:167], v[160:161]
	s_nop 0
	v_pk_fma_f32 v[158:159], v[158:159], v[162:163], v[160:161]
	global_store_dwordx4 v[170:171], v[156:159], off
	s_nop 1
	v_lshlrev_b32_e32 v158, 11, v0
	v_mov_b32_e32 v159, v1
	v_lshlrev_b32_e32 v156, 12, v0
	v_mov_b32_e32 v157, v1
	v_lshl_add_u64 v[158:159], v[134:135], 0, v[158:159]
	v_lshl_add_u64 v[164:165], v[136:137], 0, v[156:157]
	global_load_dwordx2 v[168:169], v[158:159], off
	v_lshl_add_u64 v[170:171], v[128:129], 0, v[156:157]
	ds_read_b128 v[156:159], v131 offset:2304
	global_load_dwordx4 v[160:163], v[126:127], off
	s_nop 0
	global_load_dwordx4 v[164:167], v[164:165], off
	v_or_b32_e32 v0, 24, v133
	s_waitcnt vmcnt(2)
	v_and_b32_e32 v173, 0xffff0000, v168
	v_lshlrev_b32_e32 v172, 16, v168
	s_waitcnt vmcnt(0)
	v_pk_add_f32 v[164:165], v[164:165], v[172:173]
	s_waitcnt lgkmcnt(0)
	v_pk_fma_f32 v[156:157], v[156:157], v[160:161], v[164:165]
	v_and_b32_e32 v161, 0xffff0000, v169
	v_lshlrev_b32_e32 v160, 16, v169
	v_pk_add_f32 v[160:161], v[166:167], v[160:161]
	s_nop 0
	v_pk_fma_f32 v[158:159], v[158:159], v[162:163], v[160:161]
	global_store_dwordx4 v[170:171], v[156:159], off
	s_nop 1
	v_lshlrev_b32_e32 v156, 12, v0
	v_mov_b32_e32 v157, v1
	v_lshl_add_u64 v[158:159], v[136:137], 0, v[156:157]
	v_lshlrev_b32_e32 v136, 11, v0
	v_mov_b32_e32 v137, v1
	v_lshl_add_u64 v[134:135], v[134:135], 0, v[136:137]
	global_load_dwordx2 v[160:161], v[134:135], off
	v_lshl_add_u64 v[162:163], v[128:129], 0, v[156:157]
	ds_read_b128 v[134:137], v131 offset:3456
	global_load_dwordx4 v[126:129], v[126:127], off
	s_nop 0
	global_load_dwordx4 v[156:159], v[158:159], off
	s_waitcnt vmcnt(2)
	v_and_b32_e32 v165, 0xffff0000, v160
	v_lshlrev_b32_e32 v164, 16, v160
	s_waitcnt vmcnt(0)
	v_pk_add_f32 v[156:157], v[156:157], v[164:165]
	s_waitcnt lgkmcnt(0)
	v_pk_fma_f32 v[126:127], v[134:135], v[126:127], v[156:157]
	v_and_b32_e32 v135, 0xffff0000, v161
	v_lshlrev_b32_e32 v134, 16, v161
	v_pk_add_f32 v[134:135], v[158:159], v[134:135]
	s_nop 0
	v_pk_fma_f32 v[128:129], v[136:137], v[128:129], v[134:135]
	global_store_dwordx4 v[162:163], v[126:129], off
	v_mov_b32_e32 v0, v179
	s_nop 0
	v_or_b32_e32 v126, 32, v132
	v_and_b32_e32 v127, 31, v0
	v_bfe_u32 v128, v0, 5, 1
	v_mul_u32_u24_e32 v128, 0x240, v128
	v_lshlrev_b32_e32 v127, 2, v127
	v_add3_u32 v127, v151, v128, v127
	ds_write2_b32 v127, v98, v99 offset1:36
	ds_write2_b32 v127, v100, v101 offset0:72 offset1:108
	v_add_u32_e32 v98, 0x400, v127
	ds_write2_b32 v98, v102, v103 offset0:32 offset1:68
	ds_write2_b32 v98, v104, v105 offset0:104 offset1:140
	v_add_u32_e32 v98, 0x800, v127
	ds_write2_b32 v98, v106, v107 offset0:64 offset1:100
	ds_write2_b32 v98, v108, v109 offset0:136 offset1:172
	v_add_u32_e32 v98, 0xc00, v127
	ds_write2_b32 v98, v110, v111 offset0:96 offset1:132
	ds_write2_b32 v98, v112, v113 offset0:168 offset1:204
	v_lshlrev_b32_e32 v98, 2, v0
	v_and_b32_e32 v102, 28, v98
	v_lshlrev_b32_e32 v108, 2, v102
	v_lshlrev_b32_e32 v102, 1, v102
	v_mov_b32_e32 v103, v1
	v_bfe_u32 v131, v0, 3, 3
	v_ashrrev_i32_e32 v127, 31, v126
	v_mov_b32_e32 v109, v1
	v_lshl_add_u64 v[104:105], v[118:119], 0, v[102:103]
	v_lshlrev_b32_e32 v110, 11, v131
	v_mov_b32_e32 v111, v1
	s_waitcnt lgkmcnt(0)
	v_lshl_add_u64 v[100:101], v[120:121], 0, v[108:109]
	v_lshlrev_b64 v[98:99], 2, v[126:127]
	v_mul_u32_u24_e32 v0, 0x90, v131
	v_lshl_add_u64 v[110:111], v[104:105], 0, v[110:111]
	v_lshl_add_u64 v[100:101], v[100:101], 0, v[98:99]
	v_lshl_add_u64 v[106:107], v[124:125], 0, v[108:109]
	v_lshl_add_u64 v[102:103], v[122:123], 0, v[108:109]
	v_add3_u32 v0, v151, v108, v0
	v_lshlrev_b32_e32 v108, 12, v131
	global_load_dwordx2 v[126:127], v[110:111], off offset:64
	v_lshl_add_u64 v[112:113], v[106:107], 0, v[108:109]
	v_lshl_add_u64 v[128:129], v[102:103], 0, v[108:109]
	ds_read_b128 v[108:111], v0
	global_load_dwordx4 v[118:121], v[100:101], off
	global_load_dwordx4 v[122:125], v[112:113], off offset:128
	s_waitcnt vmcnt(2)
	v_and_b32_e32 v113, 0xffff0000, v126
	v_lshlrev_b32_e32 v112, 16, v126
	s_waitcnt vmcnt(0)
	v_pk_add_f32 v[112:113], v[122:123], v[112:113]
	s_waitcnt lgkmcnt(0)
	v_pk_fma_f32 v[108:109], v[108:109], v[118:119], v[112:113]
	v_and_b32_e32 v113, 0xffff0000, v127
	v_lshlrev_b32_e32 v112, 16, v127
	v_pk_add_f32 v[112:113], v[124:125], v[112:113]
	s_nop 0
	v_pk_fma_f32 v[110:111], v[110:111], v[120:121], v[112:113]
	global_store_dwordx4 v[128:129], v[108:111], off offset:128
	s_nop 1
	v_or_b32_e32 v110, 8, v131
	v_lshlrev_b32_e32 v108, 12, v110
	v_lshlrev_b32_e32 v110, 11, v110
	v_mov_b32_e32 v111, v1
	v_lshl_add_u64 v[110:111], v[104:105], 0, v[110:111]
	v_mov_b32_e32 v109, v1
	global_load_dwordx2 v[126:127], v[110:111], off offset:64
	v_lshl_add_u64 v[112:113], v[106:107], 0, v[108:109]
	v_lshl_add_u64 v[128:129], v[102:103], 0, v[108:109]
	ds_read_b128 v[108:111], v0 offset:1152
	global_load_dwordx4 v[118:121], v[100:101], off
	global_load_dwordx4 v[122:125], v[112:113], off offset:128
	s_waitcnt vmcnt(2)
	v_and_b32_e32 v113, 0xffff0000, v126
	v_lshlrev_b32_e32 v112, 16, v126
	s_waitcnt vmcnt(0)
	v_pk_add_f32 v[112:113], v[122:123], v[112:113]
	s_waitcnt lgkmcnt(0)
	v_pk_fma_f32 v[108:109], v[108:109], v[118:119], v[112:113]
	v_and_b32_e32 v113, 0xffff0000, v127
	v_lshlrev_b32_e32 v112, 16, v127
	v_pk_add_f32 v[112:113], v[124:125], v[112:113]
	s_nop 0
	v_pk_fma_f32 v[110:111], v[110:111], v[120:121], v[112:113]
	global_store_dwordx4 v[128:129], v[108:111], off offset:128
	s_nop 1
	v_or_b32_e32 v110, 16, v131
	v_lshlrev_b32_e32 v108, 12, v110
	v_lshlrev_b32_e32 v110, 11, v110
	v_mov_b32_e32 v111, v1
	v_lshl_add_u64 v[110:111], v[104:105], 0, v[110:111]
	v_mov_b32_e32 v109, v1
	global_load_dwordx2 v[126:127], v[110:111], off offset:64
	v_lshl_add_u64 v[112:113], v[106:107], 0, v[108:109]
	v_lshl_add_u64 v[128:129], v[102:103], 0, v[108:109]
	ds_read_b128 v[108:111], v0 offset:2304
	global_load_dwordx4 v[118:121], v[100:101], off
	global_load_dwordx4 v[122:125], v[112:113], off offset:128
	s_waitcnt vmcnt(2)
	v_and_b32_e32 v113, 0xffff0000, v126
	v_lshlrev_b32_e32 v112, 16, v126
	s_waitcnt vmcnt(0)
	v_pk_add_f32 v[112:113], v[122:123], v[112:113]
	s_waitcnt lgkmcnt(0)
	v_pk_fma_f32 v[108:109], v[108:109], v[118:119], v[112:113]
	v_and_b32_e32 v113, 0xffff0000, v127
	v_lshlrev_b32_e32 v112, 16, v127
	v_pk_add_f32 v[112:113], v[124:125], v[112:113]
	s_nop 0
	v_pk_fma_f32 v[110:111], v[110:111], v[120:121], v[112:113]
	v_or_b32_e32 v112, 24, v131
	global_store_dwordx4 v[128:129], v[108:111], off offset:128
	s_nop 1
	v_lshlrev_b32_e32 v108, 12, v112
	v_mov_b32_e32 v109, v1
	v_lshl_add_u64 v[110:111], v[106:107], 0, v[108:109]
	v_lshlrev_b32_e32 v106, 11, v112
	v_mov_b32_e32 v107, v1
	v_lshl_add_u64 v[104:105], v[104:105], 0, v[106:107]
	global_load_dwordx2 v[118:119], v[104:105], off offset:64
	v_lshl_add_u64 v[120:121], v[102:103], 0, v[108:109]
	ds_read_b128 v[102:105], v0 offset:3456
	global_load_dwordx4 v[106:109], v[100:101], off
	s_nop 0
	global_load_dwordx4 v[110:113], v[110:111], off offset:128
	s_waitcnt vmcnt(2)
	v_and_b32_e32 v101, 0xffff0000, v118
	v_lshlrev_b32_e32 v100, 16, v118
	s_waitcnt vmcnt(0)
	v_pk_add_f32 v[100:101], v[110:111], v[100:101]
	s_waitcnt lgkmcnt(0)
	v_pk_fma_f32 v[100:101], v[102:103], v[106:107], v[100:101]
	v_and_b32_e32 v103, 0xffff0000, v119
	v_lshlrev_b32_e32 v102, 16, v119
	v_pk_add_f32 v[102:103], v[112:113], v[102:103]
	s_nop 0
	v_pk_fma_f32 v[102:103], v[104:105], v[108:109], v[102:103]
	global_store_dwordx4 v[120:121], v[100:103], off offset:128
	s_nop 1
	v_or_b32_e32 v100, 32, v130
	v_add_u32_e32 v0, v100, v155
	v_ashrrev_i32_e32 v0, 14, v0
	v_mul_i32_i24_e32 v101, 0x4000, v0
	v_sub_u32_e32 v101, v100, v101
	v_add_u32_e32 v106, 0x100, v101
	v_mul_i32_i24_e32 v102, 0xc00, v0
	v_mul_hi_i32_i24_e32 v105, 0x4100, v0
	v_mul_i32_i24_e32 v104, 0x4100, v0
	v_ashrrev_i32_e32 v107, 31, v106
	v_mov_b32_e32 v0, v179
	v_lshl_add_u64 v[104:105], v[104:105], 0, v[106:107]
	v_ashrrev_i32_e32 v103, 31, v102
	v_and_b32_e32 v106, 31, v0
	v_bfe_u32 v107, v0, 5, 1
	v_mul_u32_u24_e32 v107, 0x240, v107
	v_lshlrev_b32_e32 v106, 2, v106
	v_add3_u32 v106, v151, v107, v106
	ds_write2_b32 v106, v82, v83 offset1:36
	ds_write2_b32 v106, v84, v85 offset0:72 offset1:108
	v_add_u32_e32 v82, 0x400, v106
	ds_write2_b32 v82, v86, v87 offset0:32 offset1:68
	ds_write2_b32 v82, v88, v89 offset0:104 offset1:140
	v_add_u32_e32 v82, 0x800, v106
	ds_write2_b32 v82, v90, v91 offset0:64 offset1:100
	ds_write2_b32 v82, v92, v93 offset0:136 offset1:172
	v_add_u32_e32 v82, 0xc00, v106
	v_lshlrev_b64 v[104:105], 11, v[104:105]
	v_ashrrev_i32_e32 v101, 31, v100
	ds_write2_b32 v82, v94, v95 offset0:96 offset1:132
	ds_write2_b32 v82, v96, v97 offset0:168 offset1:204
	v_lshl_add_u64 v[82:83], v[102:103], 2, s[54:55]
	v_lshlrev_b32_e32 v92, 2, v0
	v_lshl_add_u64 v[86:87], v[82:83], 0, s[2:3]
	v_lshl_add_u64 v[82:83], s[0:1], 0, v[104:105]
	v_lshlrev_b64 v[84:85], 12, v[100:101]
	v_and_b32_e32 v92, 28, v92
	v_lshl_add_u64 v[82:83], v[82:83], 0, v[116:117]
	v_lshl_add_u64 v[88:89], s[36:37], 0, v[84:85]
	v_lshl_add_u64 v[84:85], s[52:53], 0, v[84:85]
	v_lshlrev_b32_e32 v100, 2, v92
	v_lshlrev_b32_e32 v92, 1, v92
	v_mov_b32_e32 v93, v1
	v_bfe_u32 v122, v0, 3, 3
	v_lshl_add_u64 v[90:91], v[86:87], 0, v[114:115]
	v_lshl_add_u64 v[88:89], v[88:89], 0, v[114:115]
	v_lshl_add_u64 v[84:85], v[84:85], 0, v[114:115]
	v_mov_b32_e32 v101, v1
	v_lshl_add_u64 v[94:95], v[82:83], 0, v[92:93]
	v_mul_u32_u24_e32 v0, 0x90, v122
	v_lshlrev_b32_e32 v102, 11, v122
	v_mov_b32_e32 v103, v1
	s_waitcnt lgkmcnt(0)
	v_lshl_add_u64 v[90:91], v[90:91], 0, v[100:101]
	v_lshl_add_u64 v[96:97], v[88:89], 0, v[100:101]
	v_lshl_add_u64 v[92:93], v[84:85], 0, v[100:101]
	v_add3_u32 v0, v151, v100, v0
	v_lshlrev_b32_e32 v100, 12, v122
	v_lshl_add_u64 v[102:103], v[94:95], 0, v[102:103]
	v_lshl_add_u64 v[108:109], v[96:97], 0, v[100:101]
	global_load_dwordx2 v[112:113], v[102:103], off
	v_lshl_add_u64 v[118:119], v[92:93], 0, v[100:101]
	ds_read_b128 v[100:103], v0
	global_load_dwordx4 v[104:107], v[90:91], off
	s_nop 0
	global_load_dwordx4 v[108:111], v[108:109], off
	s_waitcnt vmcnt(2)
	v_and_b32_e32 v121, 0xffff0000, v112
	v_lshlrev_b32_e32 v120, 16, v112
	s_waitcnt vmcnt(0)
	v_pk_add_f32 v[108:109], v[108:109], v[120:121]
	s_waitcnt lgkmcnt(0)
	v_pk_fma_f32 v[100:101], v[100:101], v[104:105], v[108:109]
	v_and_b32_e32 v105, 0xffff0000, v113
	v_lshlrev_b32_e32 v104, 16, v113
	v_pk_add_f32 v[104:105], v[110:111], v[104:105]
	s_nop 0
	v_pk_fma_f32 v[102:103], v[102:103], v[106:107], v[104:105]
	global_store_dwordx4 v[118:119], v[100:103], off
	s_nop 1
	v_or_b32_e32 v102, 8, v122
	v_lshlrev_b32_e32 v100, 12, v102
	v_lshlrev_b32_e32 v102, 11, v102
	v_mov_b32_e32 v103, v1
	v_mov_b32_e32 v101, v1
	v_lshl_add_u64 v[102:103], v[94:95], 0, v[102:103]
	v_lshl_add_u64 v[108:109], v[96:97], 0, v[100:101]
	global_load_dwordx2 v[112:113], v[102:103], off
	v_lshl_add_u64 v[118:119], v[92:93], 0, v[100:101]
	ds_read_b128 v[100:103], v0 offset:1152
	global_load_dwordx4 v[104:107], v[90:91], off
	s_nop 0
	global_load_dwordx4 v[108:111], v[108:109], off
	s_waitcnt vmcnt(2)
	v_and_b32_e32 v121, 0xffff0000, v112
	v_lshlrev_b32_e32 v120, 16, v112
	s_waitcnt vmcnt(0)
	v_pk_add_f32 v[108:109], v[108:109], v[120:121]
	s_waitcnt lgkmcnt(0)
	v_pk_fma_f32 v[100:101], v[100:101], v[104:105], v[108:109]
	v_and_b32_e32 v105, 0xffff0000, v113
	v_lshlrev_b32_e32 v104, 16, v113
	v_pk_add_f32 v[104:105], v[110:111], v[104:105]
	s_nop 0
	v_pk_fma_f32 v[102:103], v[102:103], v[106:107], v[104:105]
	global_store_dwordx4 v[118:119], v[100:103], off
	s_nop 1
	v_or_b32_e32 v102, 16, v122
	v_lshlrev_b32_e32 v100, 12, v102
	v_lshlrev_b32_e32 v102, 11, v102
	v_mov_b32_e32 v103, v1
	v_mov_b32_e32 v101, v1
	v_lshl_add_u64 v[102:103], v[94:95], 0, v[102:103]
	v_lshl_add_u64 v[108:109], v[96:97], 0, v[100:101]
	global_load_dwordx2 v[112:113], v[102:103], off
	v_lshl_add_u64 v[118:119], v[92:93], 0, v[100:101]
	ds_read_b128 v[100:103], v0 offset:2304
	global_load_dwordx4 v[104:107], v[90:91], off
	s_nop 0
	global_load_dwordx4 v[108:111], v[108:109], off
	s_waitcnt vmcnt(2)
	v_and_b32_e32 v121, 0xffff0000, v112
	v_lshlrev_b32_e32 v120, 16, v112
	s_waitcnt vmcnt(0)
	v_pk_add_f32 v[108:109], v[108:109], v[120:121]
	s_waitcnt lgkmcnt(0)
	v_pk_fma_f32 v[100:101], v[100:101], v[104:105], v[108:109]
	v_and_b32_e32 v105, 0xffff0000, v113
	v_lshlrev_b32_e32 v104, 16, v113
	v_pk_add_f32 v[104:105], v[110:111], v[104:105]
	s_nop 0
	v_pk_fma_f32 v[102:103], v[102:103], v[106:107], v[104:105]
	global_store_dwordx4 v[118:119], v[100:103], off
	s_nop 1
	v_or_b32_e32 v102, 24, v122
	v_lshlrev_b32_e32 v100, 12, v102
	v_lshlrev_b32_e32 v102, 11, v102
	v_mov_b32_e32 v103, v1
	v_lshl_add_u64 v[94:95], v[94:95], 0, v[102:103]
	v_mov_b32_e32 v101, v1
	global_load_dwordx2 v[108:109], v[94:95], off
	v_lshl_add_u64 v[96:97], v[96:97], 0, v[100:101]
	v_lshl_add_u64 v[110:111], v[92:93], 0, v[100:101]
	ds_read_b128 v[92:95], v0 offset:3456
	global_load_dwordx4 v[100:103], v[90:91], off
	global_load_dwordx4 v[104:107], v[96:97], off
	s_waitcnt vmcnt(2)
	v_and_b32_e32 v91, 0xffff0000, v108
	v_lshlrev_b32_e32 v90, 16, v108
	s_waitcnt vmcnt(0)
	v_pk_add_f32 v[90:91], v[104:105], v[90:91]
	s_waitcnt lgkmcnt(0)
	v_pk_fma_f32 v[90:91], v[92:93], v[100:101], v[90:91]
	v_and_b32_e32 v93, 0xffff0000, v109
	v_lshlrev_b32_e32 v92, 16, v109
	v_pk_add_f32 v[92:93], v[106:107], v[92:93]
	s_nop 0
	v_pk_fma_f32 v[92:93], v[94:95], v[102:103], v[92:93]
	global_store_dwordx4 v[110:111], v[90:93], off
	v_mov_b32_e32 v0, v179
	s_nop 0
	v_and_b32_e32 v90, 31, v0
	v_bfe_u32 v91, v0, 5, 1
	v_mul_u32_u24_e32 v91, 0x240, v91
	v_lshlrev_b32_e32 v90, 2, v90
	v_add3_u32 v90, v151, v91, v90
	ds_write2_b32 v90, v66, v67 offset1:36
	ds_write2_b32 v90, v68, v69 offset0:72 offset1:108
	v_add_u32_e32 v66, 0x400, v90
	ds_write2_b32 v66, v70, v71 offset0:32 offset1:68
	ds_write2_b32 v66, v72, v73 offset0:104 offset1:140
	v_add_u32_e32 v66, 0x800, v90
	ds_write2_b32 v66, v74, v75 offset0:64 offset1:100
	ds_write2_b32 v66, v76, v77 offset0:136 offset1:172
	v_add_u32_e32 v66, 0xc00, v90
	ds_write2_b32 v66, v78, v79 offset0:96 offset1:132
	ds_write2_b32 v66, v80, v81 offset0:168 offset1:204
	v_lshlrev_b32_e32 v66, 2, v0
	v_and_b32_e32 v68, 28, v66
	v_lshlrev_b32_e32 v74, 2, v68
	v_lshlrev_b32_e32 v68, 1, v68
	v_mov_b32_e32 v69, v1
	v_bfe_u32 v92, v0, 3, 3
	v_mov_b32_e32 v75, v1
	v_lshl_add_u64 v[70:71], v[82:83], 0, v[68:69]
	v_mul_u32_u24_e32 v0, 0x90, v92
	v_lshlrev_b32_e32 v76, 11, v92
	v_mov_b32_e32 v77, v1
	s_waitcnt lgkmcnt(0)
	v_lshl_add_u64 v[66:67], v[86:87], 0, v[74:75]
	v_lshl_add_u64 v[72:73], v[88:89], 0, v[74:75]
	v_lshl_add_u64 v[68:69], v[84:85], 0, v[74:75]
	v_add3_u32 v0, v151, v74, v0
	v_lshlrev_b32_e32 v74, 12, v92
	v_lshl_add_u64 v[76:77], v[70:71], 0, v[76:77]
	v_lshl_add_u64 v[66:67], v[66:67], 0, v[98:99]
	v_lshl_add_u64 v[82:83], v[72:73], 0, v[74:75]
	global_load_dwordx2 v[86:87], v[76:77], off offset:64
	v_lshl_add_u64 v[88:89], v[68:69], 0, v[74:75]
	ds_read_b128 v[74:77], v0
	global_load_dwordx4 v[78:81], v[66:67], off
	s_nop 0
	global_load_dwordx4 v[82:85], v[82:83], off offset:128
	s_waitcnt vmcnt(2)
	v_and_b32_e32 v91, 0xffff0000, v86
	v_lshlrev_b32_e32 v90, 16, v86
	s_waitcnt vmcnt(0)
	v_pk_add_f32 v[82:83], v[82:83], v[90:91]
	s_waitcnt lgkmcnt(0)
	v_pk_fma_f32 v[74:75], v[74:75], v[78:79], v[82:83]
	v_and_b32_e32 v79, 0xffff0000, v87
	v_lshlrev_b32_e32 v78, 16, v87
	v_pk_add_f32 v[78:79], v[84:85], v[78:79]
	s_nop 0
	v_pk_fma_f32 v[76:77], v[76:77], v[80:81], v[78:79]
	global_store_dwordx4 v[88:89], v[74:77], off offset:128
	s_nop 1
	v_or_b32_e32 v76, 8, v92
	v_lshlrev_b32_e32 v74, 12, v76
	v_lshlrev_b32_e32 v76, 11, v76
	v_mov_b32_e32 v77, v1
	v_mov_b32_e32 v75, v1
	v_lshl_add_u64 v[76:77], v[70:71], 0, v[76:77]
	v_lshl_add_u64 v[82:83], v[72:73], 0, v[74:75]
	global_load_dwordx2 v[86:87], v[76:77], off offset:64
	v_lshl_add_u64 v[88:89], v[68:69], 0, v[74:75]
	ds_read_b128 v[74:77], v0 offset:1152
	global_load_dwordx4 v[78:81], v[66:67], off
	s_nop 0
	global_load_dwordx4 v[82:85], v[82:83], off offset:128
	s_waitcnt vmcnt(2)
	v_and_b32_e32 v91, 0xffff0000, v86
	v_lshlrev_b32_e32 v90, 16, v86
	s_waitcnt vmcnt(0)
	v_pk_add_f32 v[82:83], v[82:83], v[90:91]
	s_waitcnt lgkmcnt(0)
	v_pk_fma_f32 v[74:75], v[74:75], v[78:79], v[82:83]
	v_and_b32_e32 v79, 0xffff0000, v87
	v_lshlrev_b32_e32 v78, 16, v87
	v_pk_add_f32 v[78:79], v[84:85], v[78:79]
	s_nop 0
	v_pk_fma_f32 v[76:77], v[76:77], v[80:81], v[78:79]
	global_store_dwordx4 v[88:89], v[74:77], off offset:128
	s_nop 1
	v_or_b32_e32 v76, 16, v92
	v_lshlrev_b32_e32 v74, 12, v76
	v_lshlrev_b32_e32 v76, 11, v76
	v_mov_b32_e32 v77, v1
	v_mov_b32_e32 v75, v1
	v_lshl_add_u64 v[76:77], v[70:71], 0, v[76:77]
	v_lshl_add_u64 v[82:83], v[72:73], 0, v[74:75]
	global_load_dwordx2 v[86:87], v[76:77], off offset:64
	v_lshl_add_u64 v[88:89], v[68:69], 0, v[74:75]
	ds_read_b128 v[74:77], v0 offset:2304
	global_load_dwordx4 v[78:81], v[66:67], off
	s_nop 0
	global_load_dwordx4 v[82:85], v[82:83], off offset:128
	s_waitcnt vmcnt(2)
	v_and_b32_e32 v91, 0xffff0000, v86
	v_lshlrev_b32_e32 v90, 16, v86
	s_waitcnt vmcnt(0)
	v_pk_add_f32 v[82:83], v[82:83], v[90:91]
	s_waitcnt lgkmcnt(0)
	v_pk_fma_f32 v[74:75], v[74:75], v[78:79], v[82:83]
	v_and_b32_e32 v79, 0xffff0000, v87
	v_lshlrev_b32_e32 v78, 16, v87
	v_pk_add_f32 v[78:79], v[84:85], v[78:79]
	s_nop 0
	v_pk_fma_f32 v[76:77], v[76:77], v[80:81], v[78:79]
	v_or_b32_e32 v78, 24, v92
	global_store_dwordx4 v[88:89], v[74:77], off offset:128
	s_nop 1
	v_lshlrev_b32_e32 v74, 12, v78
	v_mov_b32_e32 v75, v1
	v_lshl_add_u64 v[76:77], v[72:73], 0, v[74:75]
	v_lshlrev_b32_e32 v72, 11, v78
	v_mov_b32_e32 v73, v1
	v_lshl_add_u64 v[70:71], v[70:71], 0, v[72:73]
	global_load_dwordx2 v[80:81], v[70:71], off offset:64
	v_lshl_add_u64 v[82:83], v[68:69], 0, v[74:75]
	ds_read_b128 v[68:71], v0 offset:3456
	global_load_dwordx4 v[72:75], v[66:67], off
	s_nop 0
	global_load_dwordx4 v[76:79], v[76:77], off offset:128
	s_waitcnt vmcnt(2)
	v_and_b32_e32 v67, 0xffff0000, v80
	v_lshlrev_b32_e32 v66, 16, v80
	s_waitcnt vmcnt(0)
	v_pk_add_f32 v[66:67], v[76:77], v[66:67]
	s_waitcnt lgkmcnt(0)
	v_pk_fma_f32 v[66:67], v[68:69], v[72:73], v[66:67]
	v_and_b32_e32 v69, 0xffff0000, v81
	v_lshlrev_b32_e32 v68, 16, v81
	v_pk_add_f32 v[68:69], v[78:79], v[68:69]
	s_nop 0
	v_pk_fma_f32 v[68:69], v[70:71], v[74:75], v[68:69]
	global_store_dwordx4 v[82:83], v[66:69], off offset:128
	s_nop 1
	v_or_b32_e32 v66, 64, v130
	v_add_u32_e32 v0, v66, v155
	v_ashrrev_i32_e32 v0, 14, v0
	v_mul_i32_i24_e32 v67, 0x4000, v0
	v_sub_u32_e32 v67, v66, v67
	v_add_u32_e32 v72, 0x100, v67
	v_mul_i32_i24_e32 v68, 0xc00, v0
	v_mul_hi_i32_i24_e32 v71, 0x4100, v0
	v_mul_i32_i24_e32 v70, 0x4100, v0
	v_ashrrev_i32_e32 v73, 31, v72
	v_mov_b32_e32 v0, v179
	v_lshl_add_u64 v[70:71], v[70:71], 0, v[72:73]
	v_ashrrev_i32_e32 v69, 31, v68
	v_and_b32_e32 v72, 31, v0
	v_bfe_u32 v73, v0, 5, 1
	v_mul_u32_u24_e32 v73, 0x240, v73
	v_lshlrev_b32_e32 v72, 2, v72
	v_add3_u32 v72, v151, v73, v72
	ds_write2_b32 v72, v50, v51 offset1:36
	ds_write2_b32 v72, v52, v53 offset0:72 offset1:108
	v_add_u32_e32 v50, 0x400, v72
	ds_write2_b32 v50, v54, v55 offset0:32 offset1:68
	ds_write2_b32 v50, v56, v57 offset0:104 offset1:140
	v_add_u32_e32 v50, 0x800, v72
	ds_write2_b32 v50, v58, v59 offset0:64 offset1:100
	ds_write2_b32 v50, v60, v61 offset0:136 offset1:172
	v_add_u32_e32 v50, 0xc00, v72
	v_lshlrev_b64 v[70:71], 11, v[70:71]
	v_ashrrev_i32_e32 v67, 31, v66
	ds_write2_b32 v50, v62, v63 offset0:96 offset1:132
	ds_write2_b32 v50, v64, v65 offset0:168 offset1:204
	v_lshl_add_u64 v[50:51], v[68:69], 2, s[54:55]
	v_lshlrev_b32_e32 v60, 2, v0
	v_lshl_add_u64 v[54:55], v[50:51], 0, s[2:3]
	v_lshl_add_u64 v[50:51], s[0:1], 0, v[70:71]
	v_lshlrev_b64 v[52:53], 12, v[66:67]
	v_and_b32_e32 v60, 28, v60
	v_lshl_add_u64 v[50:51], v[50:51], 0, v[116:117]
	v_lshl_add_u64 v[56:57], s[36:37], 0, v[52:53]
	v_lshl_add_u64 v[52:53], s[52:53], 0, v[52:53]
	v_lshlrev_b32_e32 v66, 2, v60
	v_lshlrev_b32_e32 v60, 1, v60
	v_mov_b32_e32 v61, v1
	v_bfe_u32 v84, v0, 3, 3
	v_lshl_add_u64 v[58:59], v[54:55], 0, v[114:115]
	v_lshl_add_u64 v[56:57], v[56:57], 0, v[114:115]
	v_lshl_add_u64 v[52:53], v[52:53], 0, v[114:115]
	v_mov_b32_e32 v67, v1
	v_lshl_add_u64 v[62:63], v[50:51], 0, v[60:61]
	v_mul_u32_u24_e32 v0, 0x90, v84
	v_lshlrev_b32_e32 v68, 11, v84
	v_mov_b32_e32 v69, v1
	s_waitcnt lgkmcnt(0)
	v_lshl_add_u64 v[58:59], v[58:59], 0, v[66:67]
	v_lshl_add_u64 v[64:65], v[56:57], 0, v[66:67]
	v_lshl_add_u64 v[60:61], v[52:53], 0, v[66:67]
	v_add3_u32 v0, v151, v66, v0
	v_lshlrev_b32_e32 v66, 12, v84
	v_lshl_add_u64 v[68:69], v[62:63], 0, v[68:69]
	v_lshl_add_u64 v[74:75], v[64:65], 0, v[66:67]
	global_load_dwordx2 v[78:79], v[68:69], off
	v_lshl_add_u64 v[80:81], v[60:61], 0, v[66:67]
	ds_read_b128 v[66:69], v0
	global_load_dwordx4 v[70:73], v[58:59], off
	s_nop 0
	global_load_dwordx4 v[74:77], v[74:75], off
	s_waitcnt vmcnt(2)
	v_and_b32_e32 v83, 0xffff0000, v78
	v_lshlrev_b32_e32 v82, 16, v78
	s_waitcnt vmcnt(0)
	v_pk_add_f32 v[74:75], v[74:75], v[82:83]
	s_waitcnt lgkmcnt(0)
	v_pk_fma_f32 v[66:67], v[66:67], v[70:71], v[74:75]
	v_and_b32_e32 v71, 0xffff0000, v79
	v_lshlrev_b32_e32 v70, 16, v79
	v_pk_add_f32 v[70:71], v[76:77], v[70:71]
	s_nop 0
	v_pk_fma_f32 v[68:69], v[68:69], v[72:73], v[70:71]
	global_store_dwordx4 v[80:81], v[66:69], off
	s_nop 1
	v_or_b32_e32 v68, 8, v84
	v_lshlrev_b32_e32 v66, 12, v68
	v_lshlrev_b32_e32 v68, 11, v68
	v_mov_b32_e32 v69, v1
	v_mov_b32_e32 v67, v1
	v_lshl_add_u64 v[68:69], v[62:63], 0, v[68:69]
	v_lshl_add_u64 v[74:75], v[64:65], 0, v[66:67]
	global_load_dwordx2 v[78:79], v[68:69], off
	v_lshl_add_u64 v[80:81], v[60:61], 0, v[66:67]
	ds_read_b128 v[66:69], v0 offset:1152
	global_load_dwordx4 v[70:73], v[58:59], off
	s_nop 0
	global_load_dwordx4 v[74:77], v[74:75], off
	s_waitcnt vmcnt(2)
	v_and_b32_e32 v83, 0xffff0000, v78
	v_lshlrev_b32_e32 v82, 16, v78
	s_waitcnt vmcnt(0)
	v_pk_add_f32 v[74:75], v[74:75], v[82:83]
	s_waitcnt lgkmcnt(0)
	v_pk_fma_f32 v[66:67], v[66:67], v[70:71], v[74:75]
	v_and_b32_e32 v71, 0xffff0000, v79
	v_lshlrev_b32_e32 v70, 16, v79
	v_pk_add_f32 v[70:71], v[76:77], v[70:71]
	s_nop 0
	v_pk_fma_f32 v[68:69], v[68:69], v[72:73], v[70:71]
	global_store_dwordx4 v[80:81], v[66:69], off
	s_nop 1
	v_or_b32_e32 v68, 16, v84
	v_lshlrev_b32_e32 v66, 12, v68
	v_lshlrev_b32_e32 v68, 11, v68
	v_mov_b32_e32 v69, v1
	v_mov_b32_e32 v67, v1
	v_lshl_add_u64 v[68:69], v[62:63], 0, v[68:69]
	v_lshl_add_u64 v[74:75], v[64:65], 0, v[66:67]
	global_load_dwordx2 v[78:79], v[68:69], off
	v_lshl_add_u64 v[80:81], v[60:61], 0, v[66:67]
	ds_read_b128 v[66:69], v0 offset:2304
	global_load_dwordx4 v[70:73], v[58:59], off
	s_nop 0
	global_load_dwordx4 v[74:77], v[74:75], off
	s_waitcnt vmcnt(2)
	v_and_b32_e32 v83, 0xffff0000, v78
	v_lshlrev_b32_e32 v82, 16, v78
	s_waitcnt vmcnt(0)
	v_pk_add_f32 v[74:75], v[74:75], v[82:83]
	s_waitcnt lgkmcnt(0)
	v_pk_fma_f32 v[66:67], v[66:67], v[70:71], v[74:75]
	v_and_b32_e32 v71, 0xffff0000, v79
	v_lshlrev_b32_e32 v70, 16, v79
	v_pk_add_f32 v[70:71], v[76:77], v[70:71]
	s_nop 0
	v_pk_fma_f32 v[68:69], v[68:69], v[72:73], v[70:71]
	v_or_b32_e32 v70, 24, v84
	global_store_dwordx4 v[80:81], v[66:69], off
	s_nop 1
	v_lshlrev_b32_e32 v66, 12, v70
	v_mov_b32_e32 v67, v1
	v_lshl_add_u64 v[68:69], v[64:65], 0, v[66:67]
	v_lshlrev_b32_e32 v64, 11, v70
	v_mov_b32_e32 v65, v1
	v_lshl_add_u64 v[62:63], v[62:63], 0, v[64:65]
	global_load_dwordx2 v[72:73], v[62:63], off
	v_lshl_add_u64 v[74:75], v[60:61], 0, v[66:67]
	ds_read_b128 v[60:63], v0 offset:3456
	global_load_dwordx4 v[64:67], v[58:59], off
	s_nop 0
	global_load_dwordx4 v[68:71], v[68:69], off
	s_waitcnt vmcnt(2)
	v_and_b32_e32 v59, 0xffff0000, v72
	v_lshlrev_b32_e32 v58, 16, v72
	s_waitcnt vmcnt(0)
	v_pk_add_f32 v[58:59], v[68:69], v[58:59]
	s_waitcnt lgkmcnt(0)
	v_pk_fma_f32 v[58:59], v[60:61], v[64:65], v[58:59]
	v_and_b32_e32 v61, 0xffff0000, v73
	v_lshlrev_b32_e32 v60, 16, v73
	v_pk_add_f32 v[60:61], v[70:71], v[60:61]
	s_nop 0
	v_pk_fma_f32 v[60:61], v[62:63], v[66:67], v[60:61]
	global_store_dwordx4 v[74:75], v[58:61], off
	v_mov_b32_e32 v0, v179
	s_nop 0
	v_and_b32_e32 v58, 31, v0
	v_bfe_u32 v59, v0, 5, 1
	v_mul_u32_u24_e32 v59, 0x240, v59
	v_lshlrev_b32_e32 v58, 2, v58
	v_add3_u32 v58, v151, v59, v58
	ds_write2_b32 v58, v34, v35 offset1:36
	ds_write2_b32 v58, v36, v37 offset0:72 offset1:108
	v_add_u32_e32 v34, 0x400, v58
	ds_write2_b32 v34, v38, v39 offset0:32 offset1:68
	ds_write2_b32 v34, v40, v41 offset0:104 offset1:140
	v_add_u32_e32 v34, 0x800, v58
	ds_write2_b32 v34, v42, v43 offset0:64 offset1:100
	ds_write2_b32 v34, v44, v45 offset0:136 offset1:172
	v_add_u32_e32 v34, 0xc00, v58
	ds_write2_b32 v34, v46, v47 offset0:96 offset1:132
	ds_write2_b32 v34, v48, v49 offset0:168 offset1:204
	v_lshlrev_b32_e32 v34, 2, v0
	v_and_b32_e32 v36, 28, v34
	v_lshlrev_b32_e32 v42, 2, v36
	v_lshlrev_b32_e32 v36, 1, v36
	v_mov_b32_e32 v37, v1
	v_bfe_u32 v60, v0, 3, 3
	v_mov_b32_e32 v43, v1
	v_lshl_add_u64 v[38:39], v[50:51], 0, v[36:37]
	v_mul_u32_u24_e32 v0, 0x90, v60
	v_lshlrev_b32_e32 v44, 11, v60
	v_mov_b32_e32 v45, v1
	s_waitcnt lgkmcnt(0)
	v_lshl_add_u64 v[34:35], v[54:55], 0, v[42:43]
	v_lshl_add_u64 v[40:41], v[56:57], 0, v[42:43]
	v_lshl_add_u64 v[36:37], v[52:53], 0, v[42:43]
	v_add3_u32 v0, v151, v42, v0
	v_lshlrev_b32_e32 v42, 12, v60
	v_lshl_add_u64 v[44:45], v[38:39], 0, v[44:45]
	v_lshl_add_u64 v[34:35], v[34:35], 0, v[98:99]
	v_lshl_add_u64 v[50:51], v[40:41], 0, v[42:43]
	global_load_dwordx2 v[54:55], v[44:45], off offset:64
	v_lshl_add_u64 v[56:57], v[36:37], 0, v[42:43]
	ds_read_b128 v[42:45], v0
	global_load_dwordx4 v[46:49], v[34:35], off
	s_nop 0
	global_load_dwordx4 v[50:53], v[50:51], off offset:128
	s_waitcnt vmcnt(2)
	v_and_b32_e32 v59, 0xffff0000, v54
	v_lshlrev_b32_e32 v58, 16, v54
	s_waitcnt vmcnt(0)
	v_pk_add_f32 v[50:51], v[50:51], v[58:59]
	s_waitcnt lgkmcnt(0)
	v_pk_fma_f32 v[42:43], v[42:43], v[46:47], v[50:51]
	v_and_b32_e32 v47, 0xffff0000, v55
	v_lshlrev_b32_e32 v46, 16, v55
	v_pk_add_f32 v[46:47], v[52:53], v[46:47]
	s_nop 0
	v_pk_fma_f32 v[44:45], v[44:45], v[48:49], v[46:47]
	global_store_dwordx4 v[56:57], v[42:45], off offset:128
	s_nop 1
	v_or_b32_e32 v44, 8, v60
	v_lshlrev_b32_e32 v42, 12, v44
	v_lshlrev_b32_e32 v44, 11, v44
	v_mov_b32_e32 v45, v1
	v_mov_b32_e32 v43, v1
	v_lshl_add_u64 v[44:45], v[38:39], 0, v[44:45]
	v_lshl_add_u64 v[50:51], v[40:41], 0, v[42:43]
	global_load_dwordx2 v[54:55], v[44:45], off offset:64
	v_lshl_add_u64 v[56:57], v[36:37], 0, v[42:43]
	ds_read_b128 v[42:45], v0 offset:1152
	global_load_dwordx4 v[46:49], v[34:35], off
	s_nop 0
	global_load_dwordx4 v[50:53], v[50:51], off offset:128
	s_waitcnt vmcnt(2)
	v_and_b32_e32 v59, 0xffff0000, v54
	v_lshlrev_b32_e32 v58, 16, v54
	s_waitcnt vmcnt(0)
	v_pk_add_f32 v[50:51], v[50:51], v[58:59]
	s_waitcnt lgkmcnt(0)
	v_pk_fma_f32 v[42:43], v[42:43], v[46:47], v[50:51]
	v_and_b32_e32 v47, 0xffff0000, v55
	v_lshlrev_b32_e32 v46, 16, v55
	v_pk_add_f32 v[46:47], v[52:53], v[46:47]
	s_nop 0
	v_pk_fma_f32 v[44:45], v[44:45], v[48:49], v[46:47]
	global_store_dwordx4 v[56:57], v[42:45], off offset:128
	s_nop 1
	v_or_b32_e32 v44, 16, v60
	v_lshlrev_b32_e32 v42, 12, v44
	v_lshlrev_b32_e32 v44, 11, v44
	v_mov_b32_e32 v45, v1
	v_mov_b32_e32 v43, v1
	v_lshl_add_u64 v[44:45], v[38:39], 0, v[44:45]
	v_lshl_add_u64 v[50:51], v[40:41], 0, v[42:43]
	global_load_dwordx2 v[54:55], v[44:45], off offset:64
	v_lshl_add_u64 v[56:57], v[36:37], 0, v[42:43]
	ds_read_b128 v[42:45], v0 offset:2304
	global_load_dwordx4 v[46:49], v[34:35], off
	s_nop 0
	global_load_dwordx4 v[50:53], v[50:51], off offset:128
	s_waitcnt vmcnt(2)
	v_and_b32_e32 v59, 0xffff0000, v54
	v_lshlrev_b32_e32 v58, 16, v54
	s_waitcnt vmcnt(0)
	v_pk_add_f32 v[50:51], v[50:51], v[58:59]
	s_waitcnt lgkmcnt(0)
	v_pk_fma_f32 v[42:43], v[42:43], v[46:47], v[50:51]
	v_and_b32_e32 v47, 0xffff0000, v55
	v_lshlrev_b32_e32 v46, 16, v55
	v_pk_add_f32 v[46:47], v[52:53], v[46:47]
	s_nop 0
	v_pk_fma_f32 v[44:45], v[44:45], v[48:49], v[46:47]
	v_or_b32_e32 v46, 24, v60
	global_store_dwordx4 v[56:57], v[42:45], off offset:128
	s_nop 1
	v_lshlrev_b32_e32 v42, 12, v46
	v_mov_b32_e32 v43, v1
	v_lshl_add_u64 v[44:45], v[40:41], 0, v[42:43]
	v_lshlrev_b32_e32 v40, 11, v46
	v_mov_b32_e32 v41, v1
	v_lshl_add_u64 v[38:39], v[38:39], 0, v[40:41]
	global_load_dwordx2 v[48:49], v[38:39], off offset:64
	v_lshl_add_u64 v[50:51], v[36:37], 0, v[42:43]
	ds_read_b128 v[36:39], v0 offset:3456
	global_load_dwordx4 v[40:43], v[34:35], off
	s_nop 0
	global_load_dwordx4 v[44:47], v[44:45], off offset:128
	s_waitcnt vmcnt(2)
	v_and_b32_e32 v35, 0xffff0000, v48
	v_lshlrev_b32_e32 v34, 16, v48
	s_waitcnt vmcnt(0)
	v_pk_add_f32 v[34:35], v[44:45], v[34:35]
	s_waitcnt lgkmcnt(0)
	v_pk_fma_f32 v[34:35], v[36:37], v[40:41], v[34:35]
	v_and_b32_e32 v37, 0xffff0000, v49
	v_lshlrev_b32_e32 v36, 16, v49
	v_pk_add_f32 v[36:37], v[46:47], v[36:37]
	s_nop 0
	v_pk_fma_f32 v[36:37], v[38:39], v[42:43], v[36:37]
	global_store_dwordx4 v[50:51], v[34:37], off offset:128
	s_nop 1
	v_or_b32_e32 v34, 0x60, v130
	v_add_u32_e32 v0, v34, v155
	v_ashrrev_i32_e32 v0, 14, v0
	v_mul_i32_i24_e32 v35, 0x4000, v0
	v_sub_u32_e32 v35, v34, v35
	v_add_u32_e32 v40, 0x100, v35
	v_mul_i32_i24_e32 v36, 0xc00, v0
	v_mul_hi_i32_i24_e32 v39, 0x4100, v0
	v_mul_i32_i24_e32 v38, 0x4100, v0
	v_ashrrev_i32_e32 v41, 31, v40
	v_mov_b32_e32 v0, v179
	v_lshl_add_u64 v[38:39], v[38:39], 0, v[40:41]
	v_ashrrev_i32_e32 v37, 31, v36
	v_and_b32_e32 v40, 31, v0
	v_bfe_u32 v41, v0, 5, 1
	v_mul_u32_u24_e32 v41, 0x240, v41
	v_lshlrev_b32_e32 v40, 2, v40
	v_add3_u32 v40, v151, v41, v40
	ds_write2_b32 v40, v18, v19 offset1:36
	ds_write2_b32 v40, v20, v21 offset0:72 offset1:108
	v_add_u32_e32 v18, 0x400, v40
	ds_write2_b32 v18, v22, v23 offset0:32 offset1:68
	ds_write2_b32 v18, v24, v25 offset0:104 offset1:140
	v_add_u32_e32 v18, 0x800, v40
	ds_write2_b32 v18, v26, v27 offset0:64 offset1:100
	ds_write2_b32 v18, v28, v29 offset0:136 offset1:172
	v_add_u32_e32 v18, 0xc00, v40
	v_lshlrev_b64 v[38:39], 11, v[38:39]
	v_ashrrev_i32_e32 v35, 31, v34
	ds_write2_b32 v18, v30, v31 offset0:96 offset1:132
	ds_write2_b32 v18, v32, v33 offset0:168 offset1:204
	v_lshl_add_u64 v[18:19], v[36:37], 2, s[54:55]
	v_lshlrev_b32_e32 v28, 2, v0
	v_lshl_add_u64 v[20:21], v[18:19], 0, s[2:3]
	v_lshl_add_u64 v[18:19], s[0:1], 0, v[38:39]
	v_lshlrev_b64 v[22:23], 12, v[34:35]
	v_and_b32_e32 v28, 28, v28
	v_lshl_add_u64 v[18:19], v[18:19], 0, v[116:117]
	v_lshl_add_u64 v[24:25], s[36:37], 0, v[22:23]
	v_lshl_add_u64 v[22:23], s[52:53], 0, v[22:23]
	v_lshlrev_b32_e32 v34, 2, v28
	v_lshlrev_b32_e32 v28, 1, v28
	v_mov_b32_e32 v29, v1
	v_bfe_u32 v52, v0, 3, 3
	v_lshl_add_u64 v[26:27], v[20:21], 0, v[114:115]
	v_lshl_add_u64 v[24:25], v[24:25], 0, v[114:115]
	v_lshl_add_u64 v[22:23], v[22:23], 0, v[114:115]
	v_mov_b32_e32 v35, v1
	v_lshl_add_u64 v[30:31], v[18:19], 0, v[28:29]
	v_mul_u32_u24_e32 v0, 0x90, v52
	v_lshlrev_b32_e32 v36, 11, v52
	v_mov_b32_e32 v37, v1
	s_waitcnt lgkmcnt(0)
	v_lshl_add_u64 v[26:27], v[26:27], 0, v[34:35]
	v_lshl_add_u64 v[32:33], v[24:25], 0, v[34:35]
	v_lshl_add_u64 v[28:29], v[22:23], 0, v[34:35]
	v_add3_u32 v0, v151, v34, v0
	v_lshlrev_b32_e32 v34, 12, v52
	v_lshl_add_u64 v[36:37], v[30:31], 0, v[36:37]
	v_lshl_add_u64 v[42:43], v[32:33], 0, v[34:35]
	global_load_dwordx2 v[46:47], v[36:37], off
	v_lshl_add_u64 v[48:49], v[28:29], 0, v[34:35]
	ds_read_b128 v[34:37], v0
	global_load_dwordx4 v[38:41], v[26:27], off
	s_nop 0
	global_load_dwordx4 v[42:45], v[42:43], off
	s_waitcnt vmcnt(2)
	v_and_b32_e32 v51, 0xffff0000, v46
	v_lshlrev_b32_e32 v50, 16, v46
	s_waitcnt vmcnt(0)
	v_pk_add_f32 v[42:43], v[42:43], v[50:51]
	s_waitcnt lgkmcnt(0)
	v_pk_fma_f32 v[34:35], v[34:35], v[38:39], v[42:43]
	v_and_b32_e32 v39, 0xffff0000, v47
	v_lshlrev_b32_e32 v38, 16, v47
	v_pk_add_f32 v[38:39], v[44:45], v[38:39]
	s_nop 0
	v_pk_fma_f32 v[36:37], v[36:37], v[40:41], v[38:39]
	global_store_dwordx4 v[48:49], v[34:37], off
	s_nop 1
	v_or_b32_e32 v36, 8, v52
	v_lshlrev_b32_e32 v34, 12, v36
	v_lshlrev_b32_e32 v36, 11, v36
	v_mov_b32_e32 v37, v1
	v_mov_b32_e32 v35, v1
	v_lshl_add_u64 v[36:37], v[30:31], 0, v[36:37]
	v_lshl_add_u64 v[42:43], v[32:33], 0, v[34:35]
	global_load_dwordx2 v[46:47], v[36:37], off
	v_lshl_add_u64 v[48:49], v[28:29], 0, v[34:35]
	ds_read_b128 v[34:37], v0 offset:1152
	global_load_dwordx4 v[38:41], v[26:27], off
	s_nop 0
	global_load_dwordx4 v[42:45], v[42:43], off
	s_waitcnt vmcnt(2)
	v_and_b32_e32 v51, 0xffff0000, v46
	v_lshlrev_b32_e32 v50, 16, v46
	s_waitcnt vmcnt(0)
	v_pk_add_f32 v[42:43], v[42:43], v[50:51]
	s_waitcnt lgkmcnt(0)
	v_pk_fma_f32 v[34:35], v[34:35], v[38:39], v[42:43]
	v_and_b32_e32 v39, 0xffff0000, v47
	v_lshlrev_b32_e32 v38, 16, v47
	v_pk_add_f32 v[38:39], v[44:45], v[38:39]
	s_nop 0
	v_pk_fma_f32 v[36:37], v[36:37], v[40:41], v[38:39]
	global_store_dwordx4 v[48:49], v[34:37], off
	s_nop 1
	v_or_b32_e32 v36, 16, v52
	v_lshlrev_b32_e32 v34, 12, v36
	v_lshlrev_b32_e32 v36, 11, v36
	v_mov_b32_e32 v37, v1
	v_mov_b32_e32 v35, v1
	v_lshl_add_u64 v[36:37], v[30:31], 0, v[36:37]
	v_lshl_add_u64 v[42:43], v[32:33], 0, v[34:35]
	global_load_dwordx2 v[46:47], v[36:37], off
	v_lshl_add_u64 v[48:49], v[28:29], 0, v[34:35]
	ds_read_b128 v[34:37], v0 offset:2304
	global_load_dwordx4 v[38:41], v[26:27], off
	s_nop 0
	global_load_dwordx4 v[42:45], v[42:43], off
	s_waitcnt vmcnt(2)
	v_and_b32_e32 v51, 0xffff0000, v46
	v_lshlrev_b32_e32 v50, 16, v46
	s_waitcnt vmcnt(0)
	v_pk_add_f32 v[42:43], v[42:43], v[50:51]
	s_waitcnt lgkmcnt(0)
	v_pk_fma_f32 v[34:35], v[34:35], v[38:39], v[42:43]
	v_and_b32_e32 v39, 0xffff0000, v47
	v_lshlrev_b32_e32 v38, 16, v47
	v_pk_add_f32 v[38:39], v[44:45], v[38:39]
	s_nop 0
	v_pk_fma_f32 v[36:37], v[36:37], v[40:41], v[38:39]
	v_or_b32_e32 v38, 24, v52
	global_store_dwordx4 v[48:49], v[34:37], off
	s_nop 1
	v_lshlrev_b32_e32 v34, 12, v38
	v_mov_b32_e32 v35, v1
	v_lshl_add_u64 v[36:37], v[32:33], 0, v[34:35]
	v_lshlrev_b32_e32 v32, 11, v38
	v_mov_b32_e32 v33, v1
	v_lshl_add_u64 v[30:31], v[30:31], 0, v[32:33]
	global_load_dwordx2 v[40:41], v[30:31], off
	v_lshl_add_u64 v[42:43], v[28:29], 0, v[34:35]
	ds_read_b128 v[28:31], v0 offset:3456
	global_load_dwordx4 v[32:35], v[26:27], off
	s_nop 0
	global_load_dwordx4 v[36:39], v[36:37], off
	s_waitcnt vmcnt(2)
	v_and_b32_e32 v27, 0xffff0000, v40
	v_lshlrev_b32_e32 v26, 16, v40
	s_waitcnt vmcnt(0)
	v_pk_add_f32 v[26:27], v[36:37], v[26:27]
	s_waitcnt lgkmcnt(0)
	v_pk_fma_f32 v[26:27], v[28:29], v[32:33], v[26:27]
	v_and_b32_e32 v29, 0xffff0000, v41
	v_lshlrev_b32_e32 v28, 16, v41
	v_pk_add_f32 v[28:29], v[38:39], v[28:29]
	s_nop 0
	v_pk_fma_f32 v[28:29], v[30:31], v[34:35], v[28:29]
	global_store_dwordx4 v[42:43], v[26:29], off
	v_mov_b32_e32 v0, v179
	s_nop 0
	v_and_b32_e32 v26, 31, v0
	v_bfe_u32 v27, v0, 5, 1
	v_mul_u32_u24_e32 v27, 0x240, v27
	v_lshlrev_b32_e32 v26, 2, v26
	v_add3_u32 v26, v151, v27, v26
	ds_write2_b32 v26, v2, v3 offset1:36
	ds_write2_b32 v26, v4, v5 offset0:72 offset1:108
	v_add_u32_e32 v2, 0x400, v26
	ds_write2_b32 v2, v6, v7 offset0:32 offset1:68
	ds_write2_b32 v2, v8, v9 offset0:104 offset1:140
	v_add_u32_e32 v2, 0x800, v26
	ds_write2_b32 v2, v10, v11 offset0:64 offset1:100
	ds_write2_b32 v2, v12, v13 offset0:136 offset1:172
	v_add_u32_e32 v2, 0xc00, v26
	ds_write2_b32 v2, v14, v15 offset0:96 offset1:132
	ds_write2_b32 v2, v16, v17 offset0:168 offset1:204
	v_lshlrev_b32_e32 v2, 2, v0
	v_and_b32_e32 v4, 28, v2
	v_lshlrev_b32_e32 v10, 2, v4
	v_lshlrev_b32_e32 v4, 1, v4
	v_mov_b32_e32 v5, v1
	v_bfe_u32 v28, v0, 3, 3
	v_mov_b32_e32 v11, v1
	v_lshl_add_u64 v[6:7], v[18:19], 0, v[4:5]
	v_mul_u32_u24_e32 v0, 0x90, v28
	v_lshlrev_b32_e32 v12, 11, v28
	v_mov_b32_e32 v13, v1
	s_waitcnt lgkmcnt(0)
	v_lshl_add_u64 v[2:3], v[20:21], 0, v[10:11]
	v_lshl_add_u64 v[8:9], v[24:25], 0, v[10:11]
	v_lshl_add_u64 v[4:5], v[22:23], 0, v[10:11]
	v_add3_u32 v0, v151, v10, v0
	v_lshlrev_b32_e32 v10, 12, v28
	v_lshl_add_u64 v[12:13], v[6:7], 0, v[12:13]
	v_lshl_add_u64 v[2:3], v[2:3], 0, v[98:99]
	v_lshl_add_u64 v[18:19], v[8:9], 0, v[10:11]
	global_load_dwordx2 v[22:23], v[12:13], off offset:64
	v_lshl_add_u64 v[24:25], v[4:5], 0, v[10:11]
	ds_read_b128 v[10:13], v0
	global_load_dwordx4 v[14:17], v[2:3], off
	s_nop 0
	global_load_dwordx4 v[18:21], v[18:19], off offset:128
	s_waitcnt vmcnt(2)
	v_and_b32_e32 v27, 0xffff0000, v22
	v_lshlrev_b32_e32 v26, 16, v22
	s_waitcnt vmcnt(0)
	v_pk_add_f32 v[18:19], v[18:19], v[26:27]
	s_waitcnt lgkmcnt(0)
	v_pk_fma_f32 v[10:11], v[10:11], v[14:15], v[18:19]
	v_and_b32_e32 v15, 0xffff0000, v23
	v_lshlrev_b32_e32 v14, 16, v23
	v_pk_add_f32 v[14:15], v[20:21], v[14:15]
	s_nop 0
	v_pk_fma_f32 v[12:13], v[12:13], v[16:17], v[14:15]
	global_store_dwordx4 v[24:25], v[10:13], off offset:128
	s_nop 1
	v_or_b32_e32 v12, 8, v28
	v_lshlrev_b32_e32 v10, 12, v12
	v_lshlrev_b32_e32 v12, 11, v12
	v_mov_b32_e32 v13, v1
	v_mov_b32_e32 v11, v1
	v_lshl_add_u64 v[12:13], v[6:7], 0, v[12:13]
	v_lshl_add_u64 v[18:19], v[8:9], 0, v[10:11]
	global_load_dwordx2 v[22:23], v[12:13], off offset:64
	v_lshl_add_u64 v[24:25], v[4:5], 0, v[10:11]
	ds_read_b128 v[10:13], v0 offset:1152
	global_load_dwordx4 v[14:17], v[2:3], off
	s_nop 0
	global_load_dwordx4 v[18:21], v[18:19], off offset:128
	s_waitcnt vmcnt(2)
	v_and_b32_e32 v27, 0xffff0000, v22
	v_lshlrev_b32_e32 v26, 16, v22
	s_waitcnt vmcnt(0)
	v_pk_add_f32 v[18:19], v[18:19], v[26:27]
	s_waitcnt lgkmcnt(0)
	v_pk_fma_f32 v[10:11], v[10:11], v[14:15], v[18:19]
	v_and_b32_e32 v15, 0xffff0000, v23
	v_lshlrev_b32_e32 v14, 16, v23
	v_pk_add_f32 v[14:15], v[20:21], v[14:15]
	s_nop 0
	v_pk_fma_f32 v[12:13], v[12:13], v[16:17], v[14:15]
	global_store_dwordx4 v[24:25], v[10:13], off offset:128
	s_nop 1
	v_or_b32_e32 v12, 16, v28
	v_lshlrev_b32_e32 v10, 12, v12
	v_lshlrev_b32_e32 v12, 11, v12
	v_mov_b32_e32 v13, v1
	v_mov_b32_e32 v11, v1
	v_lshl_add_u64 v[12:13], v[6:7], 0, v[12:13]
	v_lshl_add_u64 v[18:19], v[8:9], 0, v[10:11]
	global_load_dwordx2 v[22:23], v[12:13], off offset:64
	v_lshl_add_u64 v[24:25], v[4:5], 0, v[10:11]
	ds_read_b128 v[10:13], v0 offset:2304
	global_load_dwordx4 v[14:17], v[2:3], off
	s_nop 0
	global_load_dwordx4 v[18:21], v[18:19], off offset:128
	s_waitcnt vmcnt(2)
	v_and_b32_e32 v27, 0xffff0000, v22
	v_lshlrev_b32_e32 v26, 16, v22
	s_waitcnt vmcnt(0)
	v_pk_add_f32 v[18:19], v[18:19], v[26:27]
	s_waitcnt lgkmcnt(0)
	v_pk_fma_f32 v[10:11], v[10:11], v[14:15], v[18:19]
	v_and_b32_e32 v15, 0xffff0000, v23
	v_lshlrev_b32_e32 v14, 16, v23
	v_pk_add_f32 v[14:15], v[20:21], v[14:15]
	s_nop 0
	v_pk_fma_f32 v[12:13], v[12:13], v[16:17], v[14:15]
	v_or_b32_e32 v14, 24, v28
	global_store_dwordx4 v[24:25], v[10:13], off offset:128
	s_nop 1
	v_lshlrev_b32_e32 v10, 12, v14
	v_mov_b32_e32 v11, v1
	v_lshl_add_u64 v[12:13], v[8:9], 0, v[10:11]
	v_lshlrev_b32_e32 v8, 11, v14
	v_mov_b32_e32 v9, v1
	v_lshl_add_u64 v[6:7], v[6:7], 0, v[8:9]
	global_load_dwordx2 v[16:17], v[6:7], off offset:64
	v_lshl_add_u64 v[18:19], v[4:5], 0, v[10:11]
	ds_read_b128 v[4:7], v0 offset:3456
	global_load_dwordx4 v[8:11], v[2:3], off
	s_nop 0
	global_load_dwordx4 v[12:15], v[12:13], off offset:128
	s_waitcnt vmcnt(2)
	v_and_b32_e32 v3, 0xffff0000, v16
	v_lshlrev_b32_e32 v2, 16, v16
	s_waitcnt vmcnt(0)
	v_pk_add_f32 v[2:3], v[12:13], v[2:3]
	s_waitcnt lgkmcnt(0)
	v_pk_fma_f32 v[2:3], v[4:5], v[8:9], v[2:3]
	v_and_b32_e32 v5, 0xffff0000, v17
	v_lshlrev_b32_e32 v4, 16, v17
	v_pk_add_f32 v[4:5], v[14:15], v[4:5]
	s_nop 0
	v_pk_fma_f32 v[4:5], v[6:7], v[10:11], v[4:5]
	global_store_dwordx4 v[18:19], v[2:5], off offset:128
	s_add_i32 s7, s7, s6
	s_cmpk_gt_i32 s7, 0x1ff
	v_readlane_b32 s64, v254, 55
	v_readlane_b32 s38, v254, 57
	v_readlane_b32 s42, v254, 59
	s_cselect_b64 s[0:1], -1, 0
	v_readlane_b32 s65, v254, 56
	v_readlane_b32 s39, v254, 58
	v_readlane_b32 s43, v254, 60
	s_mov_b32 s51, s27
	s_movk_i32 s37, 0x1000
	s_movk_i32 s36, 0x1ff
	s_mov_b32 s47, 0x7f800000
	s_mov_b32 s49, 0x20000
	s_mov_b32 s46, 0x4081e0d3
	s_mov_b32 s48, 0xc09de9e6
	s_mov_b64 s[44:45], 0x800
	s_branch .LBB0_21

.LBB0_42:
	v_cmp_le_i32_e32 vcc, s66, v172
	s_lshl_b32 s4, s66, 5
	s_and_b64 s[0:1], s[36:37], vcc
	v_cmp_ge_i32_e32 vcc, s66, v172
	v_or_b32_e32 v66, s4, v145
	s_or_b64 s[40:41], s[54:55], s[0:1]
	s_and_b64 s[0:1], s[36:37], vcc
	v_mul_lo_u32 v66, v66, s28
	s_or_b64 s[42:43], s[38:39], s[0:1]
	v_add_u32_e32 v86, s4, v84
	v_lshl_add_u32 v85, s66, 6, v174
	s_or_b64 s[0:1], s[40:41], s[42:43]
	v_add_u32_e32 v102, v170, v66
	v_add_u32_e32 v101, 1, v86
	v_add_u32_e32 v100, 2, v86
	v_add_u32_e32 v99, 3, v86
	v_add_u32_e32 v98, 8, v86
	v_add_u32_e32 v97, 9, v86
	v_add_u32_e32 v96, 10, v86
	v_add_u32_e32 v95, 11, v86
	v_add_u32_e32 v94, 16, v86
	v_add_u32_e32 v93, 17, v86
	v_add_u32_e32 v92, 18, v86
	v_add_u32_e32 v91, 19, v86
	v_add_u32_e32 v90, 24, v86
	v_add_u32_e32 v89, 25, v86
	v_add_u32_e32 v88, 26, v86
	v_add_u32_e32 v87, 27, v86
	s_and_saveexec_b64 s[44:45], s[0:1]
	s_cbranch_execz .LBB0_84
	ds_read_b128 v[66:69], v102 offset:34816
	ds_read_b128 v[104:107], v102 offset:34848
	ds_read_b128 v[70:73], v188
	ds_read_b128 v[110:113], v188 offset:32
	v_cmp_le_i32_e64 s[0:1], v86, v82
	v_cmp_ge_i32_e64 s[46:47], v86, v82
	v_cmp_le_i32_e64 s[56:57], v101, v82
	s_waitcnt lgkmcnt(1)
	v_mfma_f32_32x32x16_bf16 v[66:81], v[66:69], v[70:73], 0
	v_cmp_ge_i32_e64 s[58:59], v101, v82
	v_cmp_le_i32_e64 s[60:61], v100, v82
	v_cmp_ge_i32_e64 s[62:63], v100, v82
	v_cmp_le_i32_e64 s[64:65], v99, v82
	v_cmp_ge_i32_e64 s[68:69], v99, v82
	v_cmp_le_i32_e64 s[70:71], v98, v82
	v_cmp_ge_i32_e64 s[72:73], v98, v82
	s_waitcnt lgkmcnt(0)
	v_mfma_f32_32x32x16_bf16 v[66:81], v[104:107], v[110:113], v[66:81]
	ds_read_b128 v[104:107], v102 offset:34880
	ds_read_b128 v[110:113], v188 offset:64
	v_cmp_le_i32_e64 s[74:75], v97, v82
	v_cmp_ge_i32_e64 s[76:77], v97, v82
	v_cmp_le_i32_e64 s[78:79], v96, v82
	v_cmp_ge_i32_e64 s[80:81], v96, v82
	v_cmp_le_i32_e64 s[82:83], v95, v82
	v_cmp_ge_i32_e64 s[84:85], v95, v82
	s_waitcnt lgkmcnt(0)
	v_mfma_f32_32x32x16_bf16 v[66:81], v[104:107], v[110:113], v[66:81]
	ds_read_b128 v[104:107], v102 offset:34912
	ds_read_b128 v[110:113], v188 offset:96
	v_cmp_le_i32_e64 s[86:87], v94, v82
	v_cmp_ge_i32_e64 s[88:89], v94, v82
	v_cmp_le_i32_e64 s[90:91], v93, v82
	v_cmp_ge_i32_e64 s[92:93], v93, v82
	v_cmp_le_i32_e64 s[94:95], v92, v82
	v_cmp_ge_i32_e64 s[96:97], v92, v82
	s_waitcnt lgkmcnt(0)
	v_mfma_f32_32x32x16_bf16 v[66:81], v[104:107], v[110:113], v[66:81]
	ds_read_b128 v[104:107], v102 offset:34944
	ds_read_b128 v[110:113], v188 offset:128
	v_cmp_le_i32_e64 s[4:5], v91, v82
	v_cmp_ge_i32_e64 s[6:7], v91, v82
	v_cmp_le_i32_e64 s[8:9], v90, v82
	v_cmp_ge_i32_e64 s[10:11], v90, v82
	v_cmp_le_i32_e64 s[12:13], v89, v82
	v_cmp_ge_i32_e64 s[14:15], v89, v82
	s_waitcnt lgkmcnt(0)
	v_mfma_f32_32x32x16_bf16 v[66:81], v[104:107], v[110:113], v[66:81]
	ds_read_b128 v[104:107], v102 offset:34976
	ds_read_b128 v[110:113], v188 offset:160
	v_cmp_le_i32_e64 s[16:17], v88, v82
	v_cmp_ge_i32_e64 s[18:19], v88, v82
	v_cmp_le_i32_e64 s[20:21], v87, v82
	v_cmp_ge_i32_e64 s[22:23], v87, v82
	s_mov_b32 s30, 0
	s_mov_b64 s[24:25], -1
	s_waitcnt lgkmcnt(0)
	v_mfma_f32_32x32x16_bf16 v[66:81], v[104:107], v[110:113], v[66:81]
	ds_read_b128 v[104:107], v102 offset:35008
	ds_read_b128 v[110:113], v188 offset:192
	s_waitcnt lgkmcnt(0)
	v_mfma_f32_32x32x16_bf16 v[66:81], v[104:107], v[110:113], v[66:81]
	ds_read_b128 v[104:107], v102 offset:35040
	ds_read_b128 v[110:113], v188 offset:224
	s_waitcnt lgkmcnt(0)
	v_mfma_f32_32x32x16_bf16 v[66:81], v[104:107], v[110:113], v[66:81]
	v_lshlrev_b32_e32 v127, 2, v173
	v_lshl_add_u32 v103, v86, 2, v127
	v_lshl_add_u32 v109, v82, 2, v127
	v_add_u32_e32 v103, s33, v103
	v_add_u32_e32 v109, s33, v109
	v_add_u32_e32 v126, v85, v181
	v_add_u32_e32 v127, 0x2000, v126
	s_and_b64 vcc, exec, s[40:41]
	s_cbranch_vccz .Ls3a_d1
	ds_read_b32 v239, v109 offset:0
	ds_read_b128 v[104:107], v103 offset:0
	ds_read_b128 v[110:113], v103 offset:32
	ds_read_b128 v[114:117], v103 offset:64
	ds_read_b128 v[118:121], v103 offset:96
	ds_read_b128 v[122:125], v103 offset:8192
	ds_read_b128 v[230:233], v103 offset:8224
	ds_read_b128 v[240:243], v103 offset:8256
	ds_read_b128 v[244:247], v103 offset:8288
	s_waitcnt lgkmcnt(4)
	v_sub_f32_e32 v104, v239, v104
	v_sub_f32_e32 v105, v239, v105
	v_sub_f32_e32 v106, v239, v106
	v_sub_f32_e32 v107, v239, v107
	v_sub_f32_e32 v110, v239, v110
	v_sub_f32_e32 v111, v239, v111
	v_sub_f32_e32 v112, v239, v112
	v_sub_f32_e32 v113, v239, v113
	v_sub_f32_e32 v114, v239, v114
	v_sub_f32_e32 v115, v239, v115
	v_sub_f32_e32 v116, v239, v116
	v_sub_f32_e32 v117, v239, v117
	v_sub_f32_e32 v118, v239, v118
	v_sub_f32_e32 v119, v239, v119
	v_sub_f32_e32 v120, v239, v120
	v_sub_f32_e32 v121, v239, v121
	v_min_f32_e32 v104, 0, v104
	v_min_f32_e32 v105, 0, v105
	v_min_f32_e32 v106, 0, v106
	v_min_f32_e32 v107, 0, v107
	v_min_f32_e32 v110, 0, v110
	v_min_f32_e32 v111, 0, v111
	v_min_f32_e32 v112, 0, v112
	v_min_f32_e32 v113, 0, v113
	v_min_f32_e32 v114, 0, v114
	v_min_f32_e32 v115, 0, v115
	v_min_f32_e32 v116, 0, v116
	v_min_f32_e32 v117, 0, v117
	v_min_f32_e32 v118, 0, v118
	v_min_f32_e32 v119, 0, v119
	v_min_f32_e32 v120, 0, v120
	v_min_f32_e32 v121, 0, v121
	v_mul_f32_e32 v104, 0x3fb8aa3b, v104
	v_mul_f32_e32 v105, 0x3fb8aa3b, v105
	v_mul_f32_e32 v106, 0x3fb8aa3b, v106
	v_mul_f32_e32 v107, 0x3fb8aa3b, v107
	v_mul_f32_e32 v110, 0x3fb8aa3b, v110
	v_mul_f32_e32 v111, 0x3fb8aa3b, v111
	v_mul_f32_e32 v112, 0x3fb8aa3b, v112
	v_mul_f32_e32 v113, 0x3fb8aa3b, v113
	v_mul_f32_e32 v114, 0x3fb8aa3b, v114
	v_mul_f32_e32 v115, 0x3fb8aa3b, v115
	v_mul_f32_e32 v116, 0x3fb8aa3b, v116
	v_mul_f32_e32 v117, 0x3fb8aa3b, v117
	v_mul_f32_e32 v118, 0x3fb8aa3b, v118
	v_mul_f32_e32 v119, 0x3fb8aa3b, v119
	v_mul_f32_e32 v120, 0x3fb8aa3b, v120
	v_mul_f32_e32 v121, 0x3fb8aa3b, v121
	v_exp_f32_e32 v104, v104
	v_exp_f32_e32 v105, v105
	v_exp_f32_e32 v106, v106
	v_exp_f32_e32 v107, v107
	v_exp_f32_e32 v110, v110
	v_exp_f32_e32 v111, v111
	v_exp_f32_e32 v112, v112
	v_exp_f32_e32 v113, v113
	v_exp_f32_e32 v114, v114
	v_exp_f32_e32 v115, v115
	v_exp_f32_e32 v116, v116
	v_exp_f32_e32 v117, v117
	v_exp_f32_e32 v118, v118
	v_exp_f32_e32 v119, v119
	v_exp_f32_e32 v120, v120
	v_exp_f32_e32 v121, v121
	s_waitcnt lgkmcnt(0)
	v_mul_f32_e32 v104, v66, v104
	v_mul_f32_e32 v105, v67, v105
	v_mul_f32_e32 v106, v68, v106
	v_mul_f32_e32 v107, v69, v107
	v_mul_f32_e32 v110, v70, v110
	v_mul_f32_e32 v111, v71, v111
	v_mul_f32_e32 v112, v72, v112
	v_mul_f32_e32 v113, v73, v113
	v_mul_f32_e32 v114, v74, v114
	v_mul_f32_e32 v115, v75, v115
	v_mul_f32_e32 v116, v76, v116
	v_mul_f32_e32 v117, v77, v117
	v_mul_f32_e32 v118, v78, v118
	v_mul_f32_e32 v119, v79, v119
	v_mul_f32_e32 v120, v80, v120
	v_mul_f32_e32 v121, v81, v121
	v_mul_f32_e32 v104, v122, v104
	v_mul_f32_e32 v105, v123, v105
	v_mul_f32_e32 v106, v124, v106
	v_mul_f32_e32 v107, v125, v107
	v_mul_f32_e32 v110, v230, v110
	v_mul_f32_e32 v111, v231, v111
	v_mul_f32_e32 v112, v232, v112
	v_mul_f32_e32 v113, v233, v113
	v_mul_f32_e32 v114, v240, v114
	v_mul_f32_e32 v115, v241, v115
	v_mul_f32_e32 v116, v242, v116
	v_mul_f32_e32 v117, v243, v117
	v_mul_f32_e32 v118, v244, v118
	v_mul_f32_e32 v119, v245, v119
	v_mul_f32_e32 v120, v246, v120
	v_mul_f32_e32 v121, v247, v121
	v_cndmask_b32_e64 v104, 0, v104, s[0:1]
	v_cndmask_b32_e64 v105, 0, v105, s[56:57]
	v_cndmask_b32_e64 v106, 0, v106, s[60:61]
	v_cndmask_b32_e64 v107, 0, v107, s[64:65]
	v_cndmask_b32_e64 v110, 0, v110, s[70:71]
	v_cndmask_b32_e64 v111, 0, v111, s[74:75]
	v_cndmask_b32_e64 v112, 0, v112, s[78:79]
	v_cndmask_b32_e64 v113, 0, v113, s[82:83]
	v_cndmask_b32_e64 v114, 0, v114, s[86:87]
	v_cndmask_b32_e64 v115, 0, v115, s[90:91]
	v_cndmask_b32_e64 v116, 0, v116, s[94:95]
	v_cndmask_b32_e64 v117, 0, v117, s[4:5]
	v_cndmask_b32_e64 v118, 0, v118, s[8:9]
	v_cndmask_b32_e64 v119, 0, v119, s[12:13]
	v_cndmask_b32_e64 v120, 0, v120, s[16:17]
	v_cndmask_b32_e64 v121, 0, v121, s[20:21]
	ds_read2_b64 v[122:125], v126 offset1:2
	ds_read2_b64 v[230:233], v127 offset0:64 offset1:66
	v_cvt_pk_bf16_f32 v104, v104, v105
	v_cvt_pk_bf16_f32 v105, v106, v107
	v_cvt_pk_bf16_f32 v106, v110, v111
	v_cvt_pk_bf16_f32 v107, v112, v113
	v_cvt_pk_bf16_f32 v114, v114, v115
	v_cvt_pk_bf16_f32 v115, v116, v117
	v_cvt_pk_bf16_f32 v116, v118, v119
	v_cvt_pk_bf16_f32 v117, v120, v121
	ds_read2_b64 v[118:121], v126 offset0:4 offset1:6
	ds_read2_b64 v[110:113], v127 offset0:68 offset1:70
	s_waitcnt lgkmcnt(2)
	v_mfma_f32_32x32x16_bf16 v[50:65], v[122:125], v[104:107], v[50:65]
	v_mfma_f32_32x32x16_bf16 v[34:49], v[230:233], v[104:107], v[34:49]
	s_waitcnt lgkmcnt(0)
	v_mfma_f32_32x32x16_bf16 v[50:65], v[118:121], v[114:117], v[50:65]
	v_mfma_f32_32x32x16_bf16 v[34:49], v[110:113], v[114:117], v[34:49]
.Ls3a_d1:
	s_and_b64 vcc, exec, s[42:43]
	s_cbranch_vccz .Ls3a_done
	ds_read_b32 v239, v109 offset:4096
	ds_read_b128 v[104:107], v103 offset:4096
	ds_read_b128 v[110:113], v103 offset:4128
	ds_read_b128 v[114:117], v103 offset:4160
	ds_read_b128 v[118:121], v103 offset:4192
	ds_read_b128 v[122:125], v103 offset:12288
	ds_read_b128 v[230:233], v103 offset:12320
	ds_read_b128 v[240:243], v103 offset:12352
	ds_read_b128 v[244:247], v103 offset:12384
	s_waitcnt lgkmcnt(4)
	v_sub_f32_e32 v104, v239, v104
	v_sub_f32_e32 v105, v239, v105
	v_sub_f32_e32 v106, v239, v106
	v_sub_f32_e32 v107, v239, v107
	v_sub_f32_e32 v110, v239, v110
	v_sub_f32_e32 v111, v239, v111
	v_sub_f32_e32 v112, v239, v112
	v_sub_f32_e32 v113, v239, v113
	v_sub_f32_e32 v114, v239, v114
	v_sub_f32_e32 v115, v239, v115
	v_sub_f32_e32 v116, v239, v116
	v_sub_f32_e32 v117, v239, v117
	v_sub_f32_e32 v118, v239, v118
	v_sub_f32_e32 v119, v239, v119
	v_sub_f32_e32 v120, v239, v120
	v_sub_f32_e32 v121, v239, v121
	v_min_f32_e32 v104, 0, v104
	v_min_f32_e32 v105, 0, v105
	v_min_f32_e32 v106, 0, v106
	v_min_f32_e32 v107, 0, v107
	v_min_f32_e32 v110, 0, v110
	v_min_f32_e32 v111, 0, v111
	v_min_f32_e32 v112, 0, v112
	v_min_f32_e32 v113, 0, v113
	v_min_f32_e32 v114, 0, v114
	v_min_f32_e32 v115, 0, v115
	v_min_f32_e32 v116, 0, v116
	v_min_f32_e32 v117, 0, v117
	v_min_f32_e32 v118, 0, v118
	v_min_f32_e32 v119, 0, v119
	v_min_f32_e32 v120, 0, v120
	v_min_f32_e32 v121, 0, v121
	v_mul_f32_e32 v104, 0x3fb8aa3b, v104
	v_mul_f32_e32 v105, 0x3fb8aa3b, v105
	v_mul_f32_e32 v106, 0x3fb8aa3b, v106
	v_mul_f32_e32 v107, 0x3fb8aa3b, v107
	v_mul_f32_e32 v110, 0x3fb8aa3b, v110
	v_mul_f32_e32 v111, 0x3fb8aa3b, v111
	v_mul_f32_e32 v112, 0x3fb8aa3b, v112
	v_mul_f32_e32 v113, 0x3fb8aa3b, v113
	v_mul_f32_e32 v114, 0x3fb8aa3b, v114
	v_mul_f32_e32 v115, 0x3fb8aa3b, v115
	v_mul_f32_e32 v116, 0x3fb8aa3b, v116
	v_mul_f32_e32 v117, 0x3fb8aa3b, v117
	v_mul_f32_e32 v118, 0x3fb8aa3b, v118
	v_mul_f32_e32 v119, 0x3fb8aa3b, v119
	v_mul_f32_e32 v120, 0x3fb8aa3b, v120
	v_mul_f32_e32 v121, 0x3fb8aa3b, v121
	v_exp_f32_e32 v104, v104
	v_exp_f32_e32 v105, v105
	v_exp_f32_e32 v106, v106
	v_exp_f32_e32 v107, v107
	v_exp_f32_e32 v110, v110
	v_exp_f32_e32 v111, v111
	v_exp_f32_e32 v112, v112
	v_exp_f32_e32 v113, v113
	v_exp_f32_e32 v114, v114
	v_exp_f32_e32 v115, v115
	v_exp_f32_e32 v116, v116
	v_exp_f32_e32 v117, v117
	v_exp_f32_e32 v118, v118
	v_exp_f32_e32 v119, v119
	v_exp_f32_e32 v120, v120
	v_exp_f32_e32 v121, v121
	s_waitcnt lgkmcnt(0)
	v_mul_f32_e32 v104, v66, v104
	v_mul_f32_e32 v105, v67, v105
	v_mul_f32_e32 v106, v68, v106
	v_mul_f32_e32 v107, v69, v107
	v_mul_f32_e32 v110, v70, v110
	v_mul_f32_e32 v111, v71, v111
	v_mul_f32_e32 v112, v72, v112
	v_mul_f32_e32 v113, v73, v113
	v_mul_f32_e32 v114, v74, v114
	v_mul_f32_e32 v115, v75, v115
	v_mul_f32_e32 v116, v76, v116
	v_mul_f32_e32 v117, v77, v117
	v_mul_f32_e32 v118, v78, v118
	v_mul_f32_e32 v119, v79, v119
	v_mul_f32_e32 v120, v80, v120
	v_mul_f32_e32 v121, v81, v121
	v_mul_f32_e32 v104, v122, v104
	v_mul_f32_e32 v105, v123, v105
	v_mul_f32_e32 v106, v124, v106
	v_mul_f32_e32 v107, v125, v107
	v_mul_f32_e32 v110, v230, v110
	v_mul_f32_e32 v111, v231, v111
	v_mul_f32_e32 v112, v232, v112
	v_mul_f32_e32 v113, v233, v113
	v_mul_f32_e32 v114, v240, v114
	v_mul_f32_e32 v115, v241, v115
	v_mul_f32_e32 v116, v242, v116
	v_mul_f32_e32 v117, v243, v117
	v_mul_f32_e32 v118, v244, v118
	v_mul_f32_e32 v119, v245, v119
	v_mul_f32_e32 v120, v246, v120
	v_mul_f32_e32 v121, v247, v121
	v_cndmask_b32_e64 v104, 0, v104, s[46:47]
	v_cndmask_b32_e64 v105, 0, v105, s[58:59]
	v_cndmask_b32_e64 v106, 0, v106, s[62:63]
	v_cndmask_b32_e64 v107, 0, v107, s[68:69]
	v_cndmask_b32_e64 v110, 0, v110, s[72:73]
	v_cndmask_b32_e64 v111, 0, v111, s[76:77]
	v_cndmask_b32_e64 v112, 0, v112, s[80:81]
	v_cndmask_b32_e64 v113, 0, v113, s[84:85]
	v_cndmask_b32_e64 v114, 0, v114, s[88:89]
	v_cndmask_b32_e64 v115, 0, v115, s[92:93]
	v_cndmask_b32_e64 v116, 0, v116, s[96:97]
	v_cndmask_b32_e64 v117, 0, v117, s[6:7]
	v_cndmask_b32_e64 v118, 0, v118, s[10:11]
	v_cndmask_b32_e64 v119, 0, v119, s[14:15]
	v_cndmask_b32_e64 v120, 0, v120, s[18:19]
	v_cndmask_b32_e64 v121, 0, v121, s[22:23]
	ds_read2_b64 v[122:125], v126 offset1:2
	ds_read2_b64 v[230:233], v127 offset0:64 offset1:66
	v_cvt_pk_bf16_f32 v104, v104, v105
	v_cvt_pk_bf16_f32 v105, v106, v107
	v_cvt_pk_bf16_f32 v106, v110, v111
	v_cvt_pk_bf16_f32 v107, v112, v113
	v_cvt_pk_bf16_f32 v114, v114, v115
	v_cvt_pk_bf16_f32 v115, v116, v117
	v_cvt_pk_bf16_f32 v116, v118, v119
	v_cvt_pk_bf16_f32 v117, v120, v121
	ds_read2_b64 v[118:121], v126 offset0:4 offset1:6
	ds_read2_b64 v[110:113], v127 offset0:68 offset1:70
	s_waitcnt lgkmcnt(2)
	v_mfma_f32_32x32x16_bf16 v[50:65], v[122:125], v[104:107], v[50:65]
	v_mfma_f32_32x32x16_bf16 v[34:49], v[230:233], v[104:107], v[34:49]
	s_waitcnt lgkmcnt(0)
	v_mfma_f32_32x32x16_bf16 v[50:65], v[118:121], v[114:117], v[50:65]
	v_mfma_f32_32x32x16_bf16 v[34:49], v[110:113], v[114:117], v[34:49]
.Ls3a_done:
.LBB0_83:
	v_readlane_b32 s84, v254, 61
	v_readlane_b32 s86, v254, 63
	v_readlane_b32 s85, v254, 62
	v_readlane_b32 s87, v255, 0
	s_mov_b64 s[88:89], 0x4000
	s_mov_b32 s90, 0x3e75aa41
	s_mov_b32 s92, 0x40490fdb
	s_mov_b32 s94, 0x3d4be544
	s_mov_b32 s96, 0x3ec3ef15
	s_mov_b32 s62, 0x3f6c835e
	s_mov_b32 s80, 0x40234736
	s_mov_b32 s82, 0xc0a55e0e
	s_mov_b32 s60, 0xbfaad1da
	s_mov_b32 s46, 0x4081e0d3
	s_mov_b32 s48, 0xc09de9e6
.LBB0_84:
	s_or_b64 exec, exec, s[44:45]
	v_cmp_le_i32_e32 vcc, s66, v182
	s_and_b64 s[0:1], s[36:37], vcc
	v_cmp_gt_i32_e32 vcc, s66, v172
	s_or_b64 s[40:41], s[54:55], s[0:1]
	s_and_b64 s[0:1], s[36:37], vcc
	s_or_b64 s[44:45], s[38:39], s[0:1]
	s_or_b64 s[0:1], s[40:41], s[44:45]
	s_and_saveexec_b64 s[42:43], s[0:1]
	s_cbranch_execz .LBB0_41
	ds_read_b128 v[66:69], v102 offset:34816
	ds_read_b128 v[104:107], v102 offset:34848
	ds_read_b128 v[70:73], v187
	ds_read_b128 v[110:113], v187 offset:32
	v_cmp_le_i32_e64 s[0:1], v86, v83
	v_cmp_ge_i32_e64 s[46:47], v86, v83
	v_cmp_le_i32_e64 s[56:57], v101, v83
	s_waitcnt lgkmcnt(1)
	v_mfma_f32_32x32x16_bf16 v[66:81], v[66:69], v[70:73], 0
	v_cmp_ge_i32_e64 s[58:59], v101, v83
	v_cmp_le_i32_e64 s[60:61], v100, v83
	v_cmp_ge_i32_e64 s[62:63], v100, v83
	v_cmp_le_i32_e64 s[64:65], v99, v83
	v_cmp_ge_i32_e64 s[68:69], v99, v83
	v_cmp_le_i32_e64 s[70:71], v98, v83
	v_cmp_ge_i32_e64 s[72:73], v98, v83
	s_waitcnt lgkmcnt(0)
	v_mfma_f32_32x32x16_bf16 v[66:81], v[104:107], v[110:113], v[66:81]
	ds_read_b128 v[104:107], v102 offset:34880
	ds_read_b128 v[110:113], v187 offset:64
	v_cmp_le_i32_e64 s[74:75], v97, v83
	v_cmp_ge_i32_e64 s[76:77], v97, v83
	v_cmp_le_i32_e64 s[78:79], v96, v83
	v_cmp_ge_i32_e64 s[80:81], v96, v83
	v_cmp_le_i32_e64 s[82:83], v95, v83
	v_cmp_ge_i32_e64 s[84:85], v95, v83
	s_waitcnt lgkmcnt(0)
	v_mfma_f32_32x32x16_bf16 v[66:81], v[104:107], v[110:113], v[66:81]
	ds_read_b128 v[104:107], v102 offset:34912
	ds_read_b128 v[110:113], v187 offset:96
	v_cmp_le_i32_e64 s[86:87], v94, v83
	v_cmp_ge_i32_e64 s[88:89], v94, v83
	v_cmp_le_i32_e64 s[90:91], v93, v83
	v_cmp_ge_i32_e64 s[92:93], v93, v83
	v_cmp_le_i32_e64 s[4:5], v92, v83
	v_cmp_ge_i32_e64 s[6:7], v92, v83
	s_waitcnt lgkmcnt(0)
	v_mfma_f32_32x32x16_bf16 v[66:81], v[104:107], v[110:113], v[66:81]
	ds_read_b128 v[104:107], v102 offset:34944
	ds_read_b128 v[110:113], v187 offset:128
	v_cmp_le_i32_e64 s[8:9], v91, v83
	v_cmp_ge_i32_e64 s[10:11], v91, v83
	v_cmp_le_i32_e64 s[94:95], v90, v83
	v_cmp_ge_i32_e64 s[96:97], v90, v83
	v_cmp_le_i32_e64 s[12:13], v89, v83
	v_cmp_ge_i32_e64 s[14:15], v89, v83
	s_waitcnt lgkmcnt(0)
	v_mfma_f32_32x32x16_bf16 v[66:81], v[104:107], v[110:113], v[66:81]
	ds_read_b128 v[104:107], v102 offset:34976
	ds_read_b128 v[110:113], v187 offset:160
	v_cmp_le_i32_e64 s[16:17], v88, v83
	v_cmp_ge_i32_e64 s[18:19], v88, v83
	v_cmp_le_i32_e64 s[20:21], v87, v83
	v_cmp_ge_i32_e64 s[22:23], v87, v83
	s_mov_b32 s30, 0
	s_mov_b64 s[48:49], -1
	s_waitcnt lgkmcnt(0)
	v_mfma_f32_32x32x16_bf16 v[66:81], v[104:107], v[110:113], v[66:81]
	ds_read_b128 v[104:107], v102 offset:35008
	ds_read_b128 v[110:113], v187 offset:192
	s_waitcnt lgkmcnt(0)
	v_mfma_f32_32x32x16_bf16 v[66:81], v[104:107], v[110:113], v[66:81]
	ds_read_b128 v[102:105], v102 offset:35040
	ds_read_b128 v[110:113], v187 offset:224
	s_waitcnt lgkmcnt(0)
	v_mfma_f32_32x32x16_bf16 v[66:81], v[102:105], v[110:113], v[66:81]
	v_lshlrev_b32_e32 v127, 2, v173
	v_lshl_add_u32 v103, v86, 2, v127
	v_lshl_add_u32 v109, v83, 2, v127
	v_add_u32_e32 v103, s33, v103
	v_add_u32_e32 v109, s33, v109
	v_add_u32_e32 v126, v85, v181
	v_add_u32_e32 v127, 0x2000, v126
	s_and_b64 vcc, exec, s[40:41]
	s_cbranch_vccz .Ls3b_d1
	ds_read_b32 v239, v109 offset:0
	ds_read_b128 v[104:107], v103 offset:0
	ds_read_b128 v[110:113], v103 offset:32
	ds_read_b128 v[114:117], v103 offset:64
	ds_read_b128 v[118:121], v103 offset:96
	ds_read_b128 v[122:125], v103 offset:8192
	ds_read_b128 v[230:233], v103 offset:8224
	ds_read_b128 v[240:243], v103 offset:8256
	ds_read_b128 v[244:247], v103 offset:8288
	s_waitcnt lgkmcnt(4)
	v_sub_f32_e32 v104, v239, v104
	v_sub_f32_e32 v105, v239, v105
	v_sub_f32_e32 v106, v239, v106
	v_sub_f32_e32 v107, v239, v107
	v_sub_f32_e32 v110, v239, v110
	v_sub_f32_e32 v111, v239, v111
	v_sub_f32_e32 v112, v239, v112
	v_sub_f32_e32 v113, v239, v113
	v_sub_f32_e32 v114, v239, v114
	v_sub_f32_e32 v115, v239, v115
	v_sub_f32_e32 v116, v239, v116
	v_sub_f32_e32 v117, v239, v117
	v_sub_f32_e32 v118, v239, v118
	v_sub_f32_e32 v119, v239, v119
	v_sub_f32_e32 v120, v239, v120
	v_sub_f32_e32 v121, v239, v121
	v_min_f32_e32 v104, 0, v104
	v_min_f32_e32 v105, 0, v105
	v_min_f32_e32 v106, 0, v106
	v_min_f32_e32 v107, 0, v107
	v_min_f32_e32 v110, 0, v110
	v_min_f32_e32 v111, 0, v111
	v_min_f32_e32 v112, 0, v112
	v_min_f32_e32 v113, 0, v113
	v_min_f32_e32 v114, 0, v114
	v_min_f32_e32 v115, 0, v115
	v_min_f32_e32 v116, 0, v116
	v_min_f32_e32 v117, 0, v117
	v_min_f32_e32 v118, 0, v118
	v_min_f32_e32 v119, 0, v119
	v_min_f32_e32 v120, 0, v120
	v_min_f32_e32 v121, 0, v121
	v_mul_f32_e32 v104, 0x3fb8aa3b, v104
	v_mul_f32_e32 v105, 0x3fb8aa3b, v105
	v_mul_f32_e32 v106, 0x3fb8aa3b, v106
	v_mul_f32_e32 v107, 0x3fb8aa3b, v107
	v_mul_f32_e32 v110, 0x3fb8aa3b, v110
	v_mul_f32_e32 v111, 0x3fb8aa3b, v111
	v_mul_f32_e32 v112, 0x3fb8aa3b, v112
	v_mul_f32_e32 v113, 0x3fb8aa3b, v113
	v_mul_f32_e32 v114, 0x3fb8aa3b, v114
	v_mul_f32_e32 v115, 0x3fb8aa3b, v115
	v_mul_f32_e32 v116, 0x3fb8aa3b, v116
	v_mul_f32_e32 v117, 0x3fb8aa3b, v117
	v_mul_f32_e32 v118, 0x3fb8aa3b, v118
	v_mul_f32_e32 v119, 0x3fb8aa3b, v119
	v_mul_f32_e32 v120, 0x3fb8aa3b, v120
	v_mul_f32_e32 v121, 0x3fb8aa3b, v121
	v_exp_f32_e32 v104, v104
	v_exp_f32_e32 v105, v105
	v_exp_f32_e32 v106, v106
	v_exp_f32_e32 v107, v107
	v_exp_f32_e32 v110, v110
	v_exp_f32_e32 v111, v111
	v_exp_f32_e32 v112, v112
	v_exp_f32_e32 v113, v113
	v_exp_f32_e32 v114, v114
	v_exp_f32_e32 v115, v115
	v_exp_f32_e32 v116, v116
	v_exp_f32_e32 v117, v117
	v_exp_f32_e32 v118, v118
	v_exp_f32_e32 v119, v119
	v_exp_f32_e32 v120, v120
	v_exp_f32_e32 v121, v121
	s_waitcnt lgkmcnt(0)
	v_mul_f32_e32 v104, v66, v104
	v_mul_f32_e32 v105, v67, v105
	v_mul_f32_e32 v106, v68, v106
	v_mul_f32_e32 v107, v69, v107
	v_mul_f32_e32 v110, v70, v110
	v_mul_f32_e32 v111, v71, v111
	v_mul_f32_e32 v112, v72, v112
	v_mul_f32_e32 v113, v73, v113
	v_mul_f32_e32 v114, v74, v114
	v_mul_f32_e32 v115, v75, v115
	v_mul_f32_e32 v116, v76, v116
	v_mul_f32_e32 v117, v77, v117
	v_mul_f32_e32 v118, v78, v118
	v_mul_f32_e32 v119, v79, v119
	v_mul_f32_e32 v120, v80, v120
	v_mul_f32_e32 v121, v81, v121
	v_mul_f32_e32 v104, v122, v104
	v_mul_f32_e32 v105, v123, v105
	v_mul_f32_e32 v106, v124, v106
	v_mul_f32_e32 v107, v125, v107
	v_mul_f32_e32 v110, v230, v110
	v_mul_f32_e32 v111, v231, v111
	v_mul_f32_e32 v112, v232, v112
	v_mul_f32_e32 v113, v233, v113
	v_mul_f32_e32 v114, v240, v114
	v_mul_f32_e32 v115, v241, v115
	v_mul_f32_e32 v116, v242, v116
	v_mul_f32_e32 v117, v243, v117
	v_mul_f32_e32 v118, v244, v118
	v_mul_f32_e32 v119, v245, v119
	v_mul_f32_e32 v120, v246, v120
	v_mul_f32_e32 v121, v247, v121
	v_cndmask_b32_e64 v104, 0, v104, s[0:1]
	v_cndmask_b32_e64 v105, 0, v105, s[56:57]
	v_cndmask_b32_e64 v106, 0, v106, s[60:61]
	v_cndmask_b32_e64 v107, 0, v107, s[64:65]
	v_cndmask_b32_e64 v110, 0, v110, s[70:71]
	v_cndmask_b32_e64 v111, 0, v111, s[74:75]
	v_cndmask_b32_e64 v112, 0, v112, s[78:79]
	v_cndmask_b32_e64 v113, 0, v113, s[82:83]
	v_cndmask_b32_e64 v114, 0, v114, s[86:87]
	v_cndmask_b32_e64 v115, 0, v115, s[90:91]
	v_cndmask_b32_e64 v116, 0, v116, s[4:5]
	v_cndmask_b32_e64 v117, 0, v117, s[8:9]
	v_cndmask_b32_e64 v118, 0, v118, s[94:95]
	v_cndmask_b32_e64 v119, 0, v119, s[12:13]
	v_cndmask_b32_e64 v120, 0, v120, s[16:17]
	v_cndmask_b32_e64 v121, 0, v121, s[20:21]
	ds_read2_b64 v[122:125], v126 offset1:2
	ds_read2_b64 v[230:233], v127 offset0:64 offset1:66
	v_cvt_pk_bf16_f32 v104, v104, v105
	v_cvt_pk_bf16_f32 v105, v106, v107
	v_cvt_pk_bf16_f32 v106, v110, v111
	v_cvt_pk_bf16_f32 v107, v112, v113
	v_cvt_pk_bf16_f32 v114, v114, v115
	v_cvt_pk_bf16_f32 v115, v116, v117
	v_cvt_pk_bf16_f32 v116, v118, v119
	v_cvt_pk_bf16_f32 v117, v120, v121
	ds_read2_b64 v[118:121], v126 offset0:4 offset1:6
	ds_read2_b64 v[110:113], v127 offset0:68 offset1:70
	s_waitcnt lgkmcnt(2)
	v_mfma_f32_32x32x16_bf16 v[18:33], v[122:125], v[104:107], v[18:33]
	v_mfma_f32_32x32x16_bf16 v[2:17], v[230:233], v[104:107], v[2:17]
	s_waitcnt lgkmcnt(0)
	v_mfma_f32_32x32x16_bf16 v[18:33], v[118:121], v[114:117], v[18:33]
	v_mfma_f32_32x32x16_bf16 v[2:17], v[110:113], v[114:117], v[2:17]
.Ls3b_d1:
	s_and_b64 vcc, exec, s[44:45]
	s_cbranch_vccz .Ls3b_done
	ds_read_b32 v239, v109 offset:4096
	ds_read_b128 v[104:107], v103 offset:4096
	ds_read_b128 v[110:113], v103 offset:4128
	ds_read_b128 v[114:117], v103 offset:4160
	ds_read_b128 v[118:121], v103 offset:4192
	ds_read_b128 v[122:125], v103 offset:12288
	ds_read_b128 v[230:233], v103 offset:12320
	ds_read_b128 v[240:243], v103 offset:12352
	ds_read_b128 v[244:247], v103 offset:12384
	s_waitcnt lgkmcnt(4)
	v_sub_f32_e32 v104, v239, v104
	v_sub_f32_e32 v105, v239, v105
	v_sub_f32_e32 v106, v239, v106
	v_sub_f32_e32 v107, v239, v107
	v_sub_f32_e32 v110, v239, v110
	v_sub_f32_e32 v111, v239, v111
	v_sub_f32_e32 v112, v239, v112
	v_sub_f32_e32 v113, v239, v113
	v_sub_f32_e32 v114, v239, v114
	v_sub_f32_e32 v115, v239, v115
	v_sub_f32_e32 v116, v239, v116
	v_sub_f32_e32 v117, v239, v117
	v_sub_f32_e32 v118, v239, v118
	v_sub_f32_e32 v119, v239, v119
	v_sub_f32_e32 v120, v239, v120
	v_sub_f32_e32 v121, v239, v121
	v_min_f32_e32 v104, 0, v104
	v_min_f32_e32 v105, 0, v105
	v_min_f32_e32 v106, 0, v106
	v_min_f32_e32 v107, 0, v107
	v_min_f32_e32 v110, 0, v110
	v_min_f32_e32 v111, 0, v111
	v_min_f32_e32 v112, 0, v112
	v_min_f32_e32 v113, 0, v113
	v_min_f32_e32 v114, 0, v114
	v_min_f32_e32 v115, 0, v115
	v_min_f32_e32 v116, 0, v116
	v_min_f32_e32 v117, 0, v117
	v_min_f32_e32 v118, 0, v118
	v_min_f32_e32 v119, 0, v119
	v_min_f32_e32 v120, 0, v120
	v_min_f32_e32 v121, 0, v121
	v_mul_f32_e32 v104, 0x3fb8aa3b, v104
	v_mul_f32_e32 v105, 0x3fb8aa3b, v105
	v_mul_f32_e32 v106, 0x3fb8aa3b, v106
	v_mul_f32_e32 v107, 0x3fb8aa3b, v107
	v_mul_f32_e32 v110, 0x3fb8aa3b, v110
	v_mul_f32_e32 v111, 0x3fb8aa3b, v111
	v_mul_f32_e32 v112, 0x3fb8aa3b, v112
	v_mul_f32_e32 v113, 0x3fb8aa3b, v113
	v_mul_f32_e32 v114, 0x3fb8aa3b, v114
	v_mul_f32_e32 v115, 0x3fb8aa3b, v115
	v_mul_f32_e32 v116, 0x3fb8aa3b, v116
	v_mul_f32_e32 v117, 0x3fb8aa3b, v117
	v_mul_f32_e32 v118, 0x3fb8aa3b, v118
	v_mul_f32_e32 v119, 0x3fb8aa3b, v119
	v_mul_f32_e32 v120, 0x3fb8aa3b, v120
	v_mul_f32_e32 v121, 0x3fb8aa3b, v121
	v_exp_f32_e32 v104, v104
	v_exp_f32_e32 v105, v105
	v_exp_f32_e32 v106, v106
	v_exp_f32_e32 v107, v107
	v_exp_f32_e32 v110, v110
	v_exp_f32_e32 v111, v111
	v_exp_f32_e32 v112, v112
	v_exp_f32_e32 v113, v113
	v_exp_f32_e32 v114, v114
	v_exp_f32_e32 v115, v115
	v_exp_f32_e32 v116, v116
	v_exp_f32_e32 v117, v117
	v_exp_f32_e32 v118, v118
	v_exp_f32_e32 v119, v119
	v_exp_f32_e32 v120, v120
	v_exp_f32_e32 v121, v121
	s_waitcnt lgkmcnt(0)
	v_mul_f32_e32 v104, v66, v104
	v_mul_f32_e32 v105, v67, v105
	v_mul_f32_e32 v106, v68, v106
	v_mul_f32_e32 v107, v69, v107
	v_mul_f32_e32 v110, v70, v110
	v_mul_f32_e32 v111, v71, v111
	v_mul_f32_e32 v112, v72, v112
	v_mul_f32_e32 v113, v73, v113
	v_mul_f32_e32 v114, v74, v114
	v_mul_f32_e32 v115, v75, v115
	v_mul_f32_e32 v116, v76, v116
	v_mul_f32_e32 v117, v77, v117
	v_mul_f32_e32 v118, v78, v118
	v_mul_f32_e32 v119, v79, v119
	v_mul_f32_e32 v120, v80, v120
	v_mul_f32_e32 v121, v81, v121
	v_mul_f32_e32 v104, v122, v104
	v_mul_f32_e32 v105, v123, v105
	v_mul_f32_e32 v106, v124, v106
	v_mul_f32_e32 v107, v125, v107
	v_mul_f32_e32 v110, v230, v110
	v_mul_f32_e32 v111, v231, v111
	v_mul_f32_e32 v112, v232, v112
	v_mul_f32_e32 v113, v233, v113
	v_mul_f32_e32 v114, v240, v114
	v_mul_f32_e32 v115, v241, v115
	v_mul_f32_e32 v116, v242, v116
	v_mul_f32_e32 v117, v243, v117
	v_mul_f32_e32 v118, v244, v118
	v_mul_f32_e32 v119, v245, v119
	v_mul_f32_e32 v120, v246, v120
	v_mul_f32_e32 v121, v247, v121
	v_cndmask_b32_e64 v104, 0, v104, s[46:47]
	v_cndmask_b32_e64 v105, 0, v105, s[58:59]
	v_cndmask_b32_e64 v106, 0, v106, s[62:63]
	v_cndmask_b32_e64 v107, 0, v107, s[68:69]
	v_cndmask_b32_e64 v110, 0, v110, s[72:73]
	v_cndmask_b32_e64 v111, 0, v111, s[76:77]
	v_cndmask_b32_e64 v112, 0, v112, s[80:81]
	v_cndmask_b32_e64 v113, 0, v113, s[84:85]
	v_cndmask_b32_e64 v114, 0, v114, s[88:89]
	v_cndmask_b32_e64 v115, 0, v115, s[92:93]
	v_cndmask_b32_e64 v116, 0, v116, s[6:7]
	v_cndmask_b32_e64 v117, 0, v117, s[10:11]
	v_cndmask_b32_e64 v118, 0, v118, s[96:97]
	v_cndmask_b32_e64 v119, 0, v119, s[14:15]
	v_cndmask_b32_e64 v120, 0, v120, s[18:19]
	v_cndmask_b32_e64 v121, 0, v121, s[22:23]
	ds_read2_b64 v[122:125], v126 offset1:2
	ds_read2_b64 v[230:233], v127 offset0:64 offset1:66
	v_cvt_pk_bf16_f32 v104, v104, v105
	v_cvt_pk_bf16_f32 v105, v106, v107
	v_cvt_pk_bf16_f32 v106, v110, v111
	v_cvt_pk_bf16_f32 v107, v112, v113
	v_cvt_pk_bf16_f32 v114, v114, v115
	v_cvt_pk_bf16_f32 v115, v116, v117
	v_cvt_pk_bf16_f32 v116, v118, v119
	v_cvt_pk_bf16_f32 v117, v120, v121
	ds_read2_b64 v[118:121], v126 offset0:4 offset1:6
	ds_read2_b64 v[110:113], v127 offset0:68 offset1:70
	s_waitcnt lgkmcnt(2)
	v_mfma_f32_32x32x16_bf16 v[18:33], v[122:125], v[104:107], v[18:33]
	v_mfma_f32_32x32x16_bf16 v[2:17], v[230:233], v[104:107], v[2:17]
	s_waitcnt lgkmcnt(0)
	v_mfma_f32_32x32x16_bf16 v[18:33], v[118:121], v[114:117], v[18:33]
	v_mfma_f32_32x32x16_bf16 v[2:17], v[110:113], v[114:117], v[2:17]
.Ls3b_done:
	s_branch .LBB0_40
.LBB0_125:
	v_readlane_b32 s0, v251, 2
	v_lshlrev_b32_e32 v66, 2, v162
	v_readlane_b32 s4, v251, 6
	v_readlane_b32 s5, v251, 7
	s_barrier
	s_nop 3
	global_load_dword v67, v66, s[4:5]
	s_nop 0
	global_load_dword v66, v66, s[4:5] offset:128
	v_readlane_b32 s1, v251, 3
	v_readlane_b32 s2, v251, 4
	v_readlane_b32 s3, v251, 5
	v_readlane_b32 s0, v255, 14
	v_readlane_b32 s1, v255, 15
	v_readlane_b32 s50, v255, 16
	v_readlane_b32 s2, v255, 8
	s_lshl_b64 s[0:1], s[0:1], 14
	v_readlane_b32 s51, v255, 17
	v_readlane_b32 s38, v254, 57
	v_ashrrev_i32_e32 v83, 31, v82
	v_readlane_b32 s3, v255, 9
	s_or_b64 s[0:1], s[50:51], s[0:1]
	v_readlane_b32 s39, v254, 58
	v_readlane_b32 s64, v254, 55
	v_lshl_add_u64 v[68:69], s[2:3], 0, v[82:83]
	v_readlane_b32 s65, v254, 56
	v_lshl_add_u64 v[70:71], s[0:1], 0, v[82:83]
	v_lshlrev_b64 v[68:69], 13, v[68:69]
	v_readlane_b32 s8, v251, 10
	v_readlane_b32 s9, v251, 11
	v_readlane_b32 s8, v255, 12
	v_readlane_b32 s9, v255, 13
	v_readlane_b32 s6, v251, 8
	v_readlane_b32 s7, v251, 9
	v_readlane_b32 s10, v251, 12
	v_readlane_b32 s11, v251, 13
	v_readlane_b32 s12, v251, 14
	v_readlane_b32 s13, v251, 15
	v_readlane_b32 s14, v251, 16
	v_readlane_b32 s15, v251, 17
	s_waitcnt vmcnt(0)
	v_add_f32_e32 v72, v67, v66
	v_lshlrev_b32_e32 v66, 7, v162
	v_mov_b32_e32 v67, v1
	v_lshl_add_u64 v[74:75], s[38:39], 0, v[66:67]
	v_lshl_add_u64 v[66:67], s[64:65], 0, v[66:67]
	v_lshl_add_u64 v[76:77], v[74:75], 0, v[68:69]
	v_lshlrev_b64 v[68:69], 12, v[70:71]
	v_lshl_add_u64 v[70:71], v[66:67], 0, v[68:69]
	v_lshlrev_b32_e32 v68, 1, v150
	v_mov_b32_e32 v69, v1
	v_lshl_add_u64 v[94:95], v[76:77], 0, v[68:69]
	v_lshl_add_u64 v[88:89], v[70:71], 0, v[68:69]
	global_load_dwordx2 v[78:79], v[94:95], off
	global_load_dwordx2 v[80:81], v[88:89], off
	s_waitcnt vmcnt(1)
	v_and_b32_e32 v71, 0xffff0000, v78
	s_waitcnt vmcnt(0)
	v_lshlrev_b32_e32 v76, 16, v80
	v_mul_f32_e32 v73, 0xbfb8aa3b, v76
	v_exp_f32_e32 v73, v73
	v_lshlrev_b32_e32 v70, 16, v78
	v_and_b32_e32 v77, 0xffff0000, v80
	v_lshlrev_b32_e32 v78, 16, v81
	v_add_f32_e32 v73, 1.0, v73
	v_pk_fma_f32 v[50:51], v[72:73], v[70:71], v[50:51] op_sel_hi:[0,1,1]
	v_mul_f32_e32 v70, 0xbfb8aa3b, v77
	v_exp_f32_e32 v70, v70
	v_rcp_f32_e32 v82, v73
	v_mul_f32_e32 v73, 0xbfb8aa3b, v78
	v_exp_f32_e32 v73, v73
	v_add_f32_e32 v70, 1.0, v70
	v_rcp_f32_e32 v83, v70
	v_add_f32_e32 v73, 1.0, v73
	v_rcp_f32_e32 v80, v73
	v_pk_mul_f32 v[70:71], v[82:83], v[76:77]
	s_nop 0
	v_pk_mul_f32 v[70:71], v[50:51], v[70:71]
	v_and_b32_e32 v51, 0xffff0000, v79
	v_lshlrev_b32_e32 v50, 16, v79
	v_and_b32_e32 v79, 0xffff0000, v81
	v_pk_fma_f32 v[50:51], v[72:73], v[50:51], v[52:53] op_sel_hi:[0,1,1]
	v_mul_f32_e32 v52, 0xbfb8aa3b, v79
	v_exp_f32_e32 v52, v52
	v_pk_mul_f32 v[76:77], v[70:71], v[70:71]
	v_add_f32_e32 v52, 1.0, v52
	v_rcp_f32_e32 v81, v52
	s_nop 0
	v_pk_mul_f32 v[52:53], v[80:81], v[78:79]
	s_nop 0
	v_pk_mul_f32 v[50:51], v[50:51], v[52:53]
	global_load_dwordx2 v[52:53], v[94:95], off offset:16
	global_load_dwordx2 v[82:83], v[88:89], off offset:16
	v_pk_mul_f32 v[78:79], v[50:51], v[50:51]
	s_waitcnt vmcnt(1)
	v_and_b32_e32 v81, 0xffff0000, v52
	s_waitcnt vmcnt(0)
	v_lshlrev_b32_e32 v84, 16, v82
	v_lshlrev_b32_e32 v80, 16, v52
	v_mul_f32_e32 v52, 0xbfb8aa3b, v84
	v_exp_f32_e32 v52, v52
	v_and_b32_e32 v85, 0xffff0000, v82
	v_pk_fma_f32 v[54:55], v[72:73], v[80:81], v[54:55] op_sel_hi:[0,1,1]
	v_add_f32_e32 v52, 1.0, v52
	v_rcp_f32_e32 v86, v52
	v_mul_f32_e32 v52, 0xbfb8aa3b, v85
	v_exp_f32_e32 v52, v52
	s_nop 0
	v_add_f32_e32 v52, 1.0, v52
	v_rcp_f32_e32 v87, v52
	v_lshlrev_b32_e32 v52, 16, v83
	v_mul_f32_e32 v73, 0xbfb8aa3b, v52
	v_exp_f32_e32 v73, v73
	v_pk_mul_f32 v[80:81], v[86:87], v[84:85]
	v_and_b32_e32 v85, 0xffff0000, v53
	v_lshlrev_b32_e32 v84, 16, v53
	v_and_b32_e32 v53, 0xffff0000, v83
	v_add_f32_e32 v73, 1.0, v73
	v_rcp_f32_e32 v82, v73
	v_pk_fma_f32 v[56:57], v[72:73], v[84:85], v[56:57] op_sel_hi:[0,1,1]
	v_mul_f32_e32 v73, 0xbfb8aa3b, v53
	v_exp_f32_e32 v73, v73
	v_pk_mul_f32 v[54:55], v[54:55], v[80:81]
	v_add_f32_e32 v73, 1.0, v73
	v_rcp_f32_e32 v83, v73
	v_pk_mul_f32 v[80:81], v[54:55], v[54:55]
	v_pk_mul_f32 v[52:53], v[82:83], v[52:53]
	s_nop 0
	v_pk_mul_f32 v[52:53], v[56:57], v[52:53]
	global_load_dwordx2 v[56:57], v[94:95], off offset:32
	global_load_dwordx2 v[86:87], v[88:89], off offset:32
	v_pk_mul_f32 v[82:83], v[52:53], v[52:53]
	s_waitcnt vmcnt(1)
	v_and_b32_e32 v85, 0xffff0000, v56
	s_waitcnt vmcnt(0)
	v_lshlrev_b32_e32 v90, 16, v86
	v_lshlrev_b32_e32 v84, 16, v56
	v_mul_f32_e32 v56, 0xbfb8aa3b, v90
	v_exp_f32_e32 v56, v56
	v_and_b32_e32 v91, 0xffff0000, v86
	v_pk_fma_f32 v[58:59], v[72:73], v[84:85], v[58:59] op_sel_hi:[0,1,1]
	v_add_f32_e32 v56, 1.0, v56
	v_rcp_f32_e32 v92, v56
	v_mul_f32_e32 v56, 0xbfb8aa3b, v91
	v_exp_f32_e32 v56, v56
	s_nop 0
	v_add_f32_e32 v56, 1.0, v56
	v_rcp_f32_e32 v93, v56
	v_lshlrev_b32_e32 v56, 16, v87
	v_mul_f32_e32 v73, 0xbfb8aa3b, v56
	v_exp_f32_e32 v73, v73
	v_pk_mul_f32 v[84:85], v[92:93], v[90:91]
	v_and_b32_e32 v91, 0xffff0000, v57
	v_lshlrev_b32_e32 v90, 16, v57
	v_and_b32_e32 v57, 0xffff0000, v87
	v_add_f32_e32 v73, 1.0, v73
	v_rcp_f32_e32 v86, v73
	v_pk_fma_f32 v[60:61], v[72:73], v[90:91], v[60:61] op_sel_hi:[0,1,1]
	v_mul_f32_e32 v73, 0xbfb8aa3b, v57
	v_exp_f32_e32 v73, v73
	v_pk_mul_f32 v[58:59], v[58:59], v[84:85]
	v_add_f32_e32 v73, 1.0, v73
	v_rcp_f32_e32 v87, v73
	v_pk_mul_f32 v[84:85], v[58:59], v[58:59]
	v_pk_mul_f32 v[56:57], v[86:87], v[56:57]
	s_nop 0
	v_pk_mul_f32 v[56:57], v[60:61], v[56:57]
	global_load_dwordx2 v[60:61], v[94:95], off offset:48
	global_load_dwordx2 v[92:93], v[88:89], off offset:48
	v_pk_mul_f32 v[86:87], v[56:57], v[56:57]
	s_waitcnt vmcnt(1)
	v_and_b32_e32 v91, 0xffff0000, v60
	s_waitcnt vmcnt(0)
	v_lshlrev_b32_e32 v96, 16, v92
	v_lshlrev_b32_e32 v90, 16, v60
	v_mul_f32_e32 v60, 0xbfb8aa3b, v96
	v_exp_f32_e32 v60, v60
	v_and_b32_e32 v97, 0xffff0000, v92
	v_pk_fma_f32 v[62:63], v[72:73], v[90:91], v[62:63] op_sel_hi:[0,1,1]
	v_add_f32_e32 v60, 1.0, v60
	v_rcp_f32_e32 v98, v60
	v_mul_f32_e32 v60, 0xbfb8aa3b, v97
	v_exp_f32_e32 v60, v60
	s_nop 0
	v_add_f32_e32 v60, 1.0, v60
	v_rcp_f32_e32 v99, v60
	v_lshlrev_b32_e32 v60, 16, v93
	v_mul_f32_e32 v73, 0xbfb8aa3b, v60
	v_exp_f32_e32 v73, v73
	v_pk_mul_f32 v[90:91], v[98:99], v[96:97]
	global_load_dwordx2 v[98:99], v[94:95], off offset:64
	global_load_dwordx2 v[100:101], v[88:89], off offset:64
	v_and_b32_e32 v97, 0xffff0000, v61
	v_lshlrev_b32_e32 v96, 16, v61
	v_and_b32_e32 v61, 0xffff0000, v93
	v_add_f32_e32 v73, 1.0, v73
	v_rcp_f32_e32 v92, v73
	v_pk_fma_f32 v[64:65], v[72:73], v[96:97], v[64:65] op_sel_hi:[0,1,1]
	v_mul_f32_e32 v73, 0xbfb8aa3b, v61
	v_exp_f32_e32 v73, v73
	v_pk_mul_f32 v[62:63], v[62:63], v[90:91]
	v_add_f32_e32 v73, 1.0, v73
	v_rcp_f32_e32 v93, v73
	v_pk_mul_f32 v[90:91], v[62:63], v[62:63]
	v_pk_mul_f32 v[60:61], v[92:93], v[60:61]
	s_nop 0
	v_pk_mul_f32 v[60:61], v[64:65], v[60:61]
	s_waitcnt vmcnt(1)
	v_and_b32_e32 v65, 0xffff0000, v98
	s_waitcnt vmcnt(0)
	v_lshlrev_b32_e32 v96, 16, v100
	v_mul_f32_e32 v73, 0xbfb8aa3b, v96
	v_exp_f32_e32 v73, v73
	v_lshlrev_b32_e32 v64, 16, v98
	v_and_b32_e32 v97, 0xffff0000, v100
	v_lshlrev_b32_e32 v98, 16, v101
	v_add_f32_e32 v73, 1.0, v73
	v_pk_fma_f32 v[34:35], v[72:73], v[64:65], v[34:35] op_sel_hi:[0,1,1]
	v_mul_f32_e32 v64, 0xbfb8aa3b, v97
	v_exp_f32_e32 v64, v64
	v_rcp_f32_e32 v102, v73
	v_mul_f32_e32 v73, 0xbfb8aa3b, v98
	v_exp_f32_e32 v73, v73
	v_add_f32_e32 v64, 1.0, v64
	v_rcp_f32_e32 v103, v64
	v_pk_mul_f32 v[92:93], v[60:61], v[60:61]
	v_add_f32_e32 v73, 1.0, v73
	v_rcp_f32_e32 v100, v73
	v_pk_mul_f32 v[64:65], v[102:103], v[96:97]
	s_nop 0
	v_pk_mul_f32 v[64:65], v[34:35], v[64:65]
	v_and_b32_e32 v35, 0xffff0000, v99
	v_lshlrev_b32_e32 v34, 16, v99
	v_and_b32_e32 v99, 0xffff0000, v101
	v_pk_fma_f32 v[34:35], v[72:73], v[34:35], v[36:37] op_sel_hi:[0,1,1]
	v_mul_f32_e32 v36, 0xbfb8aa3b, v99
	v_exp_f32_e32 v36, v36
	v_pk_mul_f32 v[96:97], v[64:65], v[64:65]
	v_add_f32_e32 v36, 1.0, v36
	v_rcp_f32_e32 v101, v36
	s_nop 0
	v_pk_mul_f32 v[36:37], v[100:101], v[98:99]
	s_nop 0
	v_pk_mul_f32 v[34:35], v[34:35], v[36:37]
	global_load_dwordx2 v[36:37], v[94:95], off offset:80
	global_load_dwordx2 v[102:103], v[88:89], off offset:80
	v_pk_mul_f32 v[98:99], v[34:35], v[34:35]
	s_waitcnt vmcnt(1)
	v_and_b32_e32 v101, 0xffff0000, v36
	s_waitcnt vmcnt(0)
	v_lshlrev_b32_e32 v104, 16, v102
	v_lshlrev_b32_e32 v100, 16, v36
	v_mul_f32_e32 v36, 0xbfb8aa3b, v104
	v_exp_f32_e32 v36, v36
	v_and_b32_e32 v105, 0xffff0000, v102
	v_pk_fma_f32 v[38:39], v[72:73], v[100:101], v[38:39] op_sel_hi:[0,1,1]
	v_add_f32_e32 v36, 1.0, v36
	v_rcp_f32_e32 v106, v36
	v_mul_f32_e32 v36, 0xbfb8aa3b, v105
	v_exp_f32_e32 v36, v36
	s_nop 0
	v_add_f32_e32 v36, 1.0, v36
	v_rcp_f32_e32 v107, v36
	v_lshlrev_b32_e32 v36, 16, v103
	v_mul_f32_e32 v73, 0xbfb8aa3b, v36
	v_exp_f32_e32 v73, v73
	v_pk_mul_f32 v[100:101], v[106:107], v[104:105]
	v_and_b32_e32 v105, 0xffff0000, v37
	v_lshlrev_b32_e32 v104, 16, v37
	v_and_b32_e32 v37, 0xffff0000, v103
	v_add_f32_e32 v73, 1.0, v73
	v_rcp_f32_e32 v102, v73
	v_pk_fma_f32 v[40:41], v[72:73], v[104:105], v[40:41] op_sel_hi:[0,1,1]
	v_mul_f32_e32 v73, 0xbfb8aa3b, v37
	v_exp_f32_e32 v73, v73
	v_pk_mul_f32 v[38:39], v[38:39], v[100:101]
	v_add_f32_e32 v73, 1.0, v73
	v_rcp_f32_e32 v103, v73
	v_pk_mul_f32 v[100:101], v[38:39], v[38:39]
	v_pk_mul_f32 v[36:37], v[102:103], v[36:37]
	s_nop 0
	v_pk_mul_f32 v[36:37], v[40:41], v[36:37]
	global_load_dwordx2 v[40:41], v[94:95], off offset:96
	global_load_dwordx2 v[106:107], v[88:89], off offset:96
	s_nop 0
	global_load_dwordx2 v[94:95], v[94:95], off offset:112
	s_nop 0
	global_load_dwordx2 v[88:89], v[88:89], off offset:112
	v_pk_mul_f32 v[102:103], v[36:37], v[36:37]
	s_waitcnt vmcnt(3)
	v_and_b32_e32 v105, 0xffff0000, v40
	s_waitcnt vmcnt(2)
	v_lshlrev_b32_e32 v110, 16, v106
	v_lshlrev_b32_e32 v104, 16, v40
	v_mul_f32_e32 v40, 0xbfb8aa3b, v110
	v_exp_f32_e32 v40, v40
	v_and_b32_e32 v111, 0xffff0000, v106
	v_pk_fma_f32 v[42:43], v[72:73], v[104:105], v[42:43] op_sel_hi:[0,1,1]
	v_add_f32_e32 v40, 1.0, v40
	v_rcp_f32_e32 v112, v40
	v_mul_f32_e32 v40, 0xbfb8aa3b, v111
	v_exp_f32_e32 v40, v40
	s_nop 0
	v_add_f32_e32 v40, 1.0, v40
	v_rcp_f32_e32 v113, v40
	v_lshlrev_b32_e32 v40, 16, v107
	v_mul_f32_e32 v73, 0xbfb8aa3b, v40
	v_exp_f32_e32 v73, v73
	v_pk_mul_f32 v[104:105], v[112:113], v[110:111]
	v_and_b32_e32 v111, 0xffff0000, v41
	v_lshlrev_b32_e32 v110, 16, v41
	v_and_b32_e32 v41, 0xffff0000, v107
	v_add_f32_e32 v73, 1.0, v73
	v_rcp_f32_e32 v106, v73
	v_pk_fma_f32 v[44:45], v[72:73], v[110:111], v[44:45] op_sel_hi:[0,1,1]
	v_mul_f32_e32 v73, 0xbfb8aa3b, v41
	v_exp_f32_e32 v73, v73
	s_waitcnt vmcnt(0)
	v_lshlrev_b32_e32 v110, 16, v88
	v_and_b32_e32 v111, 0xffff0000, v88
	v_pk_mul_f32 v[42:43], v[42:43], v[104:105]
	v_add_f32_e32 v73, 1.0, v73
	v_rcp_f32_e32 v107, v73
	v_mul_f32_e32 v73, 0xbfb8aa3b, v110
	v_exp_f32_e32 v73, v73
	v_pk_mul_f32 v[104:105], v[42:43], v[42:43]
	v_pk_mul_f32 v[40:41], v[106:107], v[40:41]
	v_add_f32_e32 v73, 1.0, v73
	v_pk_mul_f32 v[40:41], v[44:45], v[40:41]
	v_and_b32_e32 v45, 0xffff0000, v94
	v_lshlrev_b32_e32 v44, 16, v94
	v_pk_fma_f32 v[44:45], v[72:73], v[44:45], v[46:47] op_sel_hi:[0,1,1]
	v_mul_f32_e32 v46, 0xbfb8aa3b, v111
	v_exp_f32_e32 v46, v46
	v_lshlrev_b32_e32 v94, 16, v89
	v_rcp_f32_e32 v112, v73
	v_mul_f32_e32 v73, 0xbfb8aa3b, v94
	v_add_f32_e32 v46, 1.0, v46
	v_rcp_f32_e32 v113, v46
	v_exp_f32_e32 v73, v73
	v_pk_mul_f32 v[106:107], v[40:41], v[40:41]
	v_pk_mul_f32 v[46:47], v[112:113], v[110:111]
	s_nop 0
	v_pk_mul_f32 v[44:45], v[44:45], v[46:47]
	v_and_b32_e32 v47, 0xffff0000, v95
	v_lshlrev_b32_e32 v46, 16, v95
	v_add_f32_e32 v73, 1.0, v73
	v_rcp_f32_e32 v88, v73
	v_pk_fma_f32 v[46:47], v[72:73], v[46:47], v[48:49] op_sel_hi:[0,1,1]
	v_add_f32_e32 v73, v76, v77
	v_add_f32_e32 v73, v78, v73
	v_add_f32_e32 v73, v79, v73
	v_add_f32_e32 v73, v80, v73
	v_add_f32_e32 v73, v81, v73
	v_add_f32_e32 v73, v82, v73
	v_add_f32_e32 v73, v83, v73
	v_add_f32_e32 v73, v84, v73
	v_add_f32_e32 v73, v85, v73
	v_add_f32_e32 v73, v86, v73
	v_add_f32_e32 v73, v87, v73
	v_add_f32_e32 v73, v90, v73
	v_add_f32_e32 v73, v91, v73
	v_add_f32_e32 v73, v92, v73
	v_add_f32_e32 v73, v93, v73
	v_and_b32_e32 v95, 0xffff0000, v89
	v_add_f32_e32 v73, v96, v73
	v_mul_f32_e32 v48, 0xbfb8aa3b, v95
	v_add_f32_e32 v73, v97, v73
	v_exp_f32_e32 v48, v48
	v_add_f32_e32 v73, v98, v73
	v_add_f32_e32 v73, v99, v73
	v_add_f32_e32 v73, v100, v73
	v_add_f32_e32 v73, v101, v73
	v_add_f32_e32 v48, 1.0, v48
	v_add_f32_e32 v73, v102, v73
	v_rcp_f32_e32 v89, v48
	v_add_f32_e32 v73, v103, v73
	v_add_f32_e32 v73, v104, v73
	v_add_f32_e32 v73, v105, v73
	v_add_f32_e32 v73, v106, v73
	v_pk_mul_f32 v[110:111], v[44:45], v[44:45]
	v_pk_mul_f32 v[48:49], v[88:89], v[94:95]
	v_add_f32_e32 v73, v107, v73
	v_pk_mul_f32 v[46:47], v[46:47], v[48:49]
	v_add_f32_e32 v73, v110, v73
	v_pk_mul_f32 v[48:49], v[46:47], v[46:47]
	v_add_f32_e32 v73, v111, v73
	v_add_f32_e32 v48, v48, v73
	v_add_f32_e32 v48, v49, v48
	ds_bpermute_b32 v49, v175, v48
	s_and_saveexec_b64 s[2:3], s[8:9]
	s_cbranch_execz .LBB0_127
	s_waitcnt lgkmcnt(0)
	v_add_f32_e32 v48, v48, v49
	ds_write_b32 v184, v48 offset:34816

.LBB0_293:
	s_add_i32 s2, s11, s12
	s_cmpk_gt_i32 s2, 0xcb1
	s_mov_b64 s[0:1], -1
	s_cbranch_scc1 .LBB0_292
	s_mul_hi_i32 s0, s2, 0x51eb851f
	s_lshr_b32 s1, s0, 31
	s_ashr_i32 s0, s0, 6
	s_add_i32 s0, s0, s1
	s_lshl_b32 s1, s0, 3
	s_sub_i32 s3, 0x82, s1
	s_min_u32 s3, s3, 8
	v_cvt_f32_ubyte0_e32 v0, s3
	v_rcp_iflag_f32_e32 v0, v0
	s_sub_i32 s5, 0, s3
	s_mulk_i32 s0, 0xff38
	s_add_i32 s0, s0, s2
	v_mul_f32_e32 v0, 0x4f7ffffe, v0
	v_cvt_u32_f32_e32 v0, v0
	s_abs_i32 s4, s0
	s_ashr_i32 s2, s0, 31
	v_readlane_b32 s16, v251, 2
	v_readfirstlane_b32 s7, v0
	s_mul_i32 s5, s5, s7
	s_mul_hi_u32 s5, s7, s5
	s_add_i32 s7, s7, s5
	s_mul_hi_u32 s5, s4, s7
	s_mul_i32 s7, s5, s3
	s_sub_i32 s4, s4, s7
	s_add_i32 s7, s5, 1
	s_sub_i32 s8, s4, s3
	s_cmp_ge_u32 s4, s3
	s_cselect_b32 s5, s7, s5
	s_cselect_b32 s4, s8, s4
	s_add_i32 s7, s5, 1
	s_cmp_ge_u32 s4, s3
	s_cselect_b32 s4, s7, s5
	s_xor_b32 s4, s4, s2
	s_sub_i32 s4, s4, s2
	s_mul_i32 s2, s4, s3
	s_sub_i32 s0, s0, s2
	s_add_i32 s0, s0, s1
	s_lshl_b32 s0, s0, 8
	s_lshl_b32 s4, s4, 8
	s_ashr_i32 s1, s0, 31
	s_ashr_i32 s5, s4, 31
	s_lshl_b64 s[2:3], s[0:1], 11
	s_lshl_b64 s[8:9], s[4:5], 11
	v_readlane_b32 s28, v251, 14
	v_readlane_b32 s29, v251, 15
	s_add_u32 s14, s28, s2
	v_mov_b32_e32 v0, v142
	s_addc_u32 s15, s29, s3
	s_waitcnt vmcnt(63) expcnt(7) lgkmcnt(15)
	s_barrier
	v_readlane_b32 s17, v251, 3
	v_lshl_add_u64 v[2:3], v[0:1], 1, s[14:15]
	v_add_u32_e32 v0, 32, v143
	v_readlane_b32 s16, v251, 42
	v_readfirstlane_b32 s1, v0
	s_mov_b32 m0, s1
	v_mov_b32_e32 v0, v144
	global_load_lds_dwordx4 v[2:3], off
	v_readlane_b32 s17, v251, 43
	v_lshl_add_u64 v[2:3], v[0:1], 1, s[14:15]
	v_add_u32_e32 v0, 32, v145
	s_add_u32 s16, s16, s8
	v_readfirstlane_b32 s1, v0
	s_mov_b32 m0, s1
	v_mov_b32_e32 v0, v146
	global_load_lds_dwordx4 v[2:3], off
	s_addc_u32 s17, s17, s9
	v_lshl_add_u64 v[2:3], v[0:1], 1, s[14:15]
	v_add_u32_e32 v0, 32, v147
	v_readlane_b32 s5, v254, 3
	v_readfirstlane_b32 s1, v0
	s_mov_b32 m0, s1
	v_mov_b32_e32 v0, v148
	global_load_lds_dwordx4 v[2:3], off
	s_mov_b32 s6, 0
	v_lshl_add_u64 v[2:3], v[0:1], 1, s[14:15]
	v_add_u32_e32 v0, 32, v149
	v_readlane_b32 s18, v251, 4
	v_readfirstlane_b32 s1, v0
	s_mov_b32 m0, s1
	v_mov_b32_e32 v0, v142
	global_load_lds_dwordx4 v[2:3], off
	v_readlane_b32 s19, v251, 5
	v_lshl_add_u64 v[2:3], v[0:1], 1, s[16:17]
	v_add_u32_e32 v0, s5, v143
	v_readlane_b32 s20, v251, 6
	v_readfirstlane_b32 s1, v0
	s_mov_b32 m0, s1
	v_mov_b32_e32 v0, v144
	global_load_lds_dwordx4 v[2:3], off
	v_readlane_b32 s21, v251, 7
	v_lshl_add_u64 v[2:3], v[0:1], 1, s[16:17]
	v_add_u32_e32 v0, s5, v145
	v_readlane_b32 s22, v251, 8
	v_readfirstlane_b32 s1, v0
	s_mov_b32 m0, s1
	v_mov_b32_e32 v0, v146
	global_load_lds_dwordx4 v[2:3], off
	v_readlane_b32 s23, v251, 9
	v_lshl_add_u64 v[2:3], v[0:1], 1, s[16:17]
	v_add_u32_e32 v0, s5, v147
	v_readlane_b32 s24, v251, 10
	v_readfirstlane_b32 s1, v0
	s_mov_b32 m0, s1
	v_mov_b32_e32 v0, v148
	global_load_lds_dwordx4 v[2:3], off
	v_readlane_b32 s25, v251, 11
	v_lshl_add_u64 v[2:3], v[0:1], 1, s[16:17]
	v_add_u32_e32 v0, s5, v149
	v_readlane_b32 s26, v251, 12
	v_readfirstlane_b32 s1, v0
	s_mov_b32 m0, s1
	v_readlane_b32 s1, v253, 29
	global_load_lds_dwordx4 v[2:3], off
	s_add_u32 s1, s1, s2
	v_readlane_b32 s2, v253, 30
	s_waitcnt vmcnt(0)
	s_addc_u32 s5, s2, s3
	v_readlane_b32 s2, v253, 31
	s_add_u32 s7, s2, s8
	v_readlane_b32 s2, v253, 32
	v_mov_b32_e32 v2, 0
	s_addc_u32 s8, s2, s9
	s_mov_b64 s[2:3], 0
	v_mov_b32_e32 v3, v2
	v_mov_b32_e32 v4, v2
	v_mov_b32_e32 v5, v2
	v_mov_b32_e32 v6, v2
	v_mov_b32_e32 v7, v2
	v_mov_b32_e32 v8, v2
	v_mov_b32_e32 v9, v2
	v_mov_b32_e32 v10, v2
	v_mov_b32_e32 v11, v2
	v_mov_b32_e32 v12, v2
	v_mov_b32_e32 v13, v2
	s_waitcnt vmcnt(0)
	v_mov_b32_e32 v14, v2
	v_mov_b32_e32 v15, v2
	v_mov_b32_e32 v16, v2
	v_mov_b32_e32 v17, v2
	v_mov_b32_e32 v18, v2
	v_mov_b32_e32 v19, v2
	v_mov_b32_e32 v20, v2
	v_mov_b32_e32 v21, v2
	v_mov_b32_e32 v22, v2
	v_mov_b32_e32 v23, v2
	v_mov_b32_e32 v24, v2
	v_mov_b32_e32 v25, v2
	v_mov_b32_e32 v26, v2
	v_mov_b32_e32 v27, v2
	v_mov_b32_e32 v28, v2
	v_mov_b32_e32 v29, v2
	v_mov_b32_e32 v30, v2
	v_mov_b32_e32 v31, v2
	v_mov_b32_e32 v32, v2
	v_mov_b32_e32 v33, v2
	v_mov_b32_e32 v34, v2
	v_mov_b32_e32 v35, v2
	v_mov_b32_e32 v36, v2
	v_mov_b32_e32 v37, v2
	v_mov_b32_e32 v38, v2
	v_mov_b32_e32 v39, v2
	v_mov_b32_e32 v40, v2
	v_mov_b32_e32 v41, v2
	v_mov_b32_e32 v42, v2
	v_mov_b32_e32 v43, v2
	v_mov_b32_e32 v44, v2
	v_mov_b32_e32 v45, v2
	v_mov_b32_e32 v46, v2
	v_mov_b32_e32 v47, v2
	v_mov_b32_e32 v48, v2
	v_mov_b32_e32 v49, v2
	v_mov_b32_e32 v50, v2
	v_mov_b32_e32 v51, v2
	v_mov_b32_e32 v52, v2
	v_mov_b32_e32 v53, v2
	v_mov_b32_e32 v54, v2
	v_mov_b32_e32 v55, v2
	v_mov_b32_e32 v56, v2
	v_mov_b32_e32 v57, v2
	v_mov_b32_e32 v58, v2
	v_mov_b32_e32 v59, v2
	v_mov_b32_e32 v60, v2
	v_mov_b32_e32 v61, v2
	v_mov_b32_e32 v62, v2
	v_mov_b32_e32 v63, v2
	v_mov_b32_e32 v64, v2
	v_mov_b32_e32 v65, v2
	v_mov_b32_e32 v66, v2
	v_mov_b32_e32 v67, v2
	v_mov_b32_e32 v68, v2
	v_mov_b32_e32 v69, v2
	v_mov_b32_e32 v70, v2
	v_mov_b32_e32 v71, v2
	v_mov_b32_e32 v72, v2
	v_mov_b32_e32 v73, v2
	v_mov_b32_e32 v74, v2
	v_mov_b32_e32 v75, v2
	v_mov_b32_e32 v76, v2
	v_mov_b32_e32 v77, v2
	v_mov_b32_e32 v78, v2
	v_mov_b32_e32 v79, v2
	v_mov_b32_e32 v80, v2
	v_mov_b32_e32 v81, v2
	v_mov_b32_e32 v82, v2
	v_mov_b32_e32 v83, v2
	v_mov_b32_e32 v84, v2
	v_mov_b32_e32 v85, v2
	v_mov_b32_e32 v86, v2
	v_mov_b32_e32 v87, v2
	v_mov_b32_e32 v88, v2
	v_mov_b32_e32 v89, v2
	v_mov_b32_e32 v90, v2
	v_mov_b32_e32 v91, v2
	v_mov_b32_e32 v92, v2
	v_mov_b32_e32 v93, v2
	v_mov_b32_e32 v94, v2
	v_mov_b32_e32 v95, v2
	v_mov_b32_e32 v96, v2
	v_mov_b32_e32 v97, v2
	v_mov_b32_e32 v98, v2
	v_mov_b32_e32 v99, v2
	v_mov_b32_e32 v100, v2
	v_mov_b32_e32 v101, v2
	v_mov_b32_e32 v102, v2
	v_mov_b32_e32 v103, v2
	v_mov_b32_e32 v104, v2
	v_mov_b32_e32 v105, v2
	v_mov_b32_e32 v106, v2
	v_mov_b32_e32 v107, v2
	v_mov_b32_e32 v108, v2
	v_mov_b32_e32 v109, v2
	v_mov_b32_e32 v110, v2
	v_mov_b32_e32 v111, v2
	v_mov_b32_e32 v112, v2
	v_mov_b32_e32 v113, v2
	v_mov_b32_e32 v114, v2
	v_mov_b32_e32 v115, v2
	v_mov_b32_e32 v116, v2
	v_mov_b32_e32 v117, v2
	v_mov_b32_e32 v118, v2
	v_mov_b32_e32 v119, v2
	v_mov_b32_e32 v120, v2
	v_mov_b32_e32 v121, v2
	v_mov_b32_e32 v122, v2
	v_mov_b32_e32 v123, v2
	v_mov_b32_e32 v124, v2
	v_mov_b32_e32 v125, v2
	v_mov_b32_e32 v126, v2
	v_mov_b32_e32 v127, v2
	v_mov_b32_e32 v128, v2
	v_mov_b32_e32 v129, v2
	v_readlane_b32 s27, v251, 13
	v_readlane_b32 s30, v251, 16
	v_readlane_b32 s31, v251, 17
	s_waitcnt lgkmcnt(0)
	s_barrier
	v_lshlrev_b32_e32 v159, 1, v142
	v_readfirstlane_b32 s9, v143
	v_add_u32_e32 v177, v150, v152
	v_add_u32_e32 v207, v151, v152
	v_add_u32_e32 v204, v150, v156
	v_add_u32_e32 v208, v151, v156
	v_add_u32_e32 v205, v150, v157
	v_add_u32_e32 v209, v151, v157
	v_add_u32_e32 v206, v150, v158
	v_add_u32_e32 v210, v151, v158
	s_mov_b32 s6, 7
	s_add_u32 m0, s9, 0x8020
	s_add_u32 s14, s1, s2
	s_addc_u32 s15, s5, s3
	global_load_lds_dwordx4 v159, s[14:15]
	s_add_u32 m0, s9, 0xa020
	s_add_u32 s14, s14, 0x20000
	s_addc_u32 s15, s15, 0
	global_load_lds_dwordx4 v159, s[14:15]
	s_add_u32 m0, s9, 0xc020
	s_add_u32 s14, s14, 0x20000
	s_addc_u32 s15, s15, 0
	global_load_lds_dwordx4 v159, s[14:15]
	s_add_u32 m0, s9, 0xe020
	s_add_u32 s14, s14, 0x20000
	s_addc_u32 s15, s15, 0
	global_load_lds_dwordx4 v159, s[14:15]
	ds_read_b128 v[130:133], v177 offset:0
	ds_read_b128 v[164:167], v207 offset:0
	ds_read_b128 v[168:171], v207 offset:4096
	ds_read_b128 v[134:137], v177 offset:4096
	ds_read_b128 v[138:141], v177 offset:8192
	ds_read_b128 v[160:163], v177 offset:12288
.Lg295_loop:
	s_waitcnt lgkmcnt(4)
	v_mfma_f32_32x32x16_bf16 v[114:129], v[130:133], v[164:167], v[114:129]
	ds_read_b128 v[172:175], v204 offset:0
	s_waitcnt lgkmcnt(4)
	v_mfma_f32_32x32x16_bf16 v[98:113], v[130:133], v[168:171], v[98:113]
	ds_read_b128 v[192:195], v208 offset:0
	s_add_u32 m0, s9, 0x18020
	s_add_u32 s14, s7, s2
	s_addc_u32 s15, s8, s3
	global_load_lds_dwordx4 v159, s[14:15]
	s_waitcnt lgkmcnt(4)
	v_mfma_f32_32x32x16_bf16 v[82:97], v[134:137], v[164:167], v[82:97]
	ds_read_b128 v[200:203], v208 offset:4096
	v_mfma_f32_32x32x16_bf16 v[66:81], v[134:137], v[168:171], v[66:81]
	ds_read_b128 v[180:183], v204 offset:4096
	s_add_u32 m0, s9, 0x1a020
	s_add_u32 s14, s14, 0x20000
	s_addc_u32 s15, s15, 0
	global_load_lds_dwordx4 v159, s[14:15]
	s_waitcnt lgkmcnt(5)
	v_mfma_f32_32x32x16_bf16 v[50:65], v[138:141], v[164:167], v[50:65]
	ds_read_b128 v[184:187], v204 offset:8192
	v_mfma_f32_32x32x16_bf16 v[34:49], v[138:141], v[168:171], v[34:49]
	ds_read_b128 v[188:191], v204 offset:12288
	s_add_u32 m0, s9, 0x1c020
	s_add_u32 s14, s14, 0x20000
	s_addc_u32 s15, s15, 0
	global_load_lds_dwordx4 v159, s[14:15]
	s_waitcnt lgkmcnt(6)
	v_mfma_f32_32x32x16_bf16 v[18:33], v[160:163], v[164:167], v[18:33]
	v_mfma_f32_32x32x16_bf16 v[2:17], v[160:163], v[168:171], v[2:17]
	s_add_u32 m0, s9, 0x1e020
	s_add_u32 s14, s14, 0x20000
	s_addc_u32 s15, s15, 0
	global_load_lds_dwordx4 v159, s[14:15]
	s_add_u32 s2, s2, 0x80
	s_addc_u32 s3, s3, 0
	s_waitcnt lgkmcnt(4)
	v_mfma_f32_32x32x16_bf16 v[114:129], v[172:175], v[192:195], v[114:129]
	ds_read_b128 v[130:133], v205 offset:0
	s_waitcnt lgkmcnt(4)
	v_mfma_f32_32x32x16_bf16 v[98:113], v[172:175], v[200:203], v[98:113]
	ds_read_b128 v[164:167], v209 offset:0
	s_waitcnt lgkmcnt(4)
	v_mfma_f32_32x32x16_bf16 v[82:97], v[180:183], v[192:195], v[82:97]
	ds_read_b128 v[168:171], v209 offset:4096
	v_mfma_f32_32x32x16_bf16 v[66:81], v[180:183], v[200:203], v[66:81]
	ds_read_b128 v[134:137], v205 offset:4096
	s_waitcnt lgkmcnt(5)
	v_mfma_f32_32x32x16_bf16 v[50:65], v[184:187], v[192:195], v[50:65]
	ds_read_b128 v[138:141], v205 offset:8192
	v_mfma_f32_32x32x16_bf16 v[34:49], v[184:187], v[200:203], v[34:49]
	ds_read_b128 v[160:163], v205 offset:12288
	s_waitcnt lgkmcnt(6)
	v_mfma_f32_32x32x16_bf16 v[18:33], v[188:191], v[192:195], v[18:33]
	v_mfma_f32_32x32x16_bf16 v[2:17], v[188:191], v[200:203], v[2:17]
	s_waitcnt lgkmcnt(4)
	v_mfma_f32_32x32x16_bf16 v[114:129], v[130:133], v[164:167], v[114:129]
	ds_read_b128 v[172:175], v206 offset:0
	ds_read_b128 v[192:195], v210 offset:0
	s_waitcnt lgkmcnt(5)
	v_mfma_f32_32x32x16_bf16 v[98:113], v[130:133], v[168:171], v[98:113]
	ds_read_b128 v[200:203], v210 offset:4096
	ds_read_b128 v[180:183], v206 offset:4096
	s_waitcnt lgkmcnt(6)
	v_mfma_f32_32x32x16_bf16 v[82:97], v[134:137], v[164:167], v[82:97]
	ds_read_b128 v[184:187], v206 offset:8192
	ds_read_b128 v[188:191], v206 offset:12288
	v_mfma_f32_32x32x16_bf16 v[66:81], v[134:137], v[168:171], v[66:81]
	s_waitcnt lgkmcnt(7)
	v_mfma_f32_32x32x16_bf16 v[50:65], v[138:141], v[164:167], v[50:65]
	v_mfma_f32_32x32x16_bf16 v[34:49], v[138:141], v[168:171], v[34:49]
	s_waitcnt lgkmcnt(6)
	v_mfma_f32_32x32x16_bf16 v[18:33], v[160:163], v[164:167], v[18:33]
	v_mfma_f32_32x32x16_bf16 v[2:17], v[160:163], v[168:171], v[2:17]
	s_waitcnt vmcnt(0) lgkmcnt(0)
	s_barrier
	v_mfma_f32_32x32x16_bf16 v[114:129], v[172:175], v[192:195], v[114:129]
	ds_read_b128 v[130:133], v177 offset:32768
	v_mfma_f32_32x32x16_bf16 v[98:113], v[172:175], v[200:203], v[98:113]
	ds_read_b128 v[164:167], v207 offset:32768
	s_add_u32 m0, s9, 0x20
	s_add_u32 s14, s1, s2
	s_addc_u32 s15, s5, s3
	global_load_lds_dwordx4 v159, s[14:15]
	v_mfma_f32_32x32x16_bf16 v[82:97], v[180:183], v[192:195], v[82:97]
	ds_read_b128 v[168:171], v207 offset:36864
	v_mfma_f32_32x32x16_bf16 v[66:81], v[180:183], v[200:203], v[66:81]
	ds_read_b128 v[134:137], v177 offset:36864
	s_add_u32 m0, s9, 0x2020
	s_add_u32 s14, s14, 0x20000
	s_addc_u32 s15, s15, 0
	global_load_lds_dwordx4 v159, s[14:15]
	v_mfma_f32_32x32x16_bf16 v[50:65], v[184:187], v[192:195], v[50:65]
	ds_read_b128 v[138:141], v177 offset:40960
	v_mfma_f32_32x32x16_bf16 v[34:49], v[184:187], v[200:203], v[34:49]
	ds_read_b128 v[160:163], v177 offset:45056
	s_add_u32 m0, s9, 0x4020
	s_add_u32 s14, s14, 0x20000
	s_addc_u32 s15, s15, 0
	global_load_lds_dwordx4 v159, s[14:15]
	v_mfma_f32_32x32x16_bf16 v[18:33], v[188:191], v[192:195], v[18:33]
	v_mfma_f32_32x32x16_bf16 v[2:17], v[188:191], v[200:203], v[2:17]
	s_add_u32 m0, s9, 0x6020
	s_add_u32 s14, s14, 0x20000
	s_addc_u32 s15, s15, 0
	global_load_lds_dwordx4 v159, s[14:15]
	s_waitcnt lgkmcnt(4)
	v_mfma_f32_32x32x16_bf16 v[114:129], v[130:133], v[164:167], v[114:129]
	ds_read_b128 v[172:175], v204 offset:32768
	s_waitcnt lgkmcnt(4)
	v_mfma_f32_32x32x16_bf16 v[98:113], v[130:133], v[168:171], v[98:113]
	ds_read_b128 v[192:195], v208 offset:32768
	s_add_u32 m0, s9, 0x10020
	s_add_u32 s14, s7, s2
	s_addc_u32 s15, s8, s3
	global_load_lds_dwordx4 v159, s[14:15]
	s_waitcnt lgkmcnt(4)
	v_mfma_f32_32x32x16_bf16 v[82:97], v[134:137], v[164:167], v[82:97]
	ds_read_b128 v[200:203], v208 offset:36864
	v_mfma_f32_32x32x16_bf16 v[66:81], v[134:137], v[168:171], v[66:81]
	ds_read_b128 v[180:183], v204 offset:36864
	s_add_u32 m0, s9, 0x12020
	s_add_u32 s14, s14, 0x20000
	s_addc_u32 s15, s15, 0
	global_load_lds_dwordx4 v159, s[14:15]
	s_waitcnt lgkmcnt(5)
	v_mfma_f32_32x32x16_bf16 v[50:65], v[138:141], v[164:167], v[50:65]
	ds_read_b128 v[184:187], v204 offset:40960
	v_mfma_f32_32x32x16_bf16 v[34:49], v[138:141], v[168:171], v[34:49]
	ds_read_b128 v[188:191], v204 offset:45056
	s_add_u32 m0, s9, 0x14020
	s_add_u32 s14, s14, 0x20000
	s_addc_u32 s15, s15, 0
	global_load_lds_dwordx4 v159, s[14:15]
	s_waitcnt lgkmcnt(6)
	v_mfma_f32_32x32x16_bf16 v[18:33], v[160:163], v[164:167], v[18:33]
	v_mfma_f32_32x32x16_bf16 v[2:17], v[160:163], v[168:171], v[2:17]
	s_add_u32 m0, s9, 0x16020
	s_add_u32 s14, s14, 0x20000
	s_addc_u32 s15, s15, 0
	global_load_lds_dwordx4 v159, s[14:15]
	s_add_u32 s2, s2, 0x80
	s_addc_u32 s3, s3, 0
	s_waitcnt lgkmcnt(4)
	v_mfma_f32_32x32x16_bf16 v[114:129], v[172:175], v[192:195], v[114:129]
	ds_read_b128 v[130:133], v205 offset:32768
	s_waitcnt lgkmcnt(4)
	v_mfma_f32_32x32x16_bf16 v[98:113], v[172:175], v[200:203], v[98:113]
	ds_read_b128 v[164:167], v209 offset:32768
	s_waitcnt lgkmcnt(4)
	v_mfma_f32_32x32x16_bf16 v[82:97], v[180:183], v[192:195], v[82:97]
	ds_read_b128 v[168:171], v209 offset:36864
	v_mfma_f32_32x32x16_bf16 v[66:81], v[180:183], v[200:203], v[66:81]
	ds_read_b128 v[134:137], v205 offset:36864
	s_waitcnt lgkmcnt(5)
	v_mfma_f32_32x32x16_bf16 v[50:65], v[184:187], v[192:195], v[50:65]
	ds_read_b128 v[138:141], v205 offset:40960
	v_mfma_f32_32x32x16_bf16 v[34:49], v[184:187], v[200:203], v[34:49]
	ds_read_b128 v[160:163], v205 offset:45056
	s_waitcnt lgkmcnt(6)
	v_mfma_f32_32x32x16_bf16 v[18:33], v[188:191], v[192:195], v[18:33]
	v_mfma_f32_32x32x16_bf16 v[2:17], v[188:191], v[200:203], v[2:17]
	s_waitcnt lgkmcnt(4)
	v_mfma_f32_32x32x16_bf16 v[114:129], v[130:133], v[164:167], v[114:129]
	ds_read_b128 v[172:175], v206 offset:32768
	ds_read_b128 v[192:195], v210 offset:32768
	s_waitcnt lgkmcnt(5)
	v_mfma_f32_32x32x16_bf16 v[98:113], v[130:133], v[168:171], v[98:113]
	ds_read_b128 v[200:203], v210 offset:36864
	ds_read_b128 v[180:183], v206 offset:36864
	s_waitcnt lgkmcnt(6)
	v_mfma_f32_32x32x16_bf16 v[82:97], v[134:137], v[164:167], v[82:97]
	ds_read_b128 v[184:187], v206 offset:40960
	ds_read_b128 v[188:191], v206 offset:45056
	v_mfma_f32_32x32x16_bf16 v[66:81], v[134:137], v[168:171], v[66:81]
	s_waitcnt lgkmcnt(7)
	v_mfma_f32_32x32x16_bf16 v[50:65], v[138:141], v[164:167], v[50:65]
	v_mfma_f32_32x32x16_bf16 v[34:49], v[138:141], v[168:171], v[34:49]
	s_waitcnt lgkmcnt(6)
	v_mfma_f32_32x32x16_bf16 v[18:33], v[160:163], v[164:167], v[18:33]
	v_mfma_f32_32x32x16_bf16 v[2:17], v[160:163], v[168:171], v[2:17]
	s_waitcnt vmcnt(0) lgkmcnt(0)
	s_barrier
	v_mfma_f32_32x32x16_bf16 v[114:129], v[172:175], v[192:195], v[114:129]
	ds_read_b128 v[130:133], v177 offset:0
	v_mfma_f32_32x32x16_bf16 v[98:113], v[172:175], v[200:203], v[98:113]
	ds_read_b128 v[164:167], v207 offset:0
	s_add_u32 m0, s9, 0x8020
	s_add_u32 s14, s1, s2
	s_addc_u32 s15, s5, s3
	global_load_lds_dwordx4 v159, s[14:15]
	v_mfma_f32_32x32x16_bf16 v[82:97], v[180:183], v[192:195], v[82:97]
	ds_read_b128 v[168:171], v207 offset:4096
	v_mfma_f32_32x32x16_bf16 v[66:81], v[180:183], v[200:203], v[66:81]
	ds_read_b128 v[134:137], v177 offset:4096
	s_add_u32 m0, s9, 0xa020
	s_add_u32 s14, s14, 0x20000
	s_addc_u32 s15, s15, 0
	global_load_lds_dwordx4 v159, s[14:15]
	v_mfma_f32_32x32x16_bf16 v[50:65], v[184:187], v[192:195], v[50:65]
	ds_read_b128 v[138:141], v177 offset:8192
	v_mfma_f32_32x32x16_bf16 v[34:49], v[184:187], v[200:203], v[34:49]
	ds_read_b128 v[160:163], v177 offset:12288
	s_add_u32 m0, s9, 0xc020
	s_add_u32 s14, s14, 0x20000
	s_addc_u32 s15, s15, 0
	global_load_lds_dwordx4 v159, s[14:15]
	v_mfma_f32_32x32x16_bf16 v[18:33], v[188:191], v[192:195], v[18:33]
	v_mfma_f32_32x32x16_bf16 v[2:17], v[188:191], v[200:203], v[2:17]
	s_add_u32 m0, s9, 0xe020
	s_add_u32 s14, s14, 0x20000
	s_addc_u32 s15, s15, 0
	global_load_lds_dwordx4 v159, s[14:15]
	s_sub_u32 s6, s6, 1
	s_cmp_lg_u32 s6, 0
	s_cbranch_scc1 .Lg295_loop
	s_waitcnt lgkmcnt(4)
	v_mfma_f32_32x32x16_bf16 v[114:129], v[130:133], v[164:167], v[114:129]
	ds_read_b128 v[172:175], v204 offset:0
	s_waitcnt lgkmcnt(4)
	v_mfma_f32_32x32x16_bf16 v[98:113], v[130:133], v[168:171], v[98:113]
	ds_read_b128 v[192:195], v208 offset:0
	s_add_u32 m0, s9, 0x18020
	s_add_u32 s14, s7, s2
	s_addc_u32 s15, s8, s3
	global_load_lds_dwordx4 v159, s[14:15]
	s_waitcnt lgkmcnt(4)
	v_mfma_f32_32x32x16_bf16 v[82:97], v[134:137], v[164:167], v[82:97]
	ds_read_b128 v[200:203], v208 offset:4096
	v_mfma_f32_32x32x16_bf16 v[66:81], v[134:137], v[168:171], v[66:81]
	ds_read_b128 v[180:183], v204 offset:4096
	s_add_u32 m0, s9, 0x1a020
	s_add_u32 s14, s14, 0x20000
	s_addc_u32 s15, s15, 0
	global_load_lds_dwordx4 v159, s[14:15]
	s_waitcnt lgkmcnt(5)
	v_mfma_f32_32x32x16_bf16 v[50:65], v[138:141], v[164:167], v[50:65]
	ds_read_b128 v[184:187], v204 offset:8192
	v_mfma_f32_32x32x16_bf16 v[34:49], v[138:141], v[168:171], v[34:49]
	ds_read_b128 v[188:191], v204 offset:12288
	s_add_u32 m0, s9, 0x1c020
	s_add_u32 s14, s14, 0x20000
	s_addc_u32 s15, s15, 0
	global_load_lds_dwordx4 v159, s[14:15]
	s_waitcnt lgkmcnt(6)
	v_mfma_f32_32x32x16_bf16 v[18:33], v[160:163], v[164:167], v[18:33]
	v_mfma_f32_32x32x16_bf16 v[2:17], v[160:163], v[168:171], v[2:17]
	s_add_u32 m0, s9, 0x1e020
	s_add_u32 s14, s14, 0x20000
	s_addc_u32 s15, s15, 0
	global_load_lds_dwordx4 v159, s[14:15]
	s_add_u32 s2, s2, 0x80
	s_addc_u32 s3, s3, 0
	s_waitcnt lgkmcnt(4)
	v_mfma_f32_32x32x16_bf16 v[114:129], v[172:175], v[192:195], v[114:129]
	ds_read_b128 v[130:133], v205 offset:0
	s_waitcnt lgkmcnt(4)
	v_mfma_f32_32x32x16_bf16 v[98:113], v[172:175], v[200:203], v[98:113]
	ds_read_b128 v[164:167], v209 offset:0
	s_waitcnt lgkmcnt(4)
	v_mfma_f32_32x32x16_bf16 v[82:97], v[180:183], v[192:195], v[82:97]
	ds_read_b128 v[168:171], v209 offset:4096
	v_mfma_f32_32x32x16_bf16 v[66:81], v[180:183], v[200:203], v[66:81]
	ds_read_b128 v[134:137], v205 offset:4096
	s_waitcnt lgkmcnt(5)
	v_mfma_f32_32x32x16_bf16 v[50:65], v[184:187], v[192:195], v[50:65]
	ds_read_b128 v[138:141], v205 offset:8192
	v_mfma_f32_32x32x16_bf16 v[34:49], v[184:187], v[200:203], v[34:49]
	ds_read_b128 v[160:163], v205 offset:12288
	s_waitcnt lgkmcnt(6)
	v_mfma_f32_32x32x16_bf16 v[18:33], v[188:191], v[192:195], v[18:33]
	v_mfma_f32_32x32x16_bf16 v[2:17], v[188:191], v[200:203], v[2:17]
	s_waitcnt lgkmcnt(4)
	v_mfma_f32_32x32x16_bf16 v[114:129], v[130:133], v[164:167], v[114:129]
	ds_read_b128 v[172:175], v206 offset:0
	ds_read_b128 v[192:195], v210 offset:0
	s_waitcnt lgkmcnt(5)
	v_mfma_f32_32x32x16_bf16 v[98:113], v[130:133], v[168:171], v[98:113]
	ds_read_b128 v[200:203], v210 offset:4096
	ds_read_b128 v[180:183], v206 offset:4096
	s_waitcnt lgkmcnt(6)
	v_mfma_f32_32x32x16_bf16 v[82:97], v[134:137], v[164:167], v[82:97]
	ds_read_b128 v[184:187], v206 offset:8192
	ds_read_b128 v[188:191], v206 offset:12288
	v_mfma_f32_32x32x16_bf16 v[66:81], v[134:137], v[168:171], v[66:81]
	s_waitcnt lgkmcnt(7)
	v_mfma_f32_32x32x16_bf16 v[50:65], v[138:141], v[164:167], v[50:65]
	v_mfma_f32_32x32x16_bf16 v[34:49], v[138:141], v[168:171], v[34:49]
	s_waitcnt lgkmcnt(6)
	v_mfma_f32_32x32x16_bf16 v[18:33], v[160:163], v[164:167], v[18:33]
	v_mfma_f32_32x32x16_bf16 v[2:17], v[160:163], v[168:171], v[2:17]
	s_waitcnt vmcnt(0) lgkmcnt(0)
	s_barrier
	v_mfma_f32_32x32x16_bf16 v[114:129], v[172:175], v[192:195], v[114:129]
	ds_read_b128 v[130:133], v177 offset:32768
	v_mfma_f32_32x32x16_bf16 v[98:113], v[172:175], v[200:203], v[98:113]
	ds_read_b128 v[164:167], v207 offset:32768
	v_mfma_f32_32x32x16_bf16 v[82:97], v[180:183], v[192:195], v[82:97]
	ds_read_b128 v[168:171], v207 offset:36864
	v_mfma_f32_32x32x16_bf16 v[66:81], v[180:183], v[200:203], v[66:81]
	ds_read_b128 v[134:137], v177 offset:36864
	v_mfma_f32_32x32x16_bf16 v[50:65], v[184:187], v[192:195], v[50:65]
	ds_read_b128 v[138:141], v177 offset:40960
	v_mfma_f32_32x32x16_bf16 v[34:49], v[184:187], v[200:203], v[34:49]
	ds_read_b128 v[160:163], v177 offset:45056
	v_mfma_f32_32x32x16_bf16 v[18:33], v[188:191], v[192:195], v[18:33]
	v_mfma_f32_32x32x16_bf16 v[2:17], v[188:191], v[200:203], v[2:17]
	s_waitcnt lgkmcnt(4)
	v_mfma_f32_32x32x16_bf16 v[114:129], v[130:133], v[164:167], v[114:129]
	ds_read_b128 v[172:175], v204 offset:32768
	s_waitcnt lgkmcnt(4)
	v_mfma_f32_32x32x16_bf16 v[98:113], v[130:133], v[168:171], v[98:113]
	ds_read_b128 v[192:195], v208 offset:32768
	s_waitcnt lgkmcnt(4)
	v_mfma_f32_32x32x16_bf16 v[82:97], v[134:137], v[164:167], v[82:97]
	ds_read_b128 v[200:203], v208 offset:36864
	v_mfma_f32_32x32x16_bf16 v[66:81], v[134:137], v[168:171], v[66:81]
	ds_read_b128 v[180:183], v204 offset:36864
	s_waitcnt lgkmcnt(5)
	v_mfma_f32_32x32x16_bf16 v[50:65], v[138:141], v[164:167], v[50:65]
	ds_read_b128 v[184:187], v204 offset:40960
	v_mfma_f32_32x32x16_bf16 v[34:49], v[138:141], v[168:171], v[34:49]
	ds_read_b128 v[188:191], v204 offset:45056
	s_waitcnt lgkmcnt(6)
	v_mfma_f32_32x32x16_bf16 v[18:33], v[160:163], v[164:167], v[18:33]
	v_mfma_f32_32x32x16_bf16 v[2:17], v[160:163], v[168:171], v[2:17]
	s_waitcnt lgkmcnt(4)
	v_mfma_f32_32x32x16_bf16 v[114:129], v[172:175], v[192:195], v[114:129]
	ds_read_b128 v[130:133], v205 offset:32768
	s_waitcnt lgkmcnt(4)
	v_mfma_f32_32x32x16_bf16 v[98:113], v[172:175], v[200:203], v[98:113]
	ds_read_b128 v[164:167], v209 offset:32768
	s_waitcnt lgkmcnt(4)
	v_mfma_f32_32x32x16_bf16 v[82:97], v[180:183], v[192:195], v[82:97]
	ds_read_b128 v[168:171], v209 offset:36864
	v_mfma_f32_32x32x16_bf16 v[66:81], v[180:183], v[200:203], v[66:81]
	ds_read_b128 v[134:137], v205 offset:36864
	s_waitcnt lgkmcnt(5)
	v_mfma_f32_32x32x16_bf16 v[50:65], v[184:187], v[192:195], v[50:65]
	ds_read_b128 v[138:141], v205 offset:40960
	v_mfma_f32_32x32x16_bf16 v[34:49], v[184:187], v[200:203], v[34:49]
	ds_read_b128 v[160:163], v205 offset:45056
	s_waitcnt lgkmcnt(6)
	v_mfma_f32_32x32x16_bf16 v[18:33], v[188:191], v[192:195], v[18:33]
	v_mfma_f32_32x32x16_bf16 v[2:17], v[188:191], v[200:203], v[2:17]
	s_waitcnt lgkmcnt(4)
	v_mfma_f32_32x32x16_bf16 v[114:129], v[130:133], v[164:167], v[114:129]
	ds_read_b128 v[172:175], v206 offset:32768
	ds_read_b128 v[192:195], v210 offset:32768
	s_waitcnt lgkmcnt(5)
	v_mfma_f32_32x32x16_bf16 v[98:113], v[130:133], v[168:171], v[98:113]
	ds_read_b128 v[200:203], v210 offset:36864
	ds_read_b128 v[180:183], v206 offset:36864
	s_waitcnt lgkmcnt(6)
	v_mfma_f32_32x32x16_bf16 v[82:97], v[134:137], v[164:167], v[82:97]
	ds_read_b128 v[184:187], v206 offset:40960
	ds_read_b128 v[188:191], v206 offset:45056
	v_mfma_f32_32x32x16_bf16 v[66:81], v[134:137], v[168:171], v[66:81]
	s_waitcnt lgkmcnt(7)
	v_mfma_f32_32x32x16_bf16 v[50:65], v[138:141], v[164:167], v[50:65]
	v_mfma_f32_32x32x16_bf16 v[34:49], v[138:141], v[168:171], v[34:49]
	s_waitcnt lgkmcnt(6)
	v_mfma_f32_32x32x16_bf16 v[18:33], v[160:163], v[164:167], v[18:33]
	v_mfma_f32_32x32x16_bf16 v[2:17], v[160:163], v[168:171], v[2:17]
	s_waitcnt vmcnt(0) lgkmcnt(0)
	s_barrier
	v_mfma_f32_32x32x16_bf16 v[114:129], v[172:175], v[192:195], v[114:129]
	v_mfma_f32_32x32x16_bf16 v[98:113], v[172:175], v[200:203], v[98:113]
	v_mfma_f32_32x32x16_bf16 v[82:97], v[180:183], v[192:195], v[82:97]
	v_mfma_f32_32x32x16_bf16 v[66:81], v[180:183], v[200:203], v[66:81]
	v_mfma_f32_32x32x16_bf16 v[50:65], v[184:187], v[192:195], v[50:65]
	v_mfma_f32_32x32x16_bf16 v[34:49], v[184:187], v[200:203], v[34:49]
	v_mfma_f32_32x32x16_bf16 v[18:33], v[188:191], v[192:195], v[18:33]
	v_mfma_f32_32x32x16_bf16 v[2:17], v[188:191], v[200:203], v[2:17]
	v_add_u32_e32 v159, s0, v153
	s_mov_b32 s0, 0x7e07e07f
	v_mul_hi_i32 v0, v159, s0
	v_lshrrev_b32_e32 v133, 31, v0
	v_ashrrev_i32_e32 v0, 13, v0
	v_add_u32_e32 v134, v0, v133
	v_mul_i32_i24_e32 v0, 0x4100, v134
	v_sub_u32_e32 v136, v159, v0
	s_movk_i32 s0, 0x100
	v_cmp_gt_i32_e64 s[56:57], s0, v136
	v_ashrrev_i32_e32 v137, 31, v136
	s_mov_b32 s0, 0xfff00000
	s_waitcnt vmcnt(0)
	v_ashrrev_i32_e32 v130, 7, v159
	v_lshlrev_b64 v[136:137], 12, v[136:137]
	s_mov_b32 s1, -1
	v_or_b32_e32 v132, s4, v154
	v_ashrrev_i32_e32 v131, 31, v130
	v_ashrrev_i32_e32 v135, 31, v134
	v_lshl_add_u64 v[136:137], v[136:137], 0, s[0:1]
	s_movk_i32 s0, 0x1840
	v_lshlrev_b64 v[130:131], 14, v[130:131]
	v_lshlrev_b64 v[134:135], 26, v[134:135]
	v_mov_b32_e32 v161, v179
	v_cmp_gt_i32_e64 s[54:55], s0, v132
	s_barrier
	s_and_saveexec_b64 s[2:3], s[54:55]
	s_cbranch_execz .LBB0_371
	s_movk_i32 s0, 0x7ff
	v_cmp_lt_i32_e32 vcc, s0, v132
	s_xor_b64 s[0:1], s[56:57], -1
	s_or_b64 s[0:1], vcc, s[0:1]
	s_and_b64 exec, exec, s[0:1]
	s_cbranch_execz .LBB0_371
	v_bfe_u32 v0, v161, 5, 1
	v_mul_u32_u24_e32 v0, 0x90, v0
	v_lshlrev_b32_e32 v133, 2, v161
	v_lshlrev_b32_e32 v0, 2, v0
	v_and_b32_e32 v133, 0x7c, v133
	v_add3_u32 v138, v155, v0, v133
	v_add3_u32 v0, v155, v133, v0
	ds_write_b32 v138, v114
	v_add_u32_e32 v114, 0x100, v0
	ds_write2_b32 v114, v117, v118 offset0:44 offset1:224
	v_add_u32_e32 v114, 0x400, v0
	ds_write2_b32 v114, v119, v120 offset0:68 offset1:104
	v_add_u32_e32 v114, 0x600, v0
	ds_write2_b32 v114, v121, v122 offset0:12 offset1:192
	v_add_u32_e32 v114, 0x800, v0
	ds_write2_b32 v114, v123, v124 offset0:100 offset1:136
	v_add_u32_e32 v114, 0xa00, v0
	ds_write2_b32 v114, v125, v126 offset0:44 offset1:224
	v_add_u32_e32 v114, 0xc00, v0
	ds_write2_b32 v0, v115, v116 offset0:36 offset1:72
	ds_write2_b32 v114, v127, v128 offset0:132 offset1:168
	ds_write_b32 v0, v129 offset:3888
	s_waitcnt lgkmcnt(0)
	v_and_b32_e32 v160, 63, v161
	s_and_saveexec_b64 s[0:1], vcc
	s_xor_b64 s[6:7], exec, s[0:1]
	s_cbranch_execz .LBB0_369
	s_cmpk_gt_u32 s4, 0x17ff
	s_mov_b64 s[0:1], -1
	s_cbranch_scc0 .LBB0_365
	v_readlane_b32 s16, v251, 2
	v_lshlrev_b32_e32 v116, 3, v161
	v_add_u32_e32 v0, 0xffffe800, v132
	v_readlane_b32 s17, v251, 3
	v_and_b32_e32 v116, 24, v116
	v_lshlrev_b32_e32 v140, 2, v116
	v_lshl_add_u64 v[114:115], v[0:1], 2, s[16:17]
	v_mov_b32_e32 v141, v1
	v_lshl_add_u64 v[138:139], v[114:115], 0, v[140:141]
	global_load_dwordx4 v[122:125], v[138:139], off
	global_load_dwordx4 v[114:117], v[138:139], off offset:16
	v_add_u32_e32 v162, v155, v140
	v_lshrrev_b32_e32 v133, 2, v160
	s_movk_i32 s0, 0x90
	v_mad_u32_u24 v118, v133, s0, v162
	ds_read_b128 v[126:129], v118
	ds_read_b128 v[118:121], v118 offset:16
	s_mov_b32 s0, 0xbfb8aa3b
	v_readlane_b32 s18, v251, 4
	v_readlane_b32 s19, v251, 5
	v_readlane_b32 s20, v251, 6
	v_readlane_b32 s21, v251, 7
	v_readlane_b32 s22, v251, 8
	v_readlane_b32 s23, v251, 9
	v_readlane_b32 s24, v251, 10
	v_readlane_b32 s25, v251, 11
	v_readlane_b32 s26, v251, 12
	v_readlane_b32 s27, v251, 13
	v_readlane_b32 s28, v251, 14
	v_readlane_b32 s29, v251, 15
	v_readlane_b32 s30, v251, 16
	v_readlane_b32 s31, v251, 17
	s_waitcnt vmcnt(1) lgkmcnt(1)
	v_add_f32_e32 v122, v126, v122
	v_mul_f32_e64 v126, |v122|, s0
	v_exp_f32_e32 v141, v126
	s_mov_b32 s0, 0x3c23d70a
	v_cmp_ngt_f32_e32 vcc, s0, v141
	s_and_saveexec_b64 s[0:1], vcc
	s_xor_b64 s[8:9], exec, s[0:1]
	s_cbranch_execz .LBB0_302
	v_add_f32_e32 v126, 1.0, v141
	s_mov_b32 s0, 0x800000
	v_cmp_gt_f32_e32 vcc, s0, v126
	s_mov_b32 s0, 0x3f317217
	s_nop 0
	v_cndmask_b32_e64 v141, 0, 32, vcc
	v_ldexp_f32 v126, v126, v141
	v_log_f32_e32 v126, v126
	s_nop 0
	v_mul_f32_e32 v141, 0x3f317217, v126
	v_fma_f32 v141, v126, s0, -v141
	v_fmac_f32_e32 v141, 0x3377d1cf, v126
	v_fmac_f32_e32 v141, 0x3f317217, v126
	v_cmp_lt_f32_e64 s[0:1], |v126|, s47
	s_nop 1
	v_cndmask_b32_e64 v126, v126, v141, s[0:1]
	v_cndmask_b32_e32 v141, 0, v238, vcc
	v_sub_f32_e32 v126, v126, v141

.LBB0_908:
	s_add_i32 s2, s7, s8
	s_cmpk_gt_i32 s2, 0x207
	s_mov_b64 s[0:1], -1
	s_cbranch_scc1 .LBB0_907
	s_ashr_i32 s0, s2, 31
	s_lshr_b32 s0, s0, 27
	s_add_i32 s0, s2, s0
	s_ashr_i32 s1, s0, 5
	s_lshl_b32 s1, s1, 3
	s_sub_i32 s3, 0x82, s1
	s_min_u32 s3, s3, 8
	v_cvt_f32_ubyte0_e32 v0, s3
	v_rcp_iflag_f32_e32 v0, v0
	s_sub_i32 s5, 0, s3
	s_andn2_b32 s0, s0, 31
	s_sub_i32 s0, s2, s0
	v_mul_f32_e32 v0, 0x4f7ffffe, v0
	v_cvt_u32_f32_e32 v0, v0
	s_abs_i32 s4, s0
	s_ashr_i32 s2, s0, 31
	s_waitcnt vmcnt(63) expcnt(7) lgkmcnt(15)
	v_readfirstlane_b32 s10, v0
	s_mul_i32 s5, s5, s10
	s_mul_hi_u32 s5, s10, s5
	s_add_i32 s10, s10, s5
	s_mul_hi_u32 s5, s4, s10
	s_mul_i32 s10, s5, s3
	s_sub_i32 s4, s4, s10
	s_add_i32 s10, s5, 1
	s_sub_i32 s11, s4, s3
	s_cmp_ge_u32 s4, s3
	s_cselect_b32 s5, s10, s5
	s_cselect_b32 s4, s11, s4
	s_add_i32 s10, s5, 1
	s_cmp_ge_u32 s4, s3
	s_cselect_b32 s4, s10, s5
	s_xor_b32 s4, s4, s2
	s_sub_i32 s2, s4, s2
	s_mul_i32 s3, s2, s3
	s_sub_i32 s0, s0, s3
	s_add_i32 s0, s0, s1
	s_lshl_b32 s0, s0, 8
	s_lshl_b32 s2, s2, 8
	s_ashr_i32 s1, s0, 31
	s_ashr_i32 s3, s2, 31
	s_lshl_b64 s[4:5], s[0:1], 11
	s_lshl_b64 s[10:11], s[2:3], 11
	s_add_u32 s12, s64, s4
	v_mov_b32_e32 v0, v132
	s_addc_u32 s13, s65, s5
	s_barrier
	v_readlane_b32 s14, v251, 50
	v_lshl_add_u64 v[2:3], v[0:1], 1, s[12:13]
	v_add_u32_e32 v0, 32, v133
	v_readlane_b32 s15, v251, 51
	v_readfirstlane_b32 s1, v0
	s_mov_b32 m0, s1
	v_mov_b32_e32 v0, v134
	global_load_lds_dwordx4 v[2:3], off
	s_add_u32 s14, s14, s10
	v_lshl_add_u64 v[2:3], v[0:1], 1, s[12:13]
	v_add_u32_e32 v0, 32, v135
	s_addc_u32 s15, s15, s11
	v_readfirstlane_b32 s1, v0
	s_mov_b32 m0, s1
	v_mov_b32_e32 v0, v136
	global_load_lds_dwordx4 v[2:3], off
	v_readlane_b32 s3, v254, 3
	v_lshl_add_u64 v[2:3], v[0:1], 1, s[12:13]
	v_add_u32_e32 v0, 32, v137
	s_mov_b32 s9, 0
	v_readfirstlane_b32 s1, v0
	s_mov_b32 m0, s1
	v_mov_b32_e32 v0, v138
	global_load_lds_dwordx4 v[2:3], off
	s_nop 0
	v_lshl_add_u64 v[2:3], v[0:1], 1, s[12:13]
	v_add_u32_e32 v0, 32, v139
	s_nop 0
	v_readfirstlane_b32 s1, v0
	s_mov_b32 m0, s1
	v_mov_b32_e32 v0, v132
	global_load_lds_dwordx4 v[2:3], off
	s_nop 0
	v_lshl_add_u64 v[2:3], v[0:1], 1, s[14:15]
	v_add_u32_e32 v0, s3, v133
	s_nop 0
	v_readfirstlane_b32 s1, v0
	s_mov_b32 m0, s1
	v_mov_b32_e32 v0, v134
	global_load_lds_dwordx4 v[2:3], off
	s_nop 0
	v_lshl_add_u64 v[2:3], v[0:1], 1, s[14:15]
	v_add_u32_e32 v0, s3, v135
	s_nop 0
	v_readfirstlane_b32 s1, v0
	s_mov_b32 m0, s1
	v_mov_b32_e32 v0, v136
	global_load_lds_dwordx4 v[2:3], off
	s_nop 0
	v_lshl_add_u64 v[2:3], v[0:1], 1, s[14:15]
	v_add_u32_e32 v0, s3, v137
	s_nop 0
	v_readfirstlane_b32 s1, v0
	s_mov_b32 m0, s1
	v_mov_b32_e32 v0, v138
	global_load_lds_dwordx4 v[2:3], off
	s_nop 0
	v_lshl_add_u64 v[2:3], v[0:1], 1, s[14:15]
	v_add_u32_e32 v0, s3, v139
	v_readlane_b32 s3, v253, 26
	v_readfirstlane_b32 s1, v0
	s_mov_b32 m0, s1
	v_readlane_b32 s1, v253, 25
	global_load_lds_dwordx4 v[2:3], off
	s_add_u32 s1, s1, s4
	s_waitcnt vmcnt(0)
	s_addc_u32 s3, s3, s5
	v_readlane_b32 s4, v253, 34
	s_add_u32 s10, s4, s10
	v_readlane_b32 s4, v253, 35
	v_mov_b32_e32 v2, 0
	s_addc_u32 s11, s4, s11
	s_mov_b64 s[4:5], 0
	v_mov_b32_e32 v3, v2
	v_mov_b32_e32 v4, v2
	v_mov_b32_e32 v5, v2
	v_mov_b32_e32 v6, v2
	v_mov_b32_e32 v7, v2
	v_mov_b32_e32 v8, v2
	v_mov_b32_e32 v9, v2
	v_mov_b32_e32 v10, v2
	v_mov_b32_e32 v11, v2
	v_mov_b32_e32 v12, v2
	v_mov_b32_e32 v13, v2
	s_waitcnt vmcnt(0)
	v_mov_b32_e32 v14, v2
	v_mov_b32_e32 v15, v2
	v_mov_b32_e32 v16, v2
	v_mov_b32_e32 v17, v2
	v_mov_b32_e32 v18, v2
	v_mov_b32_e32 v19, v2
	v_mov_b32_e32 v20, v2
	v_mov_b32_e32 v21, v2
	v_mov_b32_e32 v22, v2
	v_mov_b32_e32 v23, v2
	v_mov_b32_e32 v24, v2
	v_mov_b32_e32 v25, v2
	v_mov_b32_e32 v26, v2
	v_mov_b32_e32 v27, v2
	v_mov_b32_e32 v28, v2
	v_mov_b32_e32 v29, v2
	v_mov_b32_e32 v30, v2
	v_mov_b32_e32 v31, v2
	v_mov_b32_e32 v32, v2
	v_mov_b32_e32 v33, v2
	v_mov_b32_e32 v34, v2
	v_mov_b32_e32 v35, v2
	v_mov_b32_e32 v36, v2
	v_mov_b32_e32 v37, v2
	v_mov_b32_e32 v38, v2
	v_mov_b32_e32 v39, v2
	v_mov_b32_e32 v40, v2
	v_mov_b32_e32 v41, v2
	v_mov_b32_e32 v42, v2
	v_mov_b32_e32 v43, v2
	v_mov_b32_e32 v44, v2
	v_mov_b32_e32 v45, v2
	v_mov_b32_e32 v46, v2
	v_mov_b32_e32 v47, v2
	v_mov_b32_e32 v48, v2
	v_mov_b32_e32 v49, v2
	v_mov_b32_e32 v50, v2
	v_mov_b32_e32 v51, v2
	v_mov_b32_e32 v52, v2
	v_mov_b32_e32 v53, v2
	v_mov_b32_e32 v54, v2
	v_mov_b32_e32 v55, v2
	v_mov_b32_e32 v56, v2
	v_mov_b32_e32 v57, v2
	v_mov_b32_e32 v58, v2
	v_mov_b32_e32 v59, v2
	v_mov_b32_e32 v60, v2
	v_mov_b32_e32 v61, v2
	v_mov_b32_e32 v62, v2
	v_mov_b32_e32 v63, v2
	v_mov_b32_e32 v64, v2
	v_mov_b32_e32 v65, v2
	v_mov_b32_e32 v66, v2
	v_mov_b32_e32 v67, v2
	v_mov_b32_e32 v68, v2
	v_mov_b32_e32 v69, v2
	v_mov_b32_e32 v70, v2
	v_mov_b32_e32 v71, v2
	v_mov_b32_e32 v72, v2
	v_mov_b32_e32 v73, v2
	v_mov_b32_e32 v74, v2
	v_mov_b32_e32 v75, v2
	v_mov_b32_e32 v76, v2
	v_mov_b32_e32 v77, v2
	v_mov_b32_e32 v78, v2
	v_mov_b32_e32 v79, v2
	v_mov_b32_e32 v80, v2
	v_mov_b32_e32 v81, v2
	v_mov_b32_e32 v82, v2
	v_mov_b32_e32 v83, v2
	v_mov_b32_e32 v84, v2
	v_mov_b32_e32 v85, v2
	v_mov_b32_e32 v86, v2
	v_mov_b32_e32 v87, v2
	v_mov_b32_e32 v88, v2
	v_mov_b32_e32 v89, v2
	v_mov_b32_e32 v90, v2
	v_mov_b32_e32 v91, v2
	v_mov_b32_e32 v92, v2
	v_mov_b32_e32 v93, v2
	v_mov_b32_e32 v94, v2
	v_mov_b32_e32 v95, v2
	v_mov_b32_e32 v96, v2
	v_mov_b32_e32 v97, v2
	v_mov_b32_e32 v98, v2
	v_mov_b32_e32 v99, v2
	v_mov_b32_e32 v100, v2
	v_mov_b32_e32 v101, v2
	v_mov_b32_e32 v102, v2
	v_mov_b32_e32 v103, v2
	v_mov_b32_e32 v104, v2
	v_mov_b32_e32 v105, v2
	v_mov_b32_e32 v106, v2
	v_mov_b32_e32 v107, v2
	v_mov_b32_e32 v108, v2
	v_mov_b32_e32 v109, v2
	v_mov_b32_e32 v110, v2
	v_mov_b32_e32 v111, v2
	v_mov_b32_e32 v112, v2
	v_mov_b32_e32 v113, v2
	v_mov_b32_e32 v114, v2
	v_mov_b32_e32 v115, v2
	v_mov_b32_e32 v116, v2
	v_mov_b32_e32 v117, v2
	v_mov_b32_e32 v118, v2
	v_mov_b32_e32 v119, v2
	v_mov_b32_e32 v120, v2
	v_mov_b32_e32 v121, v2
	v_mov_b32_e32 v122, v2
	v_mov_b32_e32 v123, v2
	v_mov_b32_e32 v124, v2
	v_mov_b32_e32 v125, v2
	v_mov_b32_e32 v126, v2
	v_mov_b32_e32 v127, v2
	v_mov_b32_e32 v128, v2
	v_mov_b32_e32 v129, v2
	s_waitcnt lgkmcnt(0)
	s_barrier
	v_lshlrev_b32_e32 v149, 1, v132
	v_readfirstlane_b32 s14, v133
	v_add_u32_e32 v205, v140, v142
	v_add_u32_e32 v209, v141, v142
	v_add_u32_e32 v206, v140, v146
	v_add_u32_e32 v210, v141, v146
	v_add_u32_e32 v207, v140, v147
	v_add_u32_e32 v211, v141, v147
	v_add_u32_e32 v208, v140, v148
	v_add_u32_e32 v212, v141, v148
	s_mov_b32 s9, 7
	s_add_u32 m0, s14, 0x8020
	s_add_u32 s12, s1, s4
	s_addc_u32 s13, s3, s5
	global_load_lds_dwordx4 v149, s[12:13]
	s_add_u32 m0, s14, 0xa020
	s_add_u32 s12, s12, 0x20000
	s_addc_u32 s13, s13, 0
	global_load_lds_dwordx4 v149, s[12:13]
	s_add_u32 m0, s14, 0xc020
	s_add_u32 s12, s12, 0x20000
	s_addc_u32 s13, s13, 0
	global_load_lds_dwordx4 v149, s[12:13]
	s_add_u32 m0, s14, 0xe020
	s_add_u32 s12, s12, 0x20000
	s_addc_u32 s13, s13, 0
	global_load_lds_dwordx4 v149, s[12:13]
	ds_read_b128 v[150:153], v205 offset:0
	ds_read_b128 v[166:169], v209 offset:0
	ds_read_b128 v[170:173], v209 offset:4096
	ds_read_b128 v[154:157], v205 offset:4096
	ds_read_b128 v[158:161], v205 offset:8192
	ds_read_b128 v[162:165], v205 offset:12288
.Lg910_loop:
	s_waitcnt lgkmcnt(4)
	v_mfma_f32_32x32x16_bf16 v[114:129], v[150:153], v[166:169], v[114:129]
	ds_read_b128 v[174:177], v206 offset:0
	s_waitcnt lgkmcnt(4)
	v_mfma_f32_32x32x16_bf16 v[98:113], v[150:153], v[170:173], v[98:113]
	ds_read_b128 v[192:195], v210 offset:0
	s_add_u32 m0, s14, 0x18020
	s_add_u32 s12, s10, s4
	s_addc_u32 s13, s11, s5
	global_load_lds_dwordx4 v149, s[12:13]
	s_waitcnt lgkmcnt(4)
	v_mfma_f32_32x32x16_bf16 v[82:97], v[154:157], v[166:169], v[82:97]
	ds_read_b128 v[200:203], v210 offset:4096
	v_mfma_f32_32x32x16_bf16 v[66:81], v[154:157], v[170:173], v[66:81]
	ds_read_b128 v[180:183], v206 offset:4096
	s_add_u32 m0, s14, 0x1a020
	s_add_u32 s12, s12, 0x20000
	s_addc_u32 s13, s13, 0
	global_load_lds_dwordx4 v149, s[12:13]
	s_waitcnt lgkmcnt(5)
	v_mfma_f32_32x32x16_bf16 v[50:65], v[158:161], v[166:169], v[50:65]
	ds_read_b128 v[184:187], v206 offset:8192
	v_mfma_f32_32x32x16_bf16 v[34:49], v[158:161], v[170:173], v[34:49]
	ds_read_b128 v[188:191], v206 offset:12288
	s_add_u32 m0, s14, 0x1c020
	s_add_u32 s12, s12, 0x20000
	s_addc_u32 s13, s13, 0
	global_load_lds_dwordx4 v149, s[12:13]
	s_waitcnt lgkmcnt(6)
	v_mfma_f32_32x32x16_bf16 v[18:33], v[162:165], v[166:169], v[18:33]
	v_mfma_f32_32x32x16_bf16 v[2:17], v[162:165], v[170:173], v[2:17]
	s_add_u32 m0, s14, 0x1e020
	s_add_u32 s12, s12, 0x20000
	s_addc_u32 s13, s13, 0
	global_load_lds_dwordx4 v149, s[12:13]
	s_add_u32 s4, s4, 0x80
	s_addc_u32 s5, s5, 0
	s_waitcnt lgkmcnt(4)
	v_mfma_f32_32x32x16_bf16 v[114:129], v[174:177], v[192:195], v[114:129]
	ds_read_b128 v[150:153], v207 offset:0
	s_waitcnt lgkmcnt(4)
	v_mfma_f32_32x32x16_bf16 v[98:113], v[174:177], v[200:203], v[98:113]
	ds_read_b128 v[166:169], v211 offset:0
	s_waitcnt lgkmcnt(4)
	v_mfma_f32_32x32x16_bf16 v[82:97], v[180:183], v[192:195], v[82:97]
	ds_read_b128 v[170:173], v211 offset:4096
	v_mfma_f32_32x32x16_bf16 v[66:81], v[180:183], v[200:203], v[66:81]
	ds_read_b128 v[154:157], v207 offset:4096
	s_waitcnt lgkmcnt(5)
	v_mfma_f32_32x32x16_bf16 v[50:65], v[184:187], v[192:195], v[50:65]
	ds_read_b128 v[158:161], v207 offset:8192
	v_mfma_f32_32x32x16_bf16 v[34:49], v[184:187], v[200:203], v[34:49]
	ds_read_b128 v[162:165], v207 offset:12288
	s_waitcnt lgkmcnt(6)
	v_mfma_f32_32x32x16_bf16 v[18:33], v[188:191], v[192:195], v[18:33]
	v_mfma_f32_32x32x16_bf16 v[2:17], v[188:191], v[200:203], v[2:17]
	s_waitcnt lgkmcnt(4)
	v_mfma_f32_32x32x16_bf16 v[114:129], v[150:153], v[166:169], v[114:129]
	ds_read_b128 v[174:177], v208 offset:0
	ds_read_b128 v[192:195], v212 offset:0
	s_waitcnt lgkmcnt(5)
	v_mfma_f32_32x32x16_bf16 v[98:113], v[150:153], v[170:173], v[98:113]
	ds_read_b128 v[200:203], v212 offset:4096
	ds_read_b128 v[180:183], v208 offset:4096
	s_waitcnt lgkmcnt(6)
	v_mfma_f32_32x32x16_bf16 v[82:97], v[154:157], v[166:169], v[82:97]
	ds_read_b128 v[184:187], v208 offset:8192
	ds_read_b128 v[188:191], v208 offset:12288
	v_mfma_f32_32x32x16_bf16 v[66:81], v[154:157], v[170:173], v[66:81]
	s_waitcnt lgkmcnt(7)
	v_mfma_f32_32x32x16_bf16 v[50:65], v[158:161], v[166:169], v[50:65]
	v_mfma_f32_32x32x16_bf16 v[34:49], v[158:161], v[170:173], v[34:49]
	s_waitcnt lgkmcnt(6)
	v_mfma_f32_32x32x16_bf16 v[18:33], v[162:165], v[166:169], v[18:33]
	v_mfma_f32_32x32x16_bf16 v[2:17], v[162:165], v[170:173], v[2:17]
	s_waitcnt vmcnt(0) lgkmcnt(0)
	s_barrier
	v_mfma_f32_32x32x16_bf16 v[114:129], v[174:177], v[192:195], v[114:129]
	ds_read_b128 v[150:153], v205 offset:32768
	v_mfma_f32_32x32x16_bf16 v[98:113], v[174:177], v[200:203], v[98:113]
	ds_read_b128 v[166:169], v209 offset:32768
	s_add_u32 m0, s14, 0x20
	s_add_u32 s12, s1, s4
	s_addc_u32 s13, s3, s5
	global_load_lds_dwordx4 v149, s[12:13]
	v_mfma_f32_32x32x16_bf16 v[82:97], v[180:183], v[192:195], v[82:97]
	ds_read_b128 v[170:173], v209 offset:36864
	v_mfma_f32_32x32x16_bf16 v[66:81], v[180:183], v[200:203], v[66:81]
	ds_read_b128 v[154:157], v205 offset:36864
	s_add_u32 m0, s14, 0x2020
	s_add_u32 s12, s12, 0x20000
	s_addc_u32 s13, s13, 0
	global_load_lds_dwordx4 v149, s[12:13]
	v_mfma_f32_32x32x16_bf16 v[50:65], v[184:187], v[192:195], v[50:65]
	ds_read_b128 v[158:161], v205 offset:40960
	v_mfma_f32_32x32x16_bf16 v[34:49], v[184:187], v[200:203], v[34:49]
	ds_read_b128 v[162:165], v205 offset:45056
	s_add_u32 m0, s14, 0x4020
	s_add_u32 s12, s12, 0x20000
	s_addc_u32 s13, s13, 0
	global_load_lds_dwordx4 v149, s[12:13]
	v_mfma_f32_32x32x16_bf16 v[18:33], v[188:191], v[192:195], v[18:33]
	v_mfma_f32_32x32x16_bf16 v[2:17], v[188:191], v[200:203], v[2:17]
	s_add_u32 m0, s14, 0x6020
	s_add_u32 s12, s12, 0x20000
	s_addc_u32 s13, s13, 0
	global_load_lds_dwordx4 v149, s[12:13]
	s_waitcnt lgkmcnt(4)
	v_mfma_f32_32x32x16_bf16 v[114:129], v[150:153], v[166:169], v[114:129]
	ds_read_b128 v[174:177], v206 offset:32768
	s_waitcnt lgkmcnt(4)
	v_mfma_f32_32x32x16_bf16 v[98:113], v[150:153], v[170:173], v[98:113]
	ds_read_b128 v[192:195], v210 offset:32768
	s_add_u32 m0, s14, 0x10020
	s_add_u32 s12, s10, s4
	s_addc_u32 s13, s11, s5
	global_load_lds_dwordx4 v149, s[12:13]
	s_waitcnt lgkmcnt(4)
	v_mfma_f32_32x32x16_bf16 v[82:97], v[154:157], v[166:169], v[82:97]
	ds_read_b128 v[200:203], v210 offset:36864
	v_mfma_f32_32x32x16_bf16 v[66:81], v[154:157], v[170:173], v[66:81]
	ds_read_b128 v[180:183], v206 offset:36864
	s_add_u32 m0, s14, 0x12020
	s_add_u32 s12, s12, 0x20000
	s_addc_u32 s13, s13, 0
	global_load_lds_dwordx4 v149, s[12:13]
	s_waitcnt lgkmcnt(5)
	v_mfma_f32_32x32x16_bf16 v[50:65], v[158:161], v[166:169], v[50:65]
	ds_read_b128 v[184:187], v206 offset:40960
	v_mfma_f32_32x32x16_bf16 v[34:49], v[158:161], v[170:173], v[34:49]
	ds_read_b128 v[188:191], v206 offset:45056
	s_add_u32 m0, s14, 0x14020
	s_add_u32 s12, s12, 0x20000
	s_addc_u32 s13, s13, 0
	global_load_lds_dwordx4 v149, s[12:13]
	s_waitcnt lgkmcnt(6)
	v_mfma_f32_32x32x16_bf16 v[18:33], v[162:165], v[166:169], v[18:33]
	v_mfma_f32_32x32x16_bf16 v[2:17], v[162:165], v[170:173], v[2:17]
	s_add_u32 m0, s14, 0x16020
	s_add_u32 s12, s12, 0x20000
	s_addc_u32 s13, s13, 0
	global_load_lds_dwordx4 v149, s[12:13]
	s_add_u32 s4, s4, 0x80
	s_addc_u32 s5, s5, 0
	s_waitcnt lgkmcnt(4)
	v_mfma_f32_32x32x16_bf16 v[114:129], v[174:177], v[192:195], v[114:129]
	ds_read_b128 v[150:153], v207 offset:32768
	s_waitcnt lgkmcnt(4)
	v_mfma_f32_32x32x16_bf16 v[98:113], v[174:177], v[200:203], v[98:113]
	ds_read_b128 v[166:169], v211 offset:32768
	s_waitcnt lgkmcnt(4)
	v_mfma_f32_32x32x16_bf16 v[82:97], v[180:183], v[192:195], v[82:97]
	ds_read_b128 v[170:173], v211 offset:36864
	v_mfma_f32_32x32x16_bf16 v[66:81], v[180:183], v[200:203], v[66:81]
	ds_read_b128 v[154:157], v207 offset:36864
	s_waitcnt lgkmcnt(5)
	v_mfma_f32_32x32x16_bf16 v[50:65], v[184:187], v[192:195], v[50:65]
	ds_read_b128 v[158:161], v207 offset:40960
	v_mfma_f32_32x32x16_bf16 v[34:49], v[184:187], v[200:203], v[34:49]
	ds_read_b128 v[162:165], v207 offset:45056
	s_waitcnt lgkmcnt(6)
	v_mfma_f32_32x32x16_bf16 v[18:33], v[188:191], v[192:195], v[18:33]
	v_mfma_f32_32x32x16_bf16 v[2:17], v[188:191], v[200:203], v[2:17]
	s_waitcnt lgkmcnt(4)
	v_mfma_f32_32x32x16_bf16 v[114:129], v[150:153], v[166:169], v[114:129]
	ds_read_b128 v[174:177], v208 offset:32768
	ds_read_b128 v[192:195], v212 offset:32768
	s_waitcnt lgkmcnt(5)
	v_mfma_f32_32x32x16_bf16 v[98:113], v[150:153], v[170:173], v[98:113]
	ds_read_b128 v[200:203], v212 offset:36864
	ds_read_b128 v[180:183], v208 offset:36864
	s_waitcnt lgkmcnt(6)
	v_mfma_f32_32x32x16_bf16 v[82:97], v[154:157], v[166:169], v[82:97]
	ds_read_b128 v[184:187], v208 offset:40960
	ds_read_b128 v[188:191], v208 offset:45056
	v_mfma_f32_32x32x16_bf16 v[66:81], v[154:157], v[170:173], v[66:81]
	s_waitcnt lgkmcnt(7)
	v_mfma_f32_32x32x16_bf16 v[50:65], v[158:161], v[166:169], v[50:65]
	v_mfma_f32_32x32x16_bf16 v[34:49], v[158:161], v[170:173], v[34:49]
	s_waitcnt lgkmcnt(6)
	v_mfma_f32_32x32x16_bf16 v[18:33], v[162:165], v[166:169], v[18:33]
	v_mfma_f32_32x32x16_bf16 v[2:17], v[162:165], v[170:173], v[2:17]
	s_waitcnt vmcnt(0) lgkmcnt(0)
	s_barrier
	v_mfma_f32_32x32x16_bf16 v[114:129], v[174:177], v[192:195], v[114:129]
	ds_read_b128 v[150:153], v205 offset:0
	v_mfma_f32_32x32x16_bf16 v[98:113], v[174:177], v[200:203], v[98:113]
	ds_read_b128 v[166:169], v209 offset:0
	s_add_u32 m0, s14, 0x8020
	s_add_u32 s12, s1, s4
	s_addc_u32 s13, s3, s5
	global_load_lds_dwordx4 v149, s[12:13]
	v_mfma_f32_32x32x16_bf16 v[82:97], v[180:183], v[192:195], v[82:97]
	ds_read_b128 v[170:173], v209 offset:4096
	v_mfma_f32_32x32x16_bf16 v[66:81], v[180:183], v[200:203], v[66:81]
	ds_read_b128 v[154:157], v205 offset:4096
	s_add_u32 m0, s14, 0xa020
	s_add_u32 s12, s12, 0x20000
	s_addc_u32 s13, s13, 0
	global_load_lds_dwordx4 v149, s[12:13]
	v_mfma_f32_32x32x16_bf16 v[50:65], v[184:187], v[192:195], v[50:65]
	ds_read_b128 v[158:161], v205 offset:8192
	v_mfma_f32_32x32x16_bf16 v[34:49], v[184:187], v[200:203], v[34:49]
	ds_read_b128 v[162:165], v205 offset:12288
	s_add_u32 m0, s14, 0xc020
	s_add_u32 s12, s12, 0x20000
	s_addc_u32 s13, s13, 0
	global_load_lds_dwordx4 v149, s[12:13]
	v_mfma_f32_32x32x16_bf16 v[18:33], v[188:191], v[192:195], v[18:33]
	v_mfma_f32_32x32x16_bf16 v[2:17], v[188:191], v[200:203], v[2:17]
	s_add_u32 m0, s14, 0xe020
	s_add_u32 s12, s12, 0x20000
	s_addc_u32 s13, s13, 0
	global_load_lds_dwordx4 v149, s[12:13]
	s_sub_u32 s9, s9, 1
	s_cmp_lg_u32 s9, 0
	s_cbranch_scc1 .Lg910_loop
	s_waitcnt lgkmcnt(4)
	v_mfma_f32_32x32x16_bf16 v[114:129], v[150:153], v[166:169], v[114:129]
	ds_read_b128 v[174:177], v206 offset:0
	s_waitcnt lgkmcnt(4)
	v_mfma_f32_32x32x16_bf16 v[98:113], v[150:153], v[170:173], v[98:113]
	ds_read_b128 v[192:195], v210 offset:0
	s_add_u32 m0, s14, 0x18020
	s_add_u32 s12, s10, s4
	s_addc_u32 s13, s11, s5
	global_load_lds_dwordx4 v149, s[12:13]
	s_waitcnt lgkmcnt(4)
	v_mfma_f32_32x32x16_bf16 v[82:97], v[154:157], v[166:169], v[82:97]
	ds_read_b128 v[200:203], v210 offset:4096
	v_mfma_f32_32x32x16_bf16 v[66:81], v[154:157], v[170:173], v[66:81]
	ds_read_b128 v[180:183], v206 offset:4096
	s_add_u32 m0, s14, 0x1a020
	s_add_u32 s12, s12, 0x20000
	s_addc_u32 s13, s13, 0
	global_load_lds_dwordx4 v149, s[12:13]
	s_waitcnt lgkmcnt(5)
	v_mfma_f32_32x32x16_bf16 v[50:65], v[158:161], v[166:169], v[50:65]
	ds_read_b128 v[184:187], v206 offset:8192
	v_mfma_f32_32x32x16_bf16 v[34:49], v[158:161], v[170:173], v[34:49]
	ds_read_b128 v[188:191], v206 offset:12288
	s_add_u32 m0, s14, 0x1c020
	s_add_u32 s12, s12, 0x20000
	s_addc_u32 s13, s13, 0
	global_load_lds_dwordx4 v149, s[12:13]
	s_waitcnt lgkmcnt(6)
	v_mfma_f32_32x32x16_bf16 v[18:33], v[162:165], v[166:169], v[18:33]
	v_mfma_f32_32x32x16_bf16 v[2:17], v[162:165], v[170:173], v[2:17]
	s_add_u32 m0, s14, 0x1e020
	s_add_u32 s12, s12, 0x20000
	s_addc_u32 s13, s13, 0
	global_load_lds_dwordx4 v149, s[12:13]
	s_add_u32 s4, s4, 0x80
	s_addc_u32 s5, s5, 0
	s_waitcnt lgkmcnt(4)
	v_mfma_f32_32x32x16_bf16 v[114:129], v[174:177], v[192:195], v[114:129]
	ds_read_b128 v[150:153], v207 offset:0
	s_waitcnt lgkmcnt(4)
	v_mfma_f32_32x32x16_bf16 v[98:113], v[174:177], v[200:203], v[98:113]
	ds_read_b128 v[166:169], v211 offset:0
	s_waitcnt lgkmcnt(4)
	v_mfma_f32_32x32x16_bf16 v[82:97], v[180:183], v[192:195], v[82:97]
	ds_read_b128 v[170:173], v211 offset:4096
	v_mfma_f32_32x32x16_bf16 v[66:81], v[180:183], v[200:203], v[66:81]
	ds_read_b128 v[154:157], v207 offset:4096
	s_waitcnt lgkmcnt(5)
	v_mfma_f32_32x32x16_bf16 v[50:65], v[184:187], v[192:195], v[50:65]
	ds_read_b128 v[158:161], v207 offset:8192
	v_mfma_f32_32x32x16_bf16 v[34:49], v[184:187], v[200:203], v[34:49]
	ds_read_b128 v[162:165], v207 offset:12288
	s_waitcnt lgkmcnt(6)
	v_mfma_f32_32x32x16_bf16 v[18:33], v[188:191], v[192:195], v[18:33]
	v_mfma_f32_32x32x16_bf16 v[2:17], v[188:191], v[200:203], v[2:17]
	s_waitcnt lgkmcnt(4)
	v_mfma_f32_32x32x16_bf16 v[114:129], v[150:153], v[166:169], v[114:129]
	ds_read_b128 v[174:177], v208 offset:0
	ds_read_b128 v[192:195], v212 offset:0
	s_waitcnt lgkmcnt(5)
	v_mfma_f32_32x32x16_bf16 v[98:113], v[150:153], v[170:173], v[98:113]
	ds_read_b128 v[200:203], v212 offset:4096
	ds_read_b128 v[180:183], v208 offset:4096
	s_waitcnt lgkmcnt(6)
	v_mfma_f32_32x32x16_bf16 v[82:97], v[154:157], v[166:169], v[82:97]
	ds_read_b128 v[184:187], v208 offset:8192
	ds_read_b128 v[188:191], v208 offset:12288
	v_mfma_f32_32x32x16_bf16 v[66:81], v[154:157], v[170:173], v[66:81]
	s_waitcnt lgkmcnt(7)
	v_mfma_f32_32x32x16_bf16 v[50:65], v[158:161], v[166:169], v[50:65]
	v_mfma_f32_32x32x16_bf16 v[34:49], v[158:161], v[170:173], v[34:49]
	s_waitcnt lgkmcnt(6)
	v_mfma_f32_32x32x16_bf16 v[18:33], v[162:165], v[166:169], v[18:33]
	v_mfma_f32_32x32x16_bf16 v[2:17], v[162:165], v[170:173], v[2:17]
	s_waitcnt vmcnt(0) lgkmcnt(0)
	s_barrier
	v_mfma_f32_32x32x16_bf16 v[114:129], v[174:177], v[192:195], v[114:129]
	ds_read_b128 v[150:153], v205 offset:32768
	v_mfma_f32_32x32x16_bf16 v[98:113], v[174:177], v[200:203], v[98:113]
	ds_read_b128 v[166:169], v209 offset:32768
	v_mfma_f32_32x32x16_bf16 v[82:97], v[180:183], v[192:195], v[82:97]
	ds_read_b128 v[170:173], v209 offset:36864
	v_mfma_f32_32x32x16_bf16 v[66:81], v[180:183], v[200:203], v[66:81]
	ds_read_b128 v[154:157], v205 offset:36864
	v_mfma_f32_32x32x16_bf16 v[50:65], v[184:187], v[192:195], v[50:65]
	ds_read_b128 v[158:161], v205 offset:40960
	v_mfma_f32_32x32x16_bf16 v[34:49], v[184:187], v[200:203], v[34:49]
	ds_read_b128 v[162:165], v205 offset:45056
	v_mfma_f32_32x32x16_bf16 v[18:33], v[188:191], v[192:195], v[18:33]
	v_mfma_f32_32x32x16_bf16 v[2:17], v[188:191], v[200:203], v[2:17]
	s_waitcnt lgkmcnt(4)
	v_mfma_f32_32x32x16_bf16 v[114:129], v[150:153], v[166:169], v[114:129]
	ds_read_b128 v[174:177], v206 offset:32768
	s_waitcnt lgkmcnt(4)
	v_mfma_f32_32x32x16_bf16 v[98:113], v[150:153], v[170:173], v[98:113]
	ds_read_b128 v[192:195], v210 offset:32768
	s_waitcnt lgkmcnt(4)
	v_mfma_f32_32x32x16_bf16 v[82:97], v[154:157], v[166:169], v[82:97]
	ds_read_b128 v[200:203], v210 offset:36864
	v_mfma_f32_32x32x16_bf16 v[66:81], v[154:157], v[170:173], v[66:81]
	ds_read_b128 v[180:183], v206 offset:36864
	s_waitcnt lgkmcnt(5)
	v_mfma_f32_32x32x16_bf16 v[50:65], v[158:161], v[166:169], v[50:65]
	ds_read_b128 v[184:187], v206 offset:40960
	v_mfma_f32_32x32x16_bf16 v[34:49], v[158:161], v[170:173], v[34:49]
	ds_read_b128 v[188:191], v206 offset:45056
	s_waitcnt lgkmcnt(6)
	v_mfma_f32_32x32x16_bf16 v[18:33], v[162:165], v[166:169], v[18:33]
	v_mfma_f32_32x32x16_bf16 v[2:17], v[162:165], v[170:173], v[2:17]
	s_waitcnt lgkmcnt(4)
	v_mfma_f32_32x32x16_bf16 v[114:129], v[174:177], v[192:195], v[114:129]
	ds_read_b128 v[150:153], v207 offset:32768
	s_waitcnt lgkmcnt(4)
	v_mfma_f32_32x32x16_bf16 v[98:113], v[174:177], v[200:203], v[98:113]
	ds_read_b128 v[166:169], v211 offset:32768
	s_waitcnt lgkmcnt(4)
	v_mfma_f32_32x32x16_bf16 v[82:97], v[180:183], v[192:195], v[82:97]
	ds_read_b128 v[170:173], v211 offset:36864
	v_mfma_f32_32x32x16_bf16 v[66:81], v[180:183], v[200:203], v[66:81]
	ds_read_b128 v[154:157], v207 offset:36864
	s_waitcnt lgkmcnt(5)
	v_mfma_f32_32x32x16_bf16 v[50:65], v[184:187], v[192:195], v[50:65]
	ds_read_b128 v[158:161], v207 offset:40960
	v_mfma_f32_32x32x16_bf16 v[34:49], v[184:187], v[200:203], v[34:49]
	ds_read_b128 v[162:165], v207 offset:45056
	s_waitcnt lgkmcnt(6)
	v_mfma_f32_32x32x16_bf16 v[18:33], v[188:191], v[192:195], v[18:33]
	v_mfma_f32_32x32x16_bf16 v[2:17], v[188:191], v[200:203], v[2:17]
	s_waitcnt lgkmcnt(4)
	v_mfma_f32_32x32x16_bf16 v[114:129], v[150:153], v[166:169], v[114:129]
	ds_read_b128 v[174:177], v208 offset:32768
	ds_read_b128 v[192:195], v212 offset:32768
	s_waitcnt lgkmcnt(5)
	v_mfma_f32_32x32x16_bf16 v[98:113], v[150:153], v[170:173], v[98:113]
	ds_read_b128 v[200:203], v212 offset:36864
	ds_read_b128 v[180:183], v208 offset:36864
	s_waitcnt lgkmcnt(6)
	v_mfma_f32_32x32x16_bf16 v[82:97], v[154:157], v[166:169], v[82:97]
	ds_read_b128 v[184:187], v208 offset:40960
	ds_read_b128 v[188:191], v208 offset:45056
	v_mfma_f32_32x32x16_bf16 v[66:81], v[154:157], v[170:173], v[66:81]
	s_waitcnt lgkmcnt(7)
	v_mfma_f32_32x32x16_bf16 v[50:65], v[158:161], v[166:169], v[50:65]
	v_mfma_f32_32x32x16_bf16 v[34:49], v[158:161], v[170:173], v[34:49]
	s_waitcnt lgkmcnt(6)
	v_mfma_f32_32x32x16_bf16 v[18:33], v[162:165], v[166:169], v[18:33]
	v_mfma_f32_32x32x16_bf16 v[2:17], v[162:165], v[170:173], v[2:17]
	s_waitcnt vmcnt(0) lgkmcnt(0)
	s_barrier
	v_mfma_f32_32x32x16_bf16 v[114:129], v[174:177], v[192:195], v[114:129]
	v_mfma_f32_32x32x16_bf16 v[98:113], v[174:177], v[200:203], v[98:113]
	v_mfma_f32_32x32x16_bf16 v[82:97], v[180:183], v[192:195], v[82:97]
	v_mfma_f32_32x32x16_bf16 v[66:81], v[180:183], v[200:203], v[66:81]
	v_mfma_f32_32x32x16_bf16 v[50:65], v[184:187], v[192:195], v[50:65]
	v_mfma_f32_32x32x16_bf16 v[34:49], v[184:187], v[200:203], v[34:49]
	v_mfma_f32_32x32x16_bf16 v[18:33], v[188:191], v[192:195], v[18:33]
	v_mfma_f32_32x32x16_bf16 v[2:17], v[188:191], v[200:203], v[2:17]
	v_add_u32_e32 v149, s0, v143
	v_or_b32_e32 v130, s2, v144
	s_mov_b32 s2, 0x7e07e07f
	v_mul_hi_i32 v0, v149, s2
	v_lshrrev_b32_e32 v131, 31, v0
	v_ashrrev_i32_e32 v0, 13, v0
	v_add_u32_e32 v0, v0, v131
	v_mul_i32_i24_e32 v131, 0x4100, v0
	v_sub_u32_e32 v131, v149, v131
	s_movk_i32 s3, 0xff
	v_mul_i32_i24_e32 v0, 0xc00, v0
	v_cmp_lt_i32_e32 vcc, s3, v131
	v_mov_b32_e32 v162, 0x1800
	v_mov_b32_e32 v152, v179
	s_waitcnt vmcnt(0)
	s_barrier
	v_cndmask_b32_e32 v150, v162, v0, vcc
	v_readlane_b32 s12, v251, 2
	v_and_b32_e32 v0, 31, v152
	v_bfe_u32 v131, v152, 5, 1
	v_mul_u32_u24_e32 v131, 0x240, v131
	v_lshlrev_b32_e32 v0, 2, v0
	v_add3_u32 v0, v145, v131, v0
	ds_write2_b32 v0, v114, v115 offset1:36
	ds_write2_b32 v0, v116, v117 offset0:72 offset1:108
	v_add_u32_e32 v114, 0x400, v0
	v_ashrrev_i32_e32 v151, 31, v150
	ds_write2_b32 v114, v118, v119 offset0:32 offset1:68
	ds_write2_b32 v114, v120, v121 offset0:104 offset1:140
	v_add_u32_e32 v114, 0x800, v0
	v_add_u32_e32 v0, 0xc00, v0
	v_readlane_b32 s26, v251, 16
	v_readlane_b32 s27, v251, 17
	ds_write2_b32 v114, v122, v123 offset0:64 offset1:100
	ds_write2_b32 v114, v124, v125 offset0:136 offset1:172
	ds_write2_b32 v0, v126, v127 offset0:96 offset1:132
	ds_write2_b32 v0, v128, v129 offset0:168 offset1:204
	v_lshl_add_u64 v[114:115], v[150:151], 2, s[26:27]
	s_mov_b64 s[4:5], 0x1b02000
	v_ashrrev_i32_e32 v131, 31, v130
	v_readlane_b32 s0, v251, 26
	v_lshlrev_b32_e32 v0, 3, v152
	v_lshl_add_u64 v[118:119], v[114:115], 0, s[4:5]
	v_lshlrev_b64 v[116:117], 2, v[130:131]
	v_readlane_b32 s1, v251, 27
	v_and_b32_e32 v122, 24, v0
	v_lshl_add_u64 v[120:121], v[118:119], 0, v[116:117]
	v_lshl_add_u64 v[114:115], v[130:131], 1, s[0:1]
	v_lshlrev_b32_e32 v0, 2, v122
	v_bfe_u32 v131, v152, 2, 4
	v_lshl_add_u64 v[158:159], v[120:121], 0, v[0:1]
	v_lshlrev_b32_e32 v120, 1, v122
	v_mul_u32_u24_e32 v122, 0x90, v131
	s_waitcnt lgkmcnt(0)
	v_add3_u32 v0, v145, v0, v122
	ds_read_b128 v[122:125], v0
	ds_read_b128 v[126:129], v0 offset:16
	global_load_dwordx4 v[150:153], v[158:159], off offset:16
	global_load_dwordx4 v[154:157], v[158:159], off
	v_or_b32_e32 v160, v131, v149
	v_mov_b32_e32 v121, v1
	v_ashrrev_i32_e32 v161, 31, v160
	v_lshl_add_u64 v[120:121], v[114:115], 0, v[120:121]
	v_readlane_b32 s13, v251, 3
	v_readlane_b32 s14, v251, 4
	v_readlane_b32 s15, v251, 5
	v_readlane_b32 s16, v251, 6
	v_readlane_b32 s17, v251, 7
	v_readlane_b32 s18, v251, 8
	v_readlane_b32 s19, v251, 9
	v_readlane_b32 s20, v251, 10
	v_readlane_b32 s21, v251, 11
	v_readlane_b32 s22, v251, 12
	v_readlane_b32 s23, v251, 13
	v_readlane_b32 s24, v251, 14
	v_readlane_b32 s25, v251, 15
	s_waitcnt vmcnt(1) lgkmcnt(0)
	v_pk_mul_f32 v[126:127], v[126:127], v[150:151]
	s_waitcnt vmcnt(0)
	v_pk_mul_f32 v[122:123], v[122:123], v[154:155]
	v_pk_mul_f32 v[124:125], v[124:125], v[156:157]
	v_pk_mul_f32 v[128:129], v[128:129], v[152:153]
	v_cvt_pk_bf16_f32 v122, v122, v123
	v_cvt_pk_bf16_f32 v123, v124, v125
	v_cvt_pk_bf16_f32 v124, v126, v127
	v_lshlrev_b64 v[126:127], 11, v[160:161]
	v_cvt_pk_bf16_f32 v125, v128, v129
	v_lshl_add_u64 v[126:127], v[120:121], 0, v[126:127]
	global_store_dwordx4 v[126:127], v[122:125], off
	ds_read_b128 v[122:125], v0 offset:2304
	ds_read_b128 v[126:129], v0 offset:2320
	global_load_dwordx4 v[150:153], v[158:159], off offset:16
	global_load_dwordx4 v[154:157], v[158:159], off
	s_waitcnt vmcnt(1) lgkmcnt(0)
	v_pk_mul_f32 v[126:127], v[126:127], v[150:151]
	s_waitcnt vmcnt(0)
	v_pk_mul_f32 v[122:123], v[122:123], v[154:155]
	v_pk_mul_f32 v[124:125], v[124:125], v[156:157]
	v_cvt_pk_bf16_f32 v122, v122, v123
	v_cvt_pk_bf16_f32 v123, v124, v125
	v_cvt_pk_bf16_f32 v124, v126, v127
	v_or_b32_e32 v126, 16, v160
	v_ashrrev_i32_e32 v127, 31, v126
	v_pk_mul_f32 v[128:129], v[128:129], v[152:153]
	v_lshlrev_b64 v[126:127], 11, v[126:127]
	v_cvt_pk_bf16_f32 v125, v128, v129
	v_lshl_add_u64 v[120:121], v[120:121], 0, v[126:127]
	global_store_dwordx4 v[120:121], v[122:125], off
	v_mov_b32_e32 v120, v179
	v_or_b32_e32 v126, 32, v130
	v_and_b32_e32 v0, 31, v120
	v_bfe_u32 v121, v120, 5, 1
	v_mul_u32_u24_e32 v121, 0x240, v121
	v_lshlrev_b32_e32 v0, 2, v0
	v_add3_u32 v0, v145, v121, v0
	ds_write2_b32 v0, v98, v99 offset1:36
	ds_write2_b32 v0, v100, v101 offset0:72 offset1:108
	v_add_u32_e32 v98, 0x400, v0
	ds_write2_b32 v98, v102, v103 offset0:32 offset1:68
	ds_write2_b32 v98, v104, v105 offset0:104 offset1:140
	v_add_u32_e32 v98, 0x800, v0
	v_add_u32_e32 v0, 0xc00, v0
	ds_write2_b32 v98, v106, v107 offset0:64 offset1:100
	ds_write2_b32 v98, v108, v109 offset0:136 offset1:172
	ds_write2_b32 v0, v110, v111 offset0:96 offset1:132
	ds_write2_b32 v0, v112, v113 offset0:168 offset1:204
	v_lshlrev_b32_e32 v0, 3, v120
	v_and_b32_e32 v102, 24, v0
	v_ashrrev_i32_e32 v127, 31, v126
	v_lshlrev_b32_e32 v0, 2, v102
	v_lshl_add_u64 v[98:99], v[118:119], 0, v[0:1]
	v_lshlrev_b64 v[100:101], 2, v[126:127]
	v_lshl_add_u64 v[112:113], v[98:99], 0, v[100:101]
	v_lshlrev_b32_e32 v98, 1, v102
	v_mov_b32_e32 v99, v1
	v_bfe_u32 v128, v120, 2, 4
	v_lshl_add_u64 v[102:103], s[0:1], 0, v[98:99]
	v_mul_u32_u24_e32 v98, 0x90, v128
	s_waitcnt lgkmcnt(0)
	v_add3_u32 v0, v145, v0, v98
	ds_read_b128 v[104:107], v0
	ds_read_b128 v[108:111], v0 offset:16
	global_load_dwordx4 v[118:121], v[112:113], off offset:16
	global_load_dwordx4 v[122:125], v[112:113], off
	v_or_b32_e32 v128, v128, v149
	v_ashrrev_i32_e32 v129, 31, v128
	s_waitcnt vmcnt(1) lgkmcnt(0)
	v_pk_mul_f32 v[108:109], v[108:109], v[118:119]
	s_waitcnt vmcnt(0)
	v_pk_mul_f32 v[98:99], v[104:105], v[122:123]
	v_pk_mul_f32 v[106:107], v[106:107], v[124:125]
	v_cvt_pk_bf16_f32 v104, v98, v99
	v_lshlrev_b64 v[98:99], 11, v[128:129]
	v_pk_mul_f32 v[110:111], v[110:111], v[120:121]
	v_cvt_pk_bf16_f32 v105, v106, v107
	v_cvt_pk_bf16_f32 v106, v108, v109
	v_lshl_add_u64 v[108:109], v[102:103], 0, v[98:99]
	v_lshlrev_b64 v[98:99], 1, v[126:127]
	v_cvt_pk_bf16_f32 v107, v110, v111
	v_lshl_add_u64 v[108:109], v[108:109], 0, v[98:99]
	global_store_dwordx4 v[108:109], v[104:107], off
	ds_read_b128 v[104:107], v0 offset:2304
	ds_read_b128 v[108:111], v0 offset:2320
	global_load_dwordx4 v[118:121], v[112:113], off offset:16
	global_load_dwordx4 v[122:125], v[112:113], off
	s_waitcnt vmcnt(1) lgkmcnt(0)
	v_pk_mul_f32 v[108:109], v[108:109], v[118:119]
	s_waitcnt vmcnt(0)
	v_pk_mul_f32 v[104:105], v[104:105], v[122:123]
	v_pk_mul_f32 v[106:107], v[106:107], v[124:125]
	v_cvt_pk_bf16_f32 v104, v104, v105
	v_cvt_pk_bf16_f32 v105, v106, v107
	v_cvt_pk_bf16_f32 v106, v108, v109
	v_or_b32_e32 v108, 16, v128
	v_ashrrev_i32_e32 v109, 31, v108
	v_lshlrev_b64 v[108:109], 11, v[108:109]
	v_pk_mul_f32 v[110:111], v[110:111], v[120:121]
	v_lshl_add_u64 v[102:103], v[102:103], 0, v[108:109]
	v_cvt_pk_bf16_f32 v107, v110, v111
	v_lshl_add_u64 v[102:103], v[102:103], 0, v[98:99]
	global_store_dwordx4 v[102:103], v[104:107], off
	v_or_b32_e32 v110, 32, v149
	v_mul_hi_i32 v0, v110, s2
	v_lshrrev_b32_e32 v102, 31, v0
	v_ashrrev_i32_e32 v0, 13, v0
	v_add_u32_e32 v0, v0, v102
	v_mul_i32_i24_e32 v102, 0x4100, v0
	v_sub_u32_e32 v102, v110, v102
	v_mul_i32_i24_e32 v0, 0xc00, v0
	v_cmp_lt_i32_e32 vcc, s3, v102
	v_mov_b32_e32 v104, v179
	s_nop 0
	v_cndmask_b32_e32 v102, v162, v0, vcc
	v_and_b32_e32 v0, 31, v104
	v_bfe_u32 v105, v104, 5, 1
	v_mul_u32_u24_e32 v105, 0x240, v105
	v_lshlrev_b32_e32 v0, 2, v0
	v_add3_u32 v0, v145, v105, v0
	ds_write2_b32 v0, v82, v83 offset1:36
	ds_write2_b32 v0, v84, v85 offset0:72 offset1:108
	v_add_u32_e32 v82, 0x400, v0
	v_ashrrev_i32_e32 v103, 31, v102
	ds_write2_b32 v82, v86, v87 offset0:32 offset1:68
	ds_write2_b32 v82, v88, v89 offset0:104 offset1:140
	v_add_u32_e32 v82, 0x800, v0
	v_add_u32_e32 v0, 0xc00, v0
	ds_write2_b32 v82, v90, v91 offset0:64 offset1:100
	ds_write2_b32 v82, v92, v93 offset0:136 offset1:172
	ds_write2_b32 v0, v94, v95 offset0:96 offset1:132
	ds_write2_b32 v0, v96, v97 offset0:168 offset1:204
	v_lshl_add_u64 v[82:83], v[102:103], 2, s[26:27]
	v_lshlrev_b32_e32 v0, 3, v104
	v_lshl_add_u64 v[82:83], v[82:83], 0, s[4:5]
	v_and_b32_e32 v86, 24, v0
	v_lshl_add_u64 v[84:85], v[82:83], 0, v[116:117]
	v_lshlrev_b32_e32 v0, 2, v86
	v_bfe_u32 v108, v104, 2, 4
	v_lshl_add_u64 v[106:107], v[84:85], 0, v[0:1]
	v_lshlrev_b32_e32 v84, 1, v86
	v_mul_u32_u24_e32 v86, 0x90, v108
	s_waitcnt lgkmcnt(0)
	v_add3_u32 v0, v145, v0, v86
	ds_read_b128 v[86:89], v0
	ds_read_b128 v[90:93], v0 offset:16
	global_load_dwordx4 v[94:97], v[106:107], off offset:16
	global_load_dwordx4 v[102:105], v[106:107], off
	v_or_b32_e32 v108, v108, v110
	v_mov_b32_e32 v85, v1
	v_ashrrev_i32_e32 v109, 31, v108
	v_lshl_add_u64 v[84:85], v[114:115], 0, v[84:85]
	s_waitcnt vmcnt(1) lgkmcnt(0)
	v_pk_mul_f32 v[90:91], v[90:91], v[94:95]
	s_waitcnt vmcnt(0)
	v_pk_mul_f32 v[86:87], v[86:87], v[102:103]
	v_pk_mul_f32 v[88:89], v[88:89], v[104:105]
	v_pk_mul_f32 v[92:93], v[92:93], v[96:97]
	v_cvt_pk_bf16_f32 v86, v86, v87
	v_cvt_pk_bf16_f32 v87, v88, v89
	v_cvt_pk_bf16_f32 v88, v90, v91
	v_lshlrev_b64 v[90:91], 11, v[108:109]
	v_cvt_pk_bf16_f32 v89, v92, v93
	v_lshl_add_u64 v[90:91], v[84:85], 0, v[90:91]
	global_store_dwordx4 v[90:91], v[86:89], off
	ds_read_b128 v[86:89], v0 offset:2304
	ds_read_b128 v[90:93], v0 offset:2320
	global_load_dwordx4 v[94:97], v[106:107], off offset:16
	global_load_dwordx4 v[102:105], v[106:107], off
	s_waitcnt vmcnt(1) lgkmcnt(0)
	v_pk_mul_f32 v[90:91], v[90:91], v[94:95]
	s_waitcnt vmcnt(0)
	v_pk_mul_f32 v[86:87], v[86:87], v[102:103]
	v_pk_mul_f32 v[88:89], v[88:89], v[104:105]
	v_cvt_pk_bf16_f32 v86, v86, v87
	v_cvt_pk_bf16_f32 v87, v88, v89
	v_cvt_pk_bf16_f32 v88, v90, v91
	v_or_b32_e32 v90, 16, v108
	v_ashrrev_i32_e32 v91, 31, v90
	v_pk_mul_f32 v[92:93], v[92:93], v[96:97]
	v_lshlrev_b64 v[90:91], 11, v[90:91]
	v_cvt_pk_bf16_f32 v89, v92, v93
	v_lshl_add_u64 v[84:85], v[84:85], 0, v[90:91]
	global_store_dwordx4 v[84:85], v[86:89], off
	s_nop 1
	v_mov_b32_e32 v86, v179
	s_nop 0
	v_and_b32_e32 v0, 31, v86
	v_bfe_u32 v84, v86, 5, 1
	v_mul_u32_u24_e32 v84, 0x240, v84
	v_lshlrev_b32_e32 v0, 2, v0
	v_add3_u32 v0, v145, v84, v0
	ds_write2_b32 v0, v66, v67 offset1:36
	ds_write2_b32 v0, v68, v69 offset0:72 offset1:108
	v_add_u32_e32 v66, 0x400, v0
	ds_write2_b32 v66, v70, v71 offset0:32 offset1:68
	ds_write2_b32 v66, v72, v73 offset0:104 offset1:140
	v_add_u32_e32 v66, 0x800, v0
	v_add_u32_e32 v0, 0xc00, v0
	ds_write2_b32 v66, v74, v75 offset0:64 offset1:100
	ds_write2_b32 v66, v76, v77 offset0:136 offset1:172
	ds_write2_b32 v0, v78, v79 offset0:96 offset1:132
	ds_write2_b32 v0, v80, v81 offset0:168 offset1:204
	v_lshlrev_b32_e32 v0, 3, v86
	v_and_b32_e32 v68, 24, v0
	v_lshlrev_b32_e32 v0, 2, v68
	v_lshl_add_u64 v[66:67], v[82:83], 0, v[0:1]
	v_bfe_u32 v86, v86, 2, 4
	v_lshl_add_u64 v[84:85], v[66:67], 0, v[100:101]
	v_lshlrev_b32_e32 v66, 1, v68
	v_mul_u32_u24_e32 v68, 0x90, v86
	s_waitcnt lgkmcnt(0)
	v_add3_u32 v0, v145, v0, v68
	ds_read_b128 v[68:71], v0
	ds_read_b128 v[72:75], v0 offset:16
	global_load_dwordx4 v[76:79], v[84:85], off offset:16
	global_load_dwordx4 v[80:83], v[84:85], off
	v_or_b32_e32 v86, v86, v110
	v_mov_b32_e32 v67, v1
	v_ashrrev_i32_e32 v87, 31, v86
	v_lshl_add_u64 v[66:67], s[0:1], 0, v[66:67]
	s_waitcnt vmcnt(1) lgkmcnt(0)
	v_pk_mul_f32 v[72:73], v[72:73], v[76:77]
	s_waitcnt vmcnt(0)
	v_pk_mul_f32 v[68:69], v[68:69], v[80:81]
	v_pk_mul_f32 v[70:71], v[70:71], v[82:83]
	v_cvt_pk_bf16_f32 v68, v68, v69
	v_cvt_pk_bf16_f32 v69, v70, v71
	v_cvt_pk_bf16_f32 v70, v72, v73
	v_lshlrev_b64 v[72:73], 11, v[86:87]
	v_pk_mul_f32 v[74:75], v[74:75], v[78:79]
	v_lshl_add_u64 v[72:73], v[66:67], 0, v[72:73]
	v_cvt_pk_bf16_f32 v71, v74, v75
	v_lshl_add_u64 v[72:73], v[72:73], 0, v[98:99]
	global_store_dwordx4 v[72:73], v[68:71], off
	ds_read_b128 v[68:71], v0 offset:2304
	ds_read_b128 v[72:75], v0 offset:2320
	global_load_dwordx4 v[76:79], v[84:85], off offset:16
	global_load_dwordx4 v[80:83], v[84:85], off
	s_waitcnt vmcnt(1) lgkmcnt(0)
	v_pk_mul_f32 v[72:73], v[72:73], v[76:77]
	s_waitcnt vmcnt(0)
	v_pk_mul_f32 v[68:69], v[68:69], v[80:81]
	v_pk_mul_f32 v[70:71], v[70:71], v[82:83]
	v_cvt_pk_bf16_f32 v68, v68, v69
	v_cvt_pk_bf16_f32 v69, v70, v71
	v_cvt_pk_bf16_f32 v70, v72, v73
	v_or_b32_e32 v72, 16, v86
	v_ashrrev_i32_e32 v73, 31, v72
	v_lshlrev_b64 v[72:73], 11, v[72:73]
	v_pk_mul_f32 v[74:75], v[74:75], v[78:79]
	v_lshl_add_u64 v[66:67], v[66:67], 0, v[72:73]
	v_cvt_pk_bf16_f32 v71, v74, v75
	v_lshl_add_u64 v[66:67], v[66:67], 0, v[98:99]
	global_store_dwordx4 v[66:67], v[68:71], off
	v_or_b32_e32 v74, 64, v149
	v_mul_hi_i32 v0, v74, s2
	v_lshrrev_b32_e32 v66, 31, v0
	v_ashrrev_i32_e32 v0, 13, v0
	v_add_u32_e32 v0, v0, v66
	v_mul_i32_i24_e32 v66, 0x4100, v0
	v_sub_u32_e32 v66, v74, v66
	v_mul_i32_i24_e32 v0, 0xc00, v0
	v_cmp_lt_i32_e32 vcc, s3, v66
	v_mov_b32_e32 v68, v179
	s_nop 0
	v_cndmask_b32_e32 v66, v162, v0, vcc
	v_and_b32_e32 v0, 31, v68
	v_bfe_u32 v69, v68, 5, 1
	v_mul_u32_u24_e32 v69, 0x240, v69
	v_lshlrev_b32_e32 v0, 2, v0
	v_add3_u32 v0, v145, v69, v0
	ds_write2_b32 v0, v50, v51 offset1:36
	ds_write2_b32 v0, v52, v53 offset0:72 offset1:108
	v_add_u32_e32 v50, 0x400, v0
	v_ashrrev_i32_e32 v67, 31, v66
	ds_write2_b32 v50, v54, v55 offset0:32 offset1:68
	ds_write2_b32 v50, v56, v57 offset0:104 offset1:140
	v_add_u32_e32 v50, 0x800, v0
	v_add_u32_e32 v0, 0xc00, v0
	ds_write2_b32 v50, v58, v59 offset0:64 offset1:100
	ds_write2_b32 v50, v60, v61 offset0:136 offset1:172
	ds_write2_b32 v0, v62, v63 offset0:96 offset1:132
	ds_write2_b32 v0, v64, v65 offset0:168 offset1:204
	v_lshl_add_u64 v[50:51], v[66:67], 2, s[26:27]
	v_lshlrev_b32_e32 v0, 3, v68
	v_lshl_add_u64 v[50:51], v[50:51], 0, s[4:5]
	v_and_b32_e32 v54, 24, v0
	v_lshl_add_u64 v[52:53], v[50:51], 0, v[116:117]
	v_lshlrev_b32_e32 v0, 2, v54
	v_bfe_u32 v72, v68, 2, 4
	v_lshl_add_u64 v[70:71], v[52:53], 0, v[0:1]
	v_lshlrev_b32_e32 v52, 1, v54
	v_mul_u32_u24_e32 v54, 0x90, v72
	s_waitcnt lgkmcnt(0)
	v_add3_u32 v0, v145, v0, v54
	ds_read_b128 v[54:57], v0
	ds_read_b128 v[58:61], v0 offset:16
	global_load_dwordx4 v[62:65], v[70:71], off offset:16
	global_load_dwordx4 v[66:69], v[70:71], off
	v_or_b32_e32 v72, v72, v74
	v_mov_b32_e32 v53, v1
	v_ashrrev_i32_e32 v73, 31, v72
	v_lshl_add_u64 v[52:53], v[114:115], 0, v[52:53]
	s_waitcnt vmcnt(1) lgkmcnt(0)
	v_pk_mul_f32 v[58:59], v[58:59], v[62:63]
	s_waitcnt vmcnt(0)
	v_pk_mul_f32 v[54:55], v[54:55], v[66:67]
	v_pk_mul_f32 v[56:57], v[56:57], v[68:69]
	v_pk_mul_f32 v[60:61], v[60:61], v[64:65]
	v_cvt_pk_bf16_f32 v54, v54, v55
	v_cvt_pk_bf16_f32 v55, v56, v57
	v_cvt_pk_bf16_f32 v56, v58, v59
	v_lshlrev_b64 v[58:59], 11, v[72:73]
	v_cvt_pk_bf16_f32 v57, v60, v61
	v_lshl_add_u64 v[58:59], v[52:53], 0, v[58:59]
	global_store_dwordx4 v[58:59], v[54:57], off
	ds_read_b128 v[54:57], v0 offset:2304
	ds_read_b128 v[58:61], v0 offset:2320
	global_load_dwordx4 v[62:65], v[70:71], off offset:16
	global_load_dwordx4 v[66:69], v[70:71], off
	s_waitcnt vmcnt(1) lgkmcnt(0)
	v_pk_mul_f32 v[58:59], v[58:59], v[62:63]
	s_waitcnt vmcnt(0)
	v_pk_mul_f32 v[54:55], v[54:55], v[66:67]
	v_pk_mul_f32 v[56:57], v[56:57], v[68:69]
	v_cvt_pk_bf16_f32 v54, v54, v55
	v_cvt_pk_bf16_f32 v55, v56, v57
	v_cvt_pk_bf16_f32 v56, v58, v59
	v_or_b32_e32 v58, 16, v72
	v_ashrrev_i32_e32 v59, 31, v58
	v_pk_mul_f32 v[60:61], v[60:61], v[64:65]
	v_lshlrev_b64 v[58:59], 11, v[58:59]
	v_cvt_pk_bf16_f32 v57, v60, v61
	v_lshl_add_u64 v[52:53], v[52:53], 0, v[58:59]
	global_store_dwordx4 v[52:53], v[54:57], off
	s_nop 1
	v_mov_b32_e32 v54, v179
	s_nop 0
	v_and_b32_e32 v0, 31, v54
	v_bfe_u32 v52, v54, 5, 1
	v_mul_u32_u24_e32 v52, 0x240, v52
	v_lshlrev_b32_e32 v0, 2, v0
	v_add3_u32 v0, v145, v52, v0
	ds_write2_b32 v0, v34, v35 offset1:36
	ds_write2_b32 v0, v36, v37 offset0:72 offset1:108
	v_add_u32_e32 v34, 0x400, v0
	ds_write2_b32 v34, v38, v39 offset0:32 offset1:68
	ds_write2_b32 v34, v40, v41 offset0:104 offset1:140
	v_add_u32_e32 v34, 0x800, v0
	v_add_u32_e32 v0, 0xc00, v0
	ds_write2_b32 v34, v42, v43 offset0:64 offset1:100
	ds_write2_b32 v34, v44, v45 offset0:136 offset1:172
	ds_write2_b32 v0, v46, v47 offset0:96 offset1:132
	ds_write2_b32 v0, v48, v49 offset0:168 offset1:204
	v_lshlrev_b32_e32 v0, 3, v54
	v_and_b32_e32 v36, 24, v0
	v_lshlrev_b32_e32 v0, 2, v36
	v_lshl_add_u64 v[34:35], v[50:51], 0, v[0:1]
	v_bfe_u32 v54, v54, 2, 4
	v_lshl_add_u64 v[52:53], v[34:35], 0, v[100:101]
	v_lshlrev_b32_e32 v34, 1, v36
	v_mul_u32_u24_e32 v36, 0x90, v54
	s_waitcnt lgkmcnt(0)
	v_add3_u32 v0, v145, v0, v36
	ds_read_b128 v[36:39], v0
	ds_read_b128 v[40:43], v0 offset:16
	global_load_dwordx4 v[44:47], v[52:53], off offset:16
	global_load_dwordx4 v[48:51], v[52:53], off
	v_or_b32_e32 v54, v54, v74
	v_mov_b32_e32 v35, v1
	v_ashrrev_i32_e32 v55, 31, v54
	v_lshl_add_u64 v[34:35], s[0:1], 0, v[34:35]
	s_waitcnt vmcnt(1) lgkmcnt(0)
	v_pk_mul_f32 v[40:41], v[40:41], v[44:45]
	s_waitcnt vmcnt(0)
	v_pk_mul_f32 v[36:37], v[36:37], v[48:49]
	v_pk_mul_f32 v[38:39], v[38:39], v[50:51]
	v_cvt_pk_bf16_f32 v36, v36, v37
	v_cvt_pk_bf16_f32 v37, v38, v39
	v_cvt_pk_bf16_f32 v38, v40, v41
	v_lshlrev_b64 v[40:41], 11, v[54:55]
	v_pk_mul_f32 v[42:43], v[42:43], v[46:47]
	v_lshl_add_u64 v[40:41], v[34:35], 0, v[40:41]
	v_cvt_pk_bf16_f32 v39, v42, v43
	v_lshl_add_u64 v[40:41], v[40:41], 0, v[98:99]
	global_store_dwordx4 v[40:41], v[36:39], off
	ds_read_b128 v[36:39], v0 offset:2304
	ds_read_b128 v[40:43], v0 offset:2320
	global_load_dwordx4 v[44:47], v[52:53], off offset:16
	global_load_dwordx4 v[48:51], v[52:53], off
	s_waitcnt vmcnt(1) lgkmcnt(0)
	v_pk_mul_f32 v[40:41], v[40:41], v[44:45]
	s_waitcnt vmcnt(0)
	v_pk_mul_f32 v[36:37], v[36:37], v[48:49]
	v_pk_mul_f32 v[38:39], v[38:39], v[50:51]
	v_cvt_pk_bf16_f32 v36, v36, v37
	v_cvt_pk_bf16_f32 v37, v38, v39
	v_cvt_pk_bf16_f32 v38, v40, v41
	v_or_b32_e32 v40, 16, v54
	v_ashrrev_i32_e32 v41, 31, v40
	v_lshlrev_b64 v[40:41], 11, v[40:41]
	v_pk_mul_f32 v[42:43], v[42:43], v[46:47]
	v_lshl_add_u64 v[34:35], v[34:35], 0, v[40:41]
	v_cvt_pk_bf16_f32 v39, v42, v43
	v_lshl_add_u64 v[34:35], v[34:35], 0, v[98:99]
	global_store_dwordx4 v[34:35], v[36:39], off
	v_or_b32_e32 v42, 0x60, v149
	v_mul_hi_i32 v0, v42, s2
	v_lshrrev_b32_e32 v34, 31, v0
	v_ashrrev_i32_e32 v0, 13, v0
	v_add_u32_e32 v0, v0, v34
	v_mul_i32_i24_e32 v34, 0x4100, v0
	v_sub_u32_e32 v34, v42, v34
	v_mul_i32_i24_e32 v0, 0xc00, v0
	v_cmp_lt_i32_e32 vcc, s3, v34
	v_mov_b32_e32 v36, v179
	s_nop 0
	v_cndmask_b32_e32 v34, v162, v0, vcc
	v_and_b32_e32 v0, 31, v36
	v_bfe_u32 v37, v36, 5, 1
	v_mul_u32_u24_e32 v37, 0x240, v37
	v_lshlrev_b32_e32 v0, 2, v0
	v_add3_u32 v0, v145, v37, v0
	ds_write2_b32 v0, v18, v19 offset1:36
	ds_write2_b32 v0, v20, v21 offset0:72 offset1:108
	v_add_u32_e32 v18, 0x400, v0
	v_ashrrev_i32_e32 v35, 31, v34
	ds_write2_b32 v18, v22, v23 offset0:32 offset1:68
	ds_write2_b32 v18, v24, v25 offset0:104 offset1:140
	v_add_u32_e32 v18, 0x800, v0
	v_add_u32_e32 v0, 0xc00, v0
	ds_write2_b32 v18, v26, v27 offset0:64 offset1:100
	ds_write2_b32 v18, v28, v29 offset0:136 offset1:172
	ds_write2_b32 v0, v30, v31 offset0:96 offset1:132
	ds_write2_b32 v0, v32, v33 offset0:168 offset1:204
	v_lshl_add_u64 v[18:19], v[34:35], 2, s[26:27]
	v_lshlrev_b32_e32 v0, 3, v36
	v_lshl_add_u64 v[18:19], v[18:19], 0, s[4:5]
	v_and_b32_e32 v22, 24, v0
	v_lshl_add_u64 v[20:21], v[18:19], 0, v[116:117]
	v_lshlrev_b32_e32 v0, 2, v22
	v_bfe_u32 v40, v36, 2, 4
	v_lshl_add_u64 v[38:39], v[20:21], 0, v[0:1]
	v_lshlrev_b32_e32 v20, 1, v22
	v_mul_u32_u24_e32 v22, 0x90, v40
	s_waitcnt lgkmcnt(0)
	v_add3_u32 v0, v145, v0, v22
	ds_read_b128 v[22:25], v0
	ds_read_b128 v[26:29], v0 offset:16
	global_load_dwordx4 v[30:33], v[38:39], off offset:16
	global_load_dwordx4 v[34:37], v[38:39], off
	v_or_b32_e32 v40, v40, v42
	v_mov_b32_e32 v21, v1
	v_ashrrev_i32_e32 v41, 31, v40
	v_lshl_add_u64 v[20:21], v[114:115], 0, v[20:21]
	s_waitcnt vmcnt(1) lgkmcnt(0)
	v_pk_mul_f32 v[26:27], v[26:27], v[30:31]
	s_waitcnt vmcnt(0)
	v_pk_mul_f32 v[22:23], v[22:23], v[34:35]
	v_pk_mul_f32 v[24:25], v[24:25], v[36:37]
	v_pk_mul_f32 v[28:29], v[28:29], v[32:33]
	v_cvt_pk_bf16_f32 v22, v22, v23
	v_cvt_pk_bf16_f32 v23, v24, v25
	v_cvt_pk_bf16_f32 v24, v26, v27
	v_lshlrev_b64 v[26:27], 11, v[40:41]
	v_cvt_pk_bf16_f32 v25, v28, v29
	v_lshl_add_u64 v[26:27], v[20:21], 0, v[26:27]
	global_store_dwordx4 v[26:27], v[22:25], off
	ds_read_b128 v[22:25], v0 offset:2304
	ds_read_b128 v[26:29], v0 offset:2320
	global_load_dwordx4 v[30:33], v[38:39], off offset:16
	global_load_dwordx4 v[34:37], v[38:39], off
	s_waitcnt vmcnt(1) lgkmcnt(0)
	v_pk_mul_f32 v[26:27], v[26:27], v[30:31]
	s_waitcnt vmcnt(0)
	v_pk_mul_f32 v[22:23], v[22:23], v[34:35]
	v_pk_mul_f32 v[24:25], v[24:25], v[36:37]
	v_cvt_pk_bf16_f32 v22, v22, v23
	v_cvt_pk_bf16_f32 v23, v24, v25
	v_cvt_pk_bf16_f32 v24, v26, v27
	v_or_b32_e32 v26, 16, v40
	v_ashrrev_i32_e32 v27, 31, v26
	v_pk_mul_f32 v[28:29], v[28:29], v[32:33]
	v_lshlrev_b64 v[26:27], 11, v[26:27]
	v_cvt_pk_bf16_f32 v25, v28, v29
	v_lshl_add_u64 v[20:21], v[20:21], 0, v[26:27]
	global_store_dwordx4 v[20:21], v[22:25], off
	s_nop 1
	v_mov_b32_e32 v22, v179
	s_nop 0
	v_and_b32_e32 v0, 31, v22
	v_bfe_u32 v20, v22, 5, 1
	v_mul_u32_u24_e32 v20, 0x240, v20
	v_lshlrev_b32_e32 v0, 2, v0
	v_add3_u32 v0, v145, v20, v0
	ds_write2_b32 v0, v2, v3 offset1:36
	ds_write2_b32 v0, v4, v5 offset0:72 offset1:108
	v_add_u32_e32 v2, 0x400, v0
	ds_write2_b32 v2, v6, v7 offset0:32 offset1:68
	ds_write2_b32 v2, v8, v9 offset0:104 offset1:140
	v_add_u32_e32 v2, 0x800, v0
	v_add_u32_e32 v0, 0xc00, v0
	ds_write2_b32 v2, v10, v11 offset0:64 offset1:100
	ds_write2_b32 v2, v12, v13 offset0:136 offset1:172
	ds_write2_b32 v0, v14, v15 offset0:96 offset1:132
	ds_write2_b32 v0, v16, v17 offset0:168 offset1:204
	v_lshlrev_b32_e32 v0, 3, v22
	v_and_b32_e32 v4, 24, v0
	v_lshlrev_b32_e32 v0, 2, v4
	v_lshl_add_u64 v[2:3], v[18:19], 0, v[0:1]
	v_bfe_u32 v22, v22, 2, 4
	v_lshl_add_u64 v[20:21], v[2:3], 0, v[100:101]
	v_lshlrev_b32_e32 v2, 1, v4
	v_mul_u32_u24_e32 v4, 0x90, v22
	s_waitcnt lgkmcnt(0)
	v_add3_u32 v0, v145, v0, v4
	ds_read_b128 v[4:7], v0
	ds_read_b128 v[8:11], v0 offset:16
	global_load_dwordx4 v[12:15], v[20:21], off offset:16
	global_load_dwordx4 v[16:19], v[20:21], off
	v_or_b32_e32 v22, v22, v42
	v_mov_b32_e32 v3, v1
	v_ashrrev_i32_e32 v23, 31, v22
	v_lshl_add_u64 v[2:3], s[0:1], 0, v[2:3]
	s_waitcnt vmcnt(1) lgkmcnt(0)
	v_pk_mul_f32 v[8:9], v[8:9], v[12:13]
	s_waitcnt vmcnt(0)
	v_pk_mul_f32 v[4:5], v[4:5], v[16:17]
	v_pk_mul_f32 v[6:7], v[6:7], v[18:19]
	v_cvt_pk_bf16_f32 v4, v4, v5
	v_cvt_pk_bf16_f32 v5, v6, v7
	v_cvt_pk_bf16_f32 v6, v8, v9
	v_lshlrev_b64 v[8:9], 11, v[22:23]
	v_pk_mul_f32 v[10:11], v[10:11], v[14:15]
	v_lshl_add_u64 v[8:9], v[2:3], 0, v[8:9]
	v_cvt_pk_bf16_f32 v7, v10, v11
	v_lshl_add_u64 v[8:9], v[8:9], 0, v[98:99]
	global_store_dwordx4 v[8:9], v[4:7], off
	ds_read_b128 v[4:7], v0 offset:2304
	ds_read_b128 v[8:11], v0 offset:2320
	global_load_dwordx4 v[12:15], v[20:21], off offset:16
	global_load_dwordx4 v[16:19], v[20:21], off
	s_waitcnt vmcnt(1) lgkmcnt(0)
	v_pk_mul_f32 v[8:9], v[8:9], v[12:13]
	s_waitcnt vmcnt(0)
	v_pk_mul_f32 v[4:5], v[4:5], v[16:17]
	v_pk_mul_f32 v[6:7], v[6:7], v[18:19]
	v_cvt_pk_bf16_f32 v4, v4, v5
	v_cvt_pk_bf16_f32 v5, v6, v7
	v_cvt_pk_bf16_f32 v6, v8, v9
	v_or_b32_e32 v8, 16, v22
	v_ashrrev_i32_e32 v9, 31, v8
	v_lshlrev_b64 v[8:9], 11, v[8:9]
	v_pk_mul_f32 v[10:11], v[10:11], v[14:15]
	v_lshl_add_u64 v[2:3], v[2:3], 0, v[8:9]
	v_cvt_pk_bf16_f32 v7, v10, v11
	v_lshl_add_u64 v[2:3], v[2:3], 0, v[98:99]
	global_store_dwordx4 v[2:3], v[4:7], off
	s_add_i32 s7, s7, s6
	s_cmpk_gt_i32 s7, 0x207
	s_cselect_b64 s[0:1], -1, 0
	s_branch .LBB0_907

.LBB0_1120:
	s_add_i32 s2, s13, s14
	s_cmpk_gt_i32 s2, 0x81f
	s_mov_b64 s[0:1], -1
	s_cbranch_scc1 .LBB0_1119
	s_ashr_i32 s0, s2, 31
	s_lshr_b32 s0, s0, 25
	s_add_i32 s0, s2, s0
	s_ashr_i32 s1, s0, 7
	s_lshl_b32 s1, s1, 3
	s_sub_i32 s3, 0x82, s1
	s_min_u32 s3, s3, 8
	v_cvt_f32_ubyte0_e32 v0, s3
	v_rcp_iflag_f32_e32 v0, v0
	s_sub_i32 s6, 0, s3
	s_and_b32 s0, s0, 0xffffff80
	s_sub_i32 s0, s2, s0
	v_mul_f32_e32 v0, 0x4f7ffffe, v0
	v_cvt_u32_f32_e32 v0, v0
	s_abs_i32 s4, s0
	s_ashr_i32 s2, s0, 31
	s_waitcnt vmcnt(63) expcnt(7) lgkmcnt(15)
	v_readfirstlane_b32 s7, v0
	s_mul_i32 s6, s6, s7
	s_mul_hi_u32 s6, s7, s6
	s_add_i32 s7, s7, s6
	s_mul_hi_u32 s6, s4, s7
	s_mul_i32 s7, s6, s3
	s_sub_i32 s4, s4, s7
	s_add_i32 s7, s6, 1
	s_sub_i32 s8, s4, s3
	s_cmp_ge_u32 s4, s3
	s_cselect_b32 s6, s7, s6
	s_cselect_b32 s4, s8, s4
	s_add_i32 s7, s6, 1
	s_cmp_ge_u32 s4, s3
	s_cselect_b32 s4, s7, s6
	s_xor_b32 s4, s4, s2
	s_sub_i32 s4, s4, s2
	s_mul_i32 s2, s4, s3
	s_sub_i32 s0, s0, s2
	s_add_i32 s0, s0, s1
	s_lshl_b32 s0, s0, 8
	s_lshl_b32 s6, s4, 8
	s_ashr_i32 s1, s0, 31
	s_ashr_i32 s7, s6, 31
	s_lshl_b64 s[2:3], s[0:1], 11
	s_lshl_b64 s[8:9], s[6:7], 11
	s_add_u32 s10, s64, s2
	v_mov_b32_e32 v0, v143
	s_addc_u32 s11, s65, s3
	s_barrier
	v_readlane_b32 s16, v251, 2
	v_lshl_add_u64 v[2:3], v[0:1], 1, s[10:11]
	v_add_u32_e32 v0, 32, v158
	v_readlane_b32 s30, v251, 16
	v_readfirstlane_b32 s1, v0
	s_mov_b32 m0, s1
	v_mov_b32_e32 v0, v159
	global_load_lds_dwordx4 v[2:3], off
	v_readlane_b32 s17, v251, 3
	v_lshl_add_u64 v[2:3], v[0:1], 1, s[10:11]
	v_add_u32_e32 v0, 32, v160
	v_readlane_b32 s31, v251, 17
	v_readfirstlane_b32 s1, v0
	s_mov_b32 m0, s1
	v_mov_b32_e32 v0, v161
	global_load_lds_dwordx4 v[2:3], off
	s_add_u32 s16, s30, s8
	v_lshl_add_u64 v[2:3], v[0:1], 1, s[10:11]
	v_add_u32_e32 v0, 32, v162
	s_addc_u32 s17, s31, s9
	v_readfirstlane_b32 s1, v0
	s_mov_b32 m0, s1
	v_mov_b32_e32 v0, v163
	global_load_lds_dwordx4 v[2:3], off
	v_readlane_b32 s7, v254, 3
	v_lshl_add_u64 v[2:3], v[0:1], 1, s[10:11]
	v_add_u32_e32 v0, 32, v164
	s_mov_b32 s5, 0
	v_readfirstlane_b32 s1, v0
	s_mov_b32 m0, s1
	v_mov_b32_e32 v0, v143
	global_load_lds_dwordx4 v[2:3], off
	v_readlane_b32 s18, v251, 4
	v_lshl_add_u64 v[2:3], v[0:1], 1, s[16:17]
	v_add_u32_e32 v0, s7, v158
	v_readlane_b32 s19, v251, 5
	v_readfirstlane_b32 s1, v0
	s_mov_b32 m0, s1
	v_mov_b32_e32 v0, v159
	global_load_lds_dwordx4 v[2:3], off
	v_readlane_b32 s20, v251, 6
	v_lshl_add_u64 v[2:3], v[0:1], 1, s[16:17]
	v_add_u32_e32 v0, s7, v160
	v_readlane_b32 s21, v251, 7
	v_readfirstlane_b32 s1, v0
	s_mov_b32 m0, s1
	v_mov_b32_e32 v0, v161
	global_load_lds_dwordx4 v[2:3], off
	v_readlane_b32 s22, v251, 8
	v_lshl_add_u64 v[2:3], v[0:1], 1, s[16:17]
	v_add_u32_e32 v0, s7, v162
	v_readlane_b32 s23, v251, 9
	v_readfirstlane_b32 s1, v0
	s_mov_b32 m0, s1
	v_mov_b32_e32 v0, v163
	global_load_lds_dwordx4 v[2:3], off
	v_readlane_b32 s24, v251, 10
	v_lshl_add_u64 v[2:3], v[0:1], 1, s[16:17]
	v_add_u32_e32 v0, s7, v164
	v_readlane_b32 s25, v251, 11
	v_readfirstlane_b32 s1, v0
	s_mov_b32 m0, s1
	v_readlane_b32 s1, v253, 25
	global_load_lds_dwordx4 v[2:3], off
	s_add_u32 s1, s1, s2
	v_readlane_b32 s2, v253, 26
	s_waitcnt vmcnt(0)
	s_addc_u32 s7, s2, s3
	v_readlane_b32 s2, v253, 45
	s_add_u32 s8, s2, s8
	v_readlane_b32 s2, v253, 46
	v_mov_b32_e32 v2, 0
	s_addc_u32 s9, s2, s9
	s_mov_b64 s[2:3], 0
	v_mov_b32_e32 v3, v2
	v_mov_b32_e32 v4, v2
	v_mov_b32_e32 v5, v2
	v_mov_b32_e32 v6, v2
	v_mov_b32_e32 v7, v2
	v_mov_b32_e32 v8, v2
	v_mov_b32_e32 v9, v2
	v_mov_b32_e32 v10, v2
	v_mov_b32_e32 v11, v2
	v_mov_b32_e32 v12, v2
	v_mov_b32_e32 v13, v2
	s_waitcnt vmcnt(0)
	v_mov_b32_e32 v14, v2
	v_mov_b32_e32 v15, v2
	v_mov_b32_e32 v16, v2
	v_mov_b32_e32 v17, v2
	v_mov_b32_e32 v18, v2
	v_mov_b32_e32 v19, v2
	v_mov_b32_e32 v20, v2
	v_mov_b32_e32 v21, v2
	v_mov_b32_e32 v22, v2
	v_mov_b32_e32 v23, v2
	v_mov_b32_e32 v24, v2
	v_mov_b32_e32 v25, v2
	v_mov_b32_e32 v26, v2
	v_mov_b32_e32 v27, v2
	v_mov_b32_e32 v28, v2
	v_mov_b32_e32 v29, v2
	v_mov_b32_e32 v30, v2
	v_mov_b32_e32 v31, v2
	v_mov_b32_e32 v32, v2
	v_mov_b32_e32 v33, v2
	v_mov_b32_e32 v34, v2
	v_mov_b32_e32 v35, v2
	v_mov_b32_e32 v36, v2
	v_mov_b32_e32 v37, v2
	v_mov_b32_e32 v38, v2
	v_mov_b32_e32 v39, v2
	v_mov_b32_e32 v40, v2
	v_mov_b32_e32 v41, v2
	v_mov_b32_e32 v42, v2
	v_mov_b32_e32 v43, v2
	v_mov_b32_e32 v44, v2
	v_mov_b32_e32 v45, v2
	v_mov_b32_e32 v46, v2
	v_mov_b32_e32 v47, v2
	v_mov_b32_e32 v48, v2
	v_mov_b32_e32 v49, v2
	v_mov_b32_e32 v50, v2
	v_mov_b32_e32 v51, v2
	v_mov_b32_e32 v52, v2
	v_mov_b32_e32 v53, v2
	v_mov_b32_e32 v54, v2
	v_mov_b32_e32 v55, v2
	v_mov_b32_e32 v56, v2
	v_mov_b32_e32 v57, v2
	v_mov_b32_e32 v58, v2
	v_mov_b32_e32 v59, v2
	v_mov_b32_e32 v60, v2
	v_mov_b32_e32 v61, v2
	v_mov_b32_e32 v62, v2
	v_mov_b32_e32 v63, v2
	v_mov_b32_e32 v64, v2
	v_mov_b32_e32 v65, v2
	v_mov_b32_e32 v66, v2
	v_mov_b32_e32 v67, v2
	v_mov_b32_e32 v68, v2
	v_mov_b32_e32 v69, v2
	v_mov_b32_e32 v70, v2
	v_mov_b32_e32 v71, v2
	v_mov_b32_e32 v72, v2
	v_mov_b32_e32 v73, v2
	v_mov_b32_e32 v74, v2
	v_mov_b32_e32 v75, v2
	v_mov_b32_e32 v76, v2
	v_mov_b32_e32 v77, v2
	v_mov_b32_e32 v78, v2
	v_mov_b32_e32 v79, v2
	v_mov_b32_e32 v80, v2
	v_mov_b32_e32 v81, v2
	v_mov_b32_e32 v82, v2
	v_mov_b32_e32 v83, v2
	v_mov_b32_e32 v84, v2
	v_mov_b32_e32 v85, v2
	v_mov_b32_e32 v86, v2
	v_mov_b32_e32 v87, v2
	v_mov_b32_e32 v88, v2
	v_mov_b32_e32 v89, v2
	v_mov_b32_e32 v90, v2
	v_mov_b32_e32 v91, v2
	v_mov_b32_e32 v92, v2
	v_mov_b32_e32 v93, v2
	v_mov_b32_e32 v94, v2
	v_mov_b32_e32 v95, v2
	v_mov_b32_e32 v96, v2
	v_mov_b32_e32 v97, v2
	v_mov_b32_e32 v98, v2
	v_mov_b32_e32 v99, v2
	v_mov_b32_e32 v100, v2
	v_mov_b32_e32 v101, v2
	v_mov_b32_e32 v102, v2
	v_mov_b32_e32 v103, v2
	v_mov_b32_e32 v104, v2
	v_mov_b32_e32 v105, v2
	v_mov_b32_e32 v106, v2
	v_mov_b32_e32 v107, v2
	v_mov_b32_e32 v108, v2
	v_mov_b32_e32 v109, v2
	v_mov_b32_e32 v110, v2
	v_mov_b32_e32 v111, v2
	v_mov_b32_e32 v112, v2
	v_mov_b32_e32 v113, v2
	v_mov_b32_e32 v114, v2
	v_mov_b32_e32 v115, v2
	v_mov_b32_e32 v116, v2
	v_mov_b32_e32 v117, v2
	v_mov_b32_e32 v118, v2
	v_mov_b32_e32 v119, v2
	v_mov_b32_e32 v120, v2
	v_mov_b32_e32 v121, v2
	v_mov_b32_e32 v122, v2
	v_mov_b32_e32 v123, v2
	v_mov_b32_e32 v124, v2
	v_mov_b32_e32 v125, v2
	v_mov_b32_e32 v126, v2
	v_mov_b32_e32 v127, v2
	v_mov_b32_e32 v128, v2
	v_mov_b32_e32 v129, v2
	v_readlane_b32 s26, v251, 12
	v_readlane_b32 s27, v251, 13
	v_readlane_b32 s28, v251, 14
	v_readlane_b32 s29, v251, 15
	s_waitcnt lgkmcnt(0)
	s_barrier
	v_lshlrev_b32_e32 v142, 1, v143
	v_readfirstlane_b32 s15, v158
	v_add_u32_e32 v156, v165, v167
	v_add_u32_e32 v195, v166, v167
	v_add_u32_e32 v157, v165, v172
	v_add_u32_e32 v200, v166, v172
	v_add_u32_e32 v193, v165, v173
	v_add_u32_e32 v201, v166, v173
	v_add_u32_e32 v194, v165, v174
	v_add_u32_e32 v202, v166, v174
	s_mov_b32 s5, 7
	s_add_u32 m0, s15, 0x8020
	s_add_u32 s10, s1, s2
	s_addc_u32 s11, s7, s3
	global_load_lds_dwordx4 v142, s[10:11]
	s_add_u32 m0, s15, 0xa020
	s_add_u32 s10, s10, 0x20000
	s_addc_u32 s11, s11, 0
	global_load_lds_dwordx4 v142, s[10:11]
	s_add_u32 m0, s15, 0xc020
	s_add_u32 s10, s10, 0x20000
	s_addc_u32 s11, s11, 0
	global_load_lds_dwordx4 v142, s[10:11]
	s_add_u32 m0, s15, 0xe020
	s_add_u32 s10, s10, 0x20000
	s_addc_u32 s11, s11, 0
	global_load_lds_dwordx4 v142, s[10:11]
	ds_read_b128 v[130:133], v156 offset:0
	ds_read_b128 v[148:151], v195 offset:0
	ds_read_b128 v[152:155], v195 offset:4096
	ds_read_b128 v[134:137], v156 offset:4096
	ds_read_b128 v[138:141], v156 offset:8192
	ds_read_b128 v[144:147], v156 offset:12288
.Lg1122_loop:
	s_waitcnt lgkmcnt(4)
	v_mfma_f32_32x32x16_bf16 v[114:129], v[130:133], v[148:151], v[114:129]
	ds_read_b128 v[180:183], v157 offset:0
	s_waitcnt lgkmcnt(4)
	v_mfma_f32_32x32x16_bf16 v[98:113], v[130:133], v[152:155], v[98:113]
	ds_read_b128 v[226:229], v200 offset:0
	s_add_u32 m0, s15, 0x18020
	s_add_u32 s10, s8, s2
	s_addc_u32 s11, s9, s3
	global_load_lds_dwordx4 v142, s[10:11]
	s_waitcnt lgkmcnt(4)
	v_mfma_f32_32x32x16_bf16 v[82:97], v[134:137], v[148:151], v[82:97]
	ds_read_b128 v[230:233], v200 offset:4096
	v_mfma_f32_32x32x16_bf16 v[66:81], v[134:137], v[152:155], v[66:81]
	ds_read_b128 v[184:187], v157 offset:4096
	s_add_u32 m0, s15, 0x1a020
	s_add_u32 s10, s10, 0x20000
	s_addc_u32 s11, s11, 0
	global_load_lds_dwordx4 v142, s[10:11]
	s_waitcnt lgkmcnt(5)
	v_mfma_f32_32x32x16_bf16 v[50:65], v[138:141], v[148:151], v[50:65]
	ds_read_b128 v[188:191], v157 offset:8192
	v_mfma_f32_32x32x16_bf16 v[34:49], v[138:141], v[152:155], v[34:49]
	ds_read_b128 v[222:225], v157 offset:12288
	s_add_u32 m0, s15, 0x1c020
	s_add_u32 s10, s10, 0x20000
	s_addc_u32 s11, s11, 0
	global_load_lds_dwordx4 v142, s[10:11]
	s_waitcnt lgkmcnt(6)
	v_mfma_f32_32x32x16_bf16 v[18:33], v[144:147], v[148:151], v[18:33]
	v_mfma_f32_32x32x16_bf16 v[2:17], v[144:147], v[152:155], v[2:17]
	s_add_u32 m0, s15, 0x1e020
	s_add_u32 s10, s10, 0x20000
	s_addc_u32 s11, s11, 0
	global_load_lds_dwordx4 v142, s[10:11]
	s_add_u32 s2, s2, 0x80
	s_addc_u32 s3, s3, 0
	s_waitcnt lgkmcnt(4)
	v_mfma_f32_32x32x16_bf16 v[114:129], v[180:183], v[226:229], v[114:129]
	ds_read_b128 v[130:133], v193 offset:0
	s_waitcnt lgkmcnt(4)
	v_mfma_f32_32x32x16_bf16 v[98:113], v[180:183], v[230:233], v[98:113]
	ds_read_b128 v[148:151], v201 offset:0
	s_waitcnt lgkmcnt(4)
	v_mfma_f32_32x32x16_bf16 v[82:97], v[184:187], v[226:229], v[82:97]
	ds_read_b128 v[152:155], v201 offset:4096
	v_mfma_f32_32x32x16_bf16 v[66:81], v[184:187], v[230:233], v[66:81]
	ds_read_b128 v[134:137], v193 offset:4096
	s_waitcnt lgkmcnt(5)
	v_mfma_f32_32x32x16_bf16 v[50:65], v[188:191], v[226:229], v[50:65]
	ds_read_b128 v[138:141], v193 offset:8192
	v_mfma_f32_32x32x16_bf16 v[34:49], v[188:191], v[230:233], v[34:49]
	ds_read_b128 v[144:147], v193 offset:12288
	s_waitcnt lgkmcnt(6)
	v_mfma_f32_32x32x16_bf16 v[18:33], v[222:225], v[226:229], v[18:33]
	v_mfma_f32_32x32x16_bf16 v[2:17], v[222:225], v[230:233], v[2:17]
	s_waitcnt lgkmcnt(4)
	v_mfma_f32_32x32x16_bf16 v[114:129], v[130:133], v[148:151], v[114:129]
	ds_read_b128 v[180:183], v194 offset:0
	ds_read_b128 v[226:229], v202 offset:0
	s_waitcnt lgkmcnt(5)
	v_mfma_f32_32x32x16_bf16 v[98:113], v[130:133], v[152:155], v[98:113]
	ds_read_b128 v[230:233], v202 offset:4096
	ds_read_b128 v[184:187], v194 offset:4096
	s_waitcnt lgkmcnt(6)
	v_mfma_f32_32x32x16_bf16 v[82:97], v[134:137], v[148:151], v[82:97]
	ds_read_b128 v[188:191], v194 offset:8192
	ds_read_b128 v[222:225], v194 offset:12288
	v_mfma_f32_32x32x16_bf16 v[66:81], v[134:137], v[152:155], v[66:81]
	s_waitcnt lgkmcnt(7)
	v_mfma_f32_32x32x16_bf16 v[50:65], v[138:141], v[148:151], v[50:65]
	v_mfma_f32_32x32x16_bf16 v[34:49], v[138:141], v[152:155], v[34:49]
	s_waitcnt lgkmcnt(6)
	v_mfma_f32_32x32x16_bf16 v[18:33], v[144:147], v[148:151], v[18:33]
	v_mfma_f32_32x32x16_bf16 v[2:17], v[144:147], v[152:155], v[2:17]
	s_waitcnt vmcnt(0) lgkmcnt(0)
	s_barrier
	v_mfma_f32_32x32x16_bf16 v[114:129], v[180:183], v[226:229], v[114:129]
	ds_read_b128 v[130:133], v156 offset:32768
	v_mfma_f32_32x32x16_bf16 v[98:113], v[180:183], v[230:233], v[98:113]
	ds_read_b128 v[148:151], v195 offset:32768
	s_add_u32 m0, s15, 0x20
	s_add_u32 s10, s1, s2
	s_addc_u32 s11, s7, s3
	global_load_lds_dwordx4 v142, s[10:11]
	v_mfma_f32_32x32x16_bf16 v[82:97], v[184:187], v[226:229], v[82:97]
	ds_read_b128 v[152:155], v195 offset:36864
	v_mfma_f32_32x32x16_bf16 v[66:81], v[184:187], v[230:233], v[66:81]
	ds_read_b128 v[134:137], v156 offset:36864
	s_add_u32 m0, s15, 0x2020
	s_add_u32 s10, s10, 0x20000
	s_addc_u32 s11, s11, 0
	global_load_lds_dwordx4 v142, s[10:11]
	v_mfma_f32_32x32x16_bf16 v[50:65], v[188:191], v[226:229], v[50:65]
	ds_read_b128 v[138:141], v156 offset:40960
	v_mfma_f32_32x32x16_bf16 v[34:49], v[188:191], v[230:233], v[34:49]
	ds_read_b128 v[144:147], v156 offset:45056
	s_add_u32 m0, s15, 0x4020
	s_add_u32 s10, s10, 0x20000
	s_addc_u32 s11, s11, 0
	global_load_lds_dwordx4 v142, s[10:11]
	v_mfma_f32_32x32x16_bf16 v[18:33], v[222:225], v[226:229], v[18:33]
	v_mfma_f32_32x32x16_bf16 v[2:17], v[222:225], v[230:233], v[2:17]
	s_add_u32 m0, s15, 0x6020
	s_add_u32 s10, s10, 0x20000
	s_addc_u32 s11, s11, 0
	global_load_lds_dwordx4 v142, s[10:11]
	s_waitcnt lgkmcnt(4)
	v_mfma_f32_32x32x16_bf16 v[114:129], v[130:133], v[148:151], v[114:129]
	ds_read_b128 v[180:183], v157 offset:32768
	s_waitcnt lgkmcnt(4)
	v_mfma_f32_32x32x16_bf16 v[98:113], v[130:133], v[152:155], v[98:113]
	ds_read_b128 v[226:229], v200 offset:32768
	s_add_u32 m0, s15, 0x10020
	s_add_u32 s10, s8, s2
	s_addc_u32 s11, s9, s3
	global_load_lds_dwordx4 v142, s[10:11]
	s_waitcnt lgkmcnt(4)
	v_mfma_f32_32x32x16_bf16 v[82:97], v[134:137], v[148:151], v[82:97]
	ds_read_b128 v[230:233], v200 offset:36864
	v_mfma_f32_32x32x16_bf16 v[66:81], v[134:137], v[152:155], v[66:81]
	ds_read_b128 v[184:187], v157 offset:36864
	s_add_u32 m0, s15, 0x12020
	s_add_u32 s10, s10, 0x20000
	s_addc_u32 s11, s11, 0
	global_load_lds_dwordx4 v142, s[10:11]
	s_waitcnt lgkmcnt(5)
	v_mfma_f32_32x32x16_bf16 v[50:65], v[138:141], v[148:151], v[50:65]
	ds_read_b128 v[188:191], v157 offset:40960
	v_mfma_f32_32x32x16_bf16 v[34:49], v[138:141], v[152:155], v[34:49]
	ds_read_b128 v[222:225], v157 offset:45056
	s_add_u32 m0, s15, 0x14020
	s_add_u32 s10, s10, 0x20000
	s_addc_u32 s11, s11, 0
	global_load_lds_dwordx4 v142, s[10:11]
	s_waitcnt lgkmcnt(6)
	v_mfma_f32_32x32x16_bf16 v[18:33], v[144:147], v[148:151], v[18:33]
	v_mfma_f32_32x32x16_bf16 v[2:17], v[144:147], v[152:155], v[2:17]
	s_add_u32 m0, s15, 0x16020
	s_add_u32 s10, s10, 0x20000
	s_addc_u32 s11, s11, 0
	global_load_lds_dwordx4 v142, s[10:11]
	s_add_u32 s2, s2, 0x80
	s_addc_u32 s3, s3, 0
	s_waitcnt lgkmcnt(4)
	v_mfma_f32_32x32x16_bf16 v[114:129], v[180:183], v[226:229], v[114:129]
	ds_read_b128 v[130:133], v193 offset:32768
	s_waitcnt lgkmcnt(4)
	v_mfma_f32_32x32x16_bf16 v[98:113], v[180:183], v[230:233], v[98:113]
	ds_read_b128 v[148:151], v201 offset:32768
	s_waitcnt lgkmcnt(4)
	v_mfma_f32_32x32x16_bf16 v[82:97], v[184:187], v[226:229], v[82:97]
	ds_read_b128 v[152:155], v201 offset:36864
	v_mfma_f32_32x32x16_bf16 v[66:81], v[184:187], v[230:233], v[66:81]
	ds_read_b128 v[134:137], v193 offset:36864
	s_waitcnt lgkmcnt(5)
	v_mfma_f32_32x32x16_bf16 v[50:65], v[188:191], v[226:229], v[50:65]
	ds_read_b128 v[138:141], v193 offset:40960
	v_mfma_f32_32x32x16_bf16 v[34:49], v[188:191], v[230:233], v[34:49]
	ds_read_b128 v[144:147], v193 offset:45056
	s_waitcnt lgkmcnt(6)
	v_mfma_f32_32x32x16_bf16 v[18:33], v[222:225], v[226:229], v[18:33]
	v_mfma_f32_32x32x16_bf16 v[2:17], v[222:225], v[230:233], v[2:17]
	s_waitcnt lgkmcnt(4)
	v_mfma_f32_32x32x16_bf16 v[114:129], v[130:133], v[148:151], v[114:129]
	ds_read_b128 v[180:183], v194 offset:32768
	ds_read_b128 v[226:229], v202 offset:32768
	s_waitcnt lgkmcnt(5)
	v_mfma_f32_32x32x16_bf16 v[98:113], v[130:133], v[152:155], v[98:113]
	ds_read_b128 v[230:233], v202 offset:36864
	ds_read_b128 v[184:187], v194 offset:36864
	s_waitcnt lgkmcnt(6)
	v_mfma_f32_32x32x16_bf16 v[82:97], v[134:137], v[148:151], v[82:97]
	ds_read_b128 v[188:191], v194 offset:40960
	ds_read_b128 v[222:225], v194 offset:45056
	v_mfma_f32_32x32x16_bf16 v[66:81], v[134:137], v[152:155], v[66:81]
	s_waitcnt lgkmcnt(7)
	v_mfma_f32_32x32x16_bf16 v[50:65], v[138:141], v[148:151], v[50:65]
	v_mfma_f32_32x32x16_bf16 v[34:49], v[138:141], v[152:155], v[34:49]
	s_waitcnt lgkmcnt(6)
	v_mfma_f32_32x32x16_bf16 v[18:33], v[144:147], v[148:151], v[18:33]
	v_mfma_f32_32x32x16_bf16 v[2:17], v[144:147], v[152:155], v[2:17]
	s_waitcnt vmcnt(0) lgkmcnt(0)
	s_barrier
	v_mfma_f32_32x32x16_bf16 v[114:129], v[180:183], v[226:229], v[114:129]
	ds_read_b128 v[130:133], v156 offset:0
	v_mfma_f32_32x32x16_bf16 v[98:113], v[180:183], v[230:233], v[98:113]
	ds_read_b128 v[148:151], v195 offset:0
	s_add_u32 m0, s15, 0x8020
	s_add_u32 s10, s1, s2
	s_addc_u32 s11, s7, s3
	global_load_lds_dwordx4 v142, s[10:11]
	v_mfma_f32_32x32x16_bf16 v[82:97], v[184:187], v[226:229], v[82:97]
	ds_read_b128 v[152:155], v195 offset:4096
	v_mfma_f32_32x32x16_bf16 v[66:81], v[184:187], v[230:233], v[66:81]
	ds_read_b128 v[134:137], v156 offset:4096
	s_add_u32 m0, s15, 0xa020
	s_add_u32 s10, s10, 0x20000
	s_addc_u32 s11, s11, 0
	global_load_lds_dwordx4 v142, s[10:11]
	v_mfma_f32_32x32x16_bf16 v[50:65], v[188:191], v[226:229], v[50:65]
	ds_read_b128 v[138:141], v156 offset:8192
	v_mfma_f32_32x32x16_bf16 v[34:49], v[188:191], v[230:233], v[34:49]
	ds_read_b128 v[144:147], v156 offset:12288
	s_add_u32 m0, s15, 0xc020
	s_add_u32 s10, s10, 0x20000
	s_addc_u32 s11, s11, 0
	global_load_lds_dwordx4 v142, s[10:11]
	v_mfma_f32_32x32x16_bf16 v[18:33], v[222:225], v[226:229], v[18:33]
	v_mfma_f32_32x32x16_bf16 v[2:17], v[222:225], v[230:233], v[2:17]
	s_add_u32 m0, s15, 0xe020
	s_add_u32 s10, s10, 0x20000
	s_addc_u32 s11, s11, 0
	global_load_lds_dwordx4 v142, s[10:11]
	s_sub_u32 s5, s5, 1
	s_cmp_lg_u32 s5, 0
	s_cbranch_scc1 .Lg1122_loop
	s_waitcnt lgkmcnt(4)
	v_mfma_f32_32x32x16_bf16 v[114:129], v[130:133], v[148:151], v[114:129]
	ds_read_b128 v[180:183], v157 offset:0
	s_waitcnt lgkmcnt(4)
	v_mfma_f32_32x32x16_bf16 v[98:113], v[130:133], v[152:155], v[98:113]
	ds_read_b128 v[226:229], v200 offset:0
	s_add_u32 m0, s15, 0x18020
	s_add_u32 s10, s8, s2
	s_addc_u32 s11, s9, s3
	global_load_lds_dwordx4 v142, s[10:11]
	s_waitcnt lgkmcnt(4)
	v_mfma_f32_32x32x16_bf16 v[82:97], v[134:137], v[148:151], v[82:97]
	ds_read_b128 v[230:233], v200 offset:4096
	v_mfma_f32_32x32x16_bf16 v[66:81], v[134:137], v[152:155], v[66:81]
	ds_read_b128 v[184:187], v157 offset:4096
	s_add_u32 m0, s15, 0x1a020
	s_add_u32 s10, s10, 0x20000
	s_addc_u32 s11, s11, 0
	global_load_lds_dwordx4 v142, s[10:11]
	s_waitcnt lgkmcnt(5)
	v_mfma_f32_32x32x16_bf16 v[50:65], v[138:141], v[148:151], v[50:65]
	ds_read_b128 v[188:191], v157 offset:8192
	v_mfma_f32_32x32x16_bf16 v[34:49], v[138:141], v[152:155], v[34:49]
	ds_read_b128 v[222:225], v157 offset:12288
	s_add_u32 m0, s15, 0x1c020
	s_add_u32 s10, s10, 0x20000
	s_addc_u32 s11, s11, 0
	global_load_lds_dwordx4 v142, s[10:11]
	s_waitcnt lgkmcnt(6)
	v_mfma_f32_32x32x16_bf16 v[18:33], v[144:147], v[148:151], v[18:33]
	v_mfma_f32_32x32x16_bf16 v[2:17], v[144:147], v[152:155], v[2:17]
	s_add_u32 m0, s15, 0x1e020
	s_add_u32 s10, s10, 0x20000
	s_addc_u32 s11, s11, 0
	global_load_lds_dwordx4 v142, s[10:11]
	s_add_u32 s2, s2, 0x80
	s_addc_u32 s3, s3, 0
	s_waitcnt lgkmcnt(4)
	v_mfma_f32_32x32x16_bf16 v[114:129], v[180:183], v[226:229], v[114:129]
	ds_read_b128 v[130:133], v193 offset:0
	s_waitcnt lgkmcnt(4)
	v_mfma_f32_32x32x16_bf16 v[98:113], v[180:183], v[230:233], v[98:113]
	ds_read_b128 v[148:151], v201 offset:0
	s_waitcnt lgkmcnt(4)
	v_mfma_f32_32x32x16_bf16 v[82:97], v[184:187], v[226:229], v[82:97]
	ds_read_b128 v[152:155], v201 offset:4096
	v_mfma_f32_32x32x16_bf16 v[66:81], v[184:187], v[230:233], v[66:81]
	ds_read_b128 v[134:137], v193 offset:4096
	s_waitcnt lgkmcnt(5)
	v_mfma_f32_32x32x16_bf16 v[50:65], v[188:191], v[226:229], v[50:65]
	ds_read_b128 v[138:141], v193 offset:8192
	v_mfma_f32_32x32x16_bf16 v[34:49], v[188:191], v[230:233], v[34:49]
	ds_read_b128 v[144:147], v193 offset:12288
	s_waitcnt lgkmcnt(6)
	v_mfma_f32_32x32x16_bf16 v[18:33], v[222:225], v[226:229], v[18:33]
	v_mfma_f32_32x32x16_bf16 v[2:17], v[222:225], v[230:233], v[2:17]
	s_waitcnt lgkmcnt(4)
	v_mfma_f32_32x32x16_bf16 v[114:129], v[130:133], v[148:151], v[114:129]
	ds_read_b128 v[180:183], v194 offset:0
	ds_read_b128 v[226:229], v202 offset:0
	s_waitcnt lgkmcnt(5)
	v_mfma_f32_32x32x16_bf16 v[98:113], v[130:133], v[152:155], v[98:113]
	ds_read_b128 v[230:233], v202 offset:4096
	ds_read_b128 v[184:187], v194 offset:4096
	s_waitcnt lgkmcnt(6)
	v_mfma_f32_32x32x16_bf16 v[82:97], v[134:137], v[148:151], v[82:97]
	ds_read_b128 v[188:191], v194 offset:8192
	ds_read_b128 v[222:225], v194 offset:12288
	v_mfma_f32_32x32x16_bf16 v[66:81], v[134:137], v[152:155], v[66:81]
	s_waitcnt lgkmcnt(7)
	v_mfma_f32_32x32x16_bf16 v[50:65], v[138:141], v[148:151], v[50:65]
	v_mfma_f32_32x32x16_bf16 v[34:49], v[138:141], v[152:155], v[34:49]
	s_waitcnt lgkmcnt(6)
	v_mfma_f32_32x32x16_bf16 v[18:33], v[144:147], v[148:151], v[18:33]
	v_mfma_f32_32x32x16_bf16 v[2:17], v[144:147], v[152:155], v[2:17]
	s_waitcnt vmcnt(0) lgkmcnt(0)
	s_barrier
	v_mfma_f32_32x32x16_bf16 v[114:129], v[180:183], v[226:229], v[114:129]
	ds_read_b128 v[130:133], v156 offset:32768
	v_mfma_f32_32x32x16_bf16 v[98:113], v[180:183], v[230:233], v[98:113]
	ds_read_b128 v[148:151], v195 offset:32768
	v_mfma_f32_32x32x16_bf16 v[82:97], v[184:187], v[226:229], v[82:97]
	ds_read_b128 v[152:155], v195 offset:36864
	v_mfma_f32_32x32x16_bf16 v[66:81], v[184:187], v[230:233], v[66:81]
	ds_read_b128 v[134:137], v156 offset:36864
	v_mfma_f32_32x32x16_bf16 v[50:65], v[188:191], v[226:229], v[50:65]
	ds_read_b128 v[138:141], v156 offset:40960
	v_mfma_f32_32x32x16_bf16 v[34:49], v[188:191], v[230:233], v[34:49]
	ds_read_b128 v[144:147], v156 offset:45056
	v_mfma_f32_32x32x16_bf16 v[18:33], v[222:225], v[226:229], v[18:33]
	v_mfma_f32_32x32x16_bf16 v[2:17], v[222:225], v[230:233], v[2:17]
	s_waitcnt lgkmcnt(4)
	v_mfma_f32_32x32x16_bf16 v[114:129], v[130:133], v[148:151], v[114:129]
	ds_read_b128 v[180:183], v157 offset:32768
	s_waitcnt lgkmcnt(4)
	v_mfma_f32_32x32x16_bf16 v[98:113], v[130:133], v[152:155], v[98:113]
	ds_read_b128 v[226:229], v200 offset:32768
	s_waitcnt lgkmcnt(4)
	v_mfma_f32_32x32x16_bf16 v[82:97], v[134:137], v[148:151], v[82:97]
	ds_read_b128 v[230:233], v200 offset:36864
	v_mfma_f32_32x32x16_bf16 v[66:81], v[134:137], v[152:155], v[66:81]
	ds_read_b128 v[184:187], v157 offset:36864
	s_waitcnt lgkmcnt(5)
	v_mfma_f32_32x32x16_bf16 v[50:65], v[138:141], v[148:151], v[50:65]
	ds_read_b128 v[188:191], v157 offset:40960
	v_mfma_f32_32x32x16_bf16 v[34:49], v[138:141], v[152:155], v[34:49]
	ds_read_b128 v[222:225], v157 offset:45056
	s_waitcnt lgkmcnt(6)
	v_mfma_f32_32x32x16_bf16 v[18:33], v[144:147], v[148:151], v[18:33]
	v_mfma_f32_32x32x16_bf16 v[2:17], v[144:147], v[152:155], v[2:17]
	s_waitcnt lgkmcnt(4)
	v_mfma_f32_32x32x16_bf16 v[114:129], v[180:183], v[226:229], v[114:129]
	ds_read_b128 v[130:133], v193 offset:32768
	s_waitcnt lgkmcnt(4)
	v_mfma_f32_32x32x16_bf16 v[98:113], v[180:183], v[230:233], v[98:113]
	ds_read_b128 v[148:151], v201 offset:32768
	s_waitcnt lgkmcnt(4)
	v_mfma_f32_32x32x16_bf16 v[82:97], v[184:187], v[226:229], v[82:97]
	ds_read_b128 v[152:155], v201 offset:36864
	v_mfma_f32_32x32x16_bf16 v[66:81], v[184:187], v[230:233], v[66:81]
	ds_read_b128 v[134:137], v193 offset:36864
	s_waitcnt lgkmcnt(5)
	v_mfma_f32_32x32x16_bf16 v[50:65], v[188:191], v[226:229], v[50:65]
	ds_read_b128 v[138:141], v193 offset:40960
	v_mfma_f32_32x32x16_bf16 v[34:49], v[188:191], v[230:233], v[34:49]
	ds_read_b128 v[144:147], v193 offset:45056
	s_waitcnt lgkmcnt(6)
	v_mfma_f32_32x32x16_bf16 v[18:33], v[222:225], v[226:229], v[18:33]
	v_mfma_f32_32x32x16_bf16 v[2:17], v[222:225], v[230:233], v[2:17]
	s_waitcnt lgkmcnt(4)
	v_mfma_f32_32x32x16_bf16 v[114:129], v[130:133], v[148:151], v[114:129]
	ds_read_b128 v[180:183], v194 offset:32768
	ds_read_b128 v[226:229], v202 offset:32768
	s_waitcnt lgkmcnt(5)
	v_mfma_f32_32x32x16_bf16 v[98:113], v[130:133], v[152:155], v[98:113]
	ds_read_b128 v[230:233], v202 offset:36864
	ds_read_b128 v[184:187], v194 offset:36864
	s_waitcnt lgkmcnt(6)
	v_mfma_f32_32x32x16_bf16 v[82:97], v[134:137], v[148:151], v[82:97]
	ds_read_b128 v[188:191], v194 offset:40960
	ds_read_b128 v[222:225], v194 offset:45056
	v_mfma_f32_32x32x16_bf16 v[66:81], v[134:137], v[152:155], v[66:81]
	s_waitcnt lgkmcnt(7)
	v_mfma_f32_32x32x16_bf16 v[50:65], v[138:141], v[148:151], v[50:65]
	v_mfma_f32_32x32x16_bf16 v[34:49], v[138:141], v[152:155], v[34:49]
	s_waitcnt lgkmcnt(6)
	v_mfma_f32_32x32x16_bf16 v[18:33], v[144:147], v[148:151], v[18:33]
	v_mfma_f32_32x32x16_bf16 v[2:17], v[144:147], v[152:155], v[2:17]
	s_waitcnt vmcnt(0) lgkmcnt(0)
	s_barrier
	v_mfma_f32_32x32x16_bf16 v[114:129], v[180:183], v[226:229], v[114:129]
	v_mfma_f32_32x32x16_bf16 v[98:113], v[180:183], v[230:233], v[98:113]
	v_mfma_f32_32x32x16_bf16 v[82:97], v[184:187], v[226:229], v[82:97]
	v_mfma_f32_32x32x16_bf16 v[66:81], v[184:187], v[230:233], v[66:81]
	v_mfma_f32_32x32x16_bf16 v[50:65], v[188:191], v[226:229], v[50:65]
	v_mfma_f32_32x32x16_bf16 v[34:49], v[188:191], v[230:233], v[34:49]
	v_mfma_f32_32x32x16_bf16 v[18:33], v[222:225], v[226:229], v[18:33]
	v_mfma_f32_32x32x16_bf16 v[2:17], v[222:225], v[230:233], v[2:17]
	v_add_u32_e32 v180, s0, v168
	s_and_b32 s0, s4, 0x7ffffe
	s_mov_b32 s4, 0x7e07e07f
	v_mul_hi_i32 v0, v180, s4
	v_lshrrev_b32_e32 v130, 31, v0
	v_ashrrev_i32_e32 v0, 13, v0
	s_cmp_eq_u32 s0, 12
	v_add_u32_e32 v182, v0, v130
	s_waitcnt vmcnt(0)
	s_cselect_b64 s[2:3], -1, 0
	s_cmp_lg_u32 s0, 12
	v_mul_i32_i24_e32 v0, 0x4100, v182
	v_or_b32_e32 v138, s6, v169
	s_movk_i32 s4, 0x5ff
	s_cselect_b64 s[0:1], -1, 0
	v_sub_u32_e32 v140, v180, v0
	v_mov_b32_e32 v184, v179
	v_cmp_lt_i32_e64 s[52:53], s4, v138
	s_barrier
	v_lshl_or_b32 v181, v182, 3, v171
	v_ashrrev_i32_e32 v141, 31, v140
	s_and_b64 s[10:11], s[0:1], s[52:53]
	v_and_b32_e32 v183, 63, v184
	v_and_b32_e32 v0, 31, v184
	v_bfe_u32 v133, v184, 5, 1
	s_and_saveexec_b64 s[0:1], s[10:11]
	s_xor_b64 s[8:9], exec, s[0:1]
	s_cbranch_execz .LBB0_1136
	s_add_i32 s4, s6, 0xfffff200
	v_mul_u32_u24_e32 v130, 0x90, v133
	s_mov_b64 s[0:1], -1
	s_cmp_gt_u32 s4, 0xfffff9ff
	v_lshlrev_b32_e32 v139, 2, v0
	v_lshlrev_b32_e32 v185, 2, v130
	s_cbranch_scc0 .LBB0_1134
	v_add3_u32 v0, v170, v185, v139
	ds_write_b32 v0, v114
	v_add3_u32 v0, v170, v139, v185
	v_add_u32_e32 v130, 0x100, v0
	ds_write2_b32 v130, v117, v118 offset0:44 offset1:224
	v_add_u32_e32 v130, 0x400, v0
	ds_write2_b32 v130, v119, v120 offset0:68 offset1:104
	v_add_u32_e32 v130, 0x600, v0
	ds_write2_b32 v130, v121, v122 offset0:12 offset1:192
	v_add_u32_e32 v130, 0x800, v0
	ds_write2_b32 v130, v123, v124 offset0:100 offset1:136
	v_add_u32_e32 v130, 0xa00, v0
	ds_write2_b32 v130, v125, v126 offset0:44 offset1:224
	v_add_u32_e32 v130, 0xc00, v0
	s_cmpk_lt_u32 s6, 0xa00
	ds_write2_b32 v0, v115, v116 offset0:36 offset1:72
	ds_write2_b32 v130, v127, v128 offset0:132 offset1:168
	ds_write_b32 v0, v129 offset:3888
	s_cselect_b64 s[0:1], -1, 0
	v_mov_b32_e32 v0, 0x3e38aa3b
	v_cndmask_b32_e64 v142, 1.0, v0, s[0:1]
	v_lshlrev_b32_e32 v0, 3, v184
	v_lshrrev_b32_e32 v188, 2, v183
	s_movk_i32 s4, 0x90
	v_and_b32_e32 v187, 24, v0
	v_mad_u32_u24 v147, v188, s4, v170
	s_waitcnt lgkmcnt(0)
	v_lshl_add_u32 v130, v187, 2, v147
	ds_read_b128 v[134:137], v130
	ds_read_b128 v[130:133], v130 offset:16
	v_and_b32_e32 v144, 2, v184
	v_or_b32_e32 v150, v188, v140
	s_movk_i32 s4, 0x100
	v_cmp_eq_u32_e32 vcc, 0, v144
	v_cmp_gt_i32_e64 s[4:5], s4, v150
	s_and_saveexec_b64 s[16:17], s[4:5]
	s_xor_b64 s[4:5], exec, s[16:17]
	s_cbranch_execz .LBB0_1127
	s_waitcnt lgkmcnt(1)
	v_pk_mul_f32 v[152:153], v[142:143], v[134:135] op_sel_hi:[0,1]
	v_pk_mul_f32 v[154:155], v[142:143], v[136:137] op_sel_hi:[0,1]
	s_waitcnt lgkmcnt(0)
	v_pk_mul_f32 v[156:157], v[142:143], v[130:131] op_sel_hi:[0,1]
	v_mul_f32_e32 v145, v142, v132
